# accumulator clearing moved from the unit boundary into the first iteration's load segments (one quarter per segment, branch on the loop counter)
# speedup vs baseline: 1.0097x; 1.0097x over previous
; #define G_STAGE(bufoff, gbase, o0, h64) do { \
;         __builtin_amdgcn_global_load_lds((const unsigned*)((const char*)(gbase) + (o0)), (LAS unsigned*)(lds + (bufoff) + ldsw), 16, 0, 0); \
;         __builtin_amdgcn_global_load_lds((const unsigned*)((const char*)(gbase) + (h64) + (o0)), (LAS unsigned*)(lds + (bufoff) + ldsw + 8192), 16, 0, 0); } while (0)
; #define G_LDA(dst, b, h) do { _Pragma("unroll") for (int m = 0; m < 4; ++m) _Pragma("unroll") for (int k = 0; k < 2; ++k) dst[m][k] = *(const LAS bf16x8*)(lds + G_SA(b, h) + aoff + m * 2048 + k * 1024); } while (0)
; #define G_LDB(dst, b, h) do { _Pragma("unroll") for (int n = 0; n < 2; ++n) _Pragma("unroll") for (int k = 0; k < 2; ++k) dst[n][k] = *(const LAS bf16x8*)(lds + G_SB(b, h) + boff + n * 2048 + k * 1024); } while (0)
; #define G_WAIT_L(n) asm volatile("s_waitcnt lgkmcnt(" #n ")" ::: "memory")
; #define G_BAR __builtin_amdgcn_s_barrier()
; #define G_SCHED __builtin_amdgcn_sched_barrier(0)
;     ...
;         for (int t = 0; t < nt; t += 2) {
;             const bool last = (t == nt - 2);
;             const char* a1 = cA + (size_t)(t + 1) * ckA;
;             const char* a2 = last ? nA : cA + (size_t)(t + 2) * ckA; const char* b2 = last ? nB : cB + (size_t)(t + 2) * kB;
;             const char* a3 = a2 + ckA; const char* b3 = b2 + kB;
;             G_LDB(B0, 0, 0); G_SCHED; G_LDA(At, 0, 0); G_STAGE(G_SA(1, 1), a1 + chA, cA0, qA);
;             G_WAIT_L(8); G_BAR; G_WAIT_L(0); G_MMA(0, 0, At, B0); G_BAR; G_SCHED;
;             G_LDB(B1, 0, 1); G_STAGE(G_SB(0, 0), b2, cB0, qB);
;             G_BAR; G_WAIT_L(0); G_MMA(0, 1, At, B1); G_BAR;
;     ...
;         if (!(cs.kind == K_MG_B && cur.aux < 2))
; #pragma unroll
;         for (int a = 0; a < 2; ++a)
; #pragma unroll
;             for (int b = 0; b < 2; ++b)
; #pragma unroll
;                 for (int m = 0; m < 4; ++m)
; #pragma unroll
;                     for (int n = 0; n < 2; ++n) acc[a][b][m][n] = (f32x4){0.f, 0.f, 0.f, 0.f};
.LBB0_211:
	s_add_u32 s2, s2, 0x40080
	s_addc_u32 s3, s3, 0
	s_add_u32 s7, s22, 0x100
	s_addc_u32 s22, s23, 0
	s_mov_b32 s23, -2
	s_mov_b64 s[52:53], 0x40000
	s_mov_b64 s[54:55], 0x60000
	s_mov_b64 s[58:59], 0x20080
	s_mov_b64 s[62:63], 0x40080
	s_mov_b64 s[64:65], 0x60080
	s_cmp_eq_u32 s101, 2
	s_cselect_b32 s101, 0, s101
.LBB0_212:
	s_add_u32 s4, s2, 0xfffc0080
	s_addc_u32 s5, s3, -1
	s_add_i32 s41, 0, 0x10000
	v_add_u32_e32 v0, s41, v167
	ds_read_b128 v[136:139], v0
	ds_read_b128 v[144:147], v0 offset:1024
	ds_read_b128 v[148:151], v0 offset:2048
	ds_read_b128 v[152:155], v0 offset:3072
	s_cmp_eq_u32 s23, 12
	s_cselect_b32 s43, s19, s5
	s_cselect_b32 s42, s18, s4
	s_cselect_b32 s51, s21, s22
	s_cselect_b32 s50, s20, s7
	v_lshl_add_u64 v[164:165], s[2:3], 0, v[142:143]
	s_add_i32 m0, s27, 0xc000
	ds_read_b128 v[156:159], v172
	ds_read_b128 v[160:163], v172 offset:1024
	ds_read_b128 v[174:177], v172 offset:2048
	ds_read_b128 v[178:181], v172 offset:3072
	ds_read_b128 v[182:185], v172 offset:4096
	ds_read_b128 v[196:199], v172 offset:5120
	ds_read_b128 v[200:203], v172 offset:6144
	ds_read_b128 v[204:207], v172 offset:7168
	global_load_lds_dwordx4 v[164:165], off
	v_lshl_add_u64 v[164:165], v[164:165], 0, s[0:1]
	s_add_i32 m0, s27, 0xe000
	s_nop 0
	global_load_lds_dwordx4 v[164:165], off
	s_cmp_lg_u32 s23, -2
	s_cbranch_scc1 .Lzil_WIN_0
	v_mov_b64_e32 v[80:81], 0
	v_mov_b64_e32 v[82:83], 0
	v_mov_b64_e32 v[84:85], 0
	v_mov_b64_e32 v[86:87], 0
	v_mov_b64_e32 v[96:97], 0
	v_mov_b64_e32 v[98:99], 0
	v_mov_b64_e32 v[100:101], 0
	v_mov_b64_e32 v[102:103], 0
	v_mov_b64_e32 v[112:113], 0
	v_mov_b64_e32 v[114:115], 0
	v_mov_b64_e32 v[116:117], 0
	v_mov_b64_e32 v[118:119], 0
	v_mov_b64_e32 v[128:129], 0
	v_mov_b64_e32 v[130:131], 0
	v_mov_b64_e32 v[132:133], 0
	v_mov_b64_e32 v[134:135], 0
.Lzil_WIN_0:
	s_waitcnt lgkmcnt(8)
	s_cmp_eq_u32 s101, 1
	s_cbranch_scc1 .Ldb_WIN_sk
	s_barrier
.Ldb_WIN_sk:
	s_mov_b32 s101, 0
	s_waitcnt lgkmcnt(0)
	v_mfma_f32_16x16x32_bf16 v[132:135], v[136:139], v[156:159], v[132:135]
	v_mfma_f32_16x16x32_bf16 v[128:131], v[148:151], v[156:159], v[128:131]
	v_mfma_f32_16x16x32_bf16 v[116:119], v[136:139], v[174:177], v[116:119]
	v_mfma_f32_16x16x32_bf16 v[112:115], v[148:151], v[174:177], v[112:115]
	v_mfma_f32_16x16x32_bf16 v[100:103], v[136:139], v[182:185], v[100:103]
	v_mfma_f32_16x16x32_bf16 v[96:99], v[148:151], v[182:185], v[96:99]
	v_mfma_f32_16x16x32_bf16 v[84:87], v[136:139], v[200:203], v[84:87]
	v_mfma_f32_16x16x32_bf16 v[80:83], v[148:151], v[200:203], v[80:83]
	v_mfma_f32_16x16x32_bf16 v[132:135], v[144:147], v[160:163], v[132:135]
	v_mfma_f32_16x16x32_bf16 v[128:131], v[152:155], v[160:163], v[128:131]
	v_mfma_f32_16x16x32_bf16 v[116:119], v[144:147], v[178:181], v[116:119]
	v_mfma_f32_16x16x32_bf16 v[112:115], v[152:155], v[178:181], v[112:115]
	v_mfma_f32_16x16x32_bf16 v[100:103], v[144:147], v[196:199], v[100:103]
	v_mfma_f32_16x16x32_bf16 v[96:99], v[152:155], v[196:199], v[96:99]
	v_mfma_f32_16x16x32_bf16 v[84:87], v[144:147], v[204:207], v[84:87]
	v_mfma_f32_16x16x32_bf16 v[80:83], v[152:155], v[204:207], v[80:83]
	s_barrier
	s_add_i32 s4, 0, 0x14000
	s_add_i32 s5, s41, s26
	v_add_u32_e32 v0, s4, v167
	v_lshl_add_u64 v[164:165], s[50:51], 0, v[140:141]
	s_mov_b32 m0, s5
	ds_read_b128 v[208:211], v0
	ds_read_b128 v[212:215], v0 offset:1024
	ds_read_b128 v[216:219], v0 offset:2048
	ds_read_b128 v[220:223], v0 offset:3072
	global_load_lds_dwordx4 v[164:165], off
	v_lshl_add_u64 v[224:225], v[164:165], 0, s[0:1]
	s_add_i32 m0, s5, 0x2000
	s_nop 0
	global_load_lds_dwordx4 v[224:225], off
	s_cmp_lg_u32 s23, -2
	s_cbranch_scc1 .Lzil_WIN_1
	v_mov_b64_e32 v[72:73], 0
	v_mov_b64_e32 v[74:75], 0
	v_mov_b64_e32 v[76:77], 0
	v_mov_b64_e32 v[78:79], 0
	v_mov_b64_e32 v[88:89], 0
	v_mov_b64_e32 v[90:91], 0
	v_mov_b64_e32 v[92:93], 0
	v_mov_b64_e32 v[94:95], 0
	v_mov_b64_e32 v[104:105], 0
	v_mov_b64_e32 v[106:107], 0
	v_mov_b64_e32 v[108:109], 0
	v_mov_b64_e32 v[110:111], 0
	v_mov_b64_e32 v[120:121], 0
	v_mov_b64_e32 v[122:123], 0
	v_mov_b64_e32 v[124:125], 0
	v_mov_b64_e32 v[126:127], 0
.Lzil_WIN_1:
	s_barrier
	s_waitcnt lgkmcnt(0)
	v_mfma_f32_16x16x32_bf16 v[124:127], v[208:211], v[156:159], v[124:127]
	v_mfma_f32_16x16x32_bf16 v[120:123], v[216:219], v[156:159], v[120:123]
	v_mfma_f32_16x16x32_bf16 v[108:111], v[208:211], v[174:177], v[108:111]
	v_mfma_f32_16x16x32_bf16 v[104:107], v[216:219], v[174:177], v[104:107]
	v_mfma_f32_16x16x32_bf16 v[92:95], v[208:211], v[182:185], v[92:95]
	v_mfma_f32_16x16x32_bf16 v[88:91], v[216:219], v[182:185], v[88:91]
	v_mfma_f32_16x16x32_bf16 v[76:79], v[208:211], v[200:203], v[76:79]
	v_mfma_f32_16x16x32_bf16 v[72:75], v[216:219], v[200:203], v[72:75]
	v_mfma_f32_16x16x32_bf16 v[124:127], v[212:215], v[160:163], v[124:127]
	v_mfma_f32_16x16x32_bf16 v[120:123], v[220:223], v[160:163], v[120:123]
	v_mfma_f32_16x16x32_bf16 v[108:111], v[212:215], v[178:181], v[108:111]
	v_mfma_f32_16x16x32_bf16 v[104:107], v[220:223], v[178:181], v[104:107]
	v_mfma_f32_16x16x32_bf16 v[92:95], v[212:215], v[196:199], v[92:95]
	v_mfma_f32_16x16x32_bf16 v[88:91], v[220:223], v[196:199], v[88:91]
	v_mfma_f32_16x16x32_bf16 v[76:79], v[212:215], v[204:207], v[76:79]
	v_mfma_f32_16x16x32_bf16 v[72:75], v[220:223], v[204:207], v[72:75]
	s_barrier
	s_mov_b32 m0, s27
	v_lshl_add_u64 v[224:225], s[42:43], 0, v[2:3]
	ds_read_b128 v[156:159], v172 offset:16384
	ds_read_b128 v[160:163], v172 offset:17408
	ds_read_b128 v[174:177], v172 offset:18432
	ds_read_b128 v[178:181], v172 offset:19456
	ds_read_b128 v[182:185], v172 offset:20480
	ds_read_b128 v[196:199], v172 offset:21504
	ds_read_b128 v[200:203], v172 offset:22528
	ds_read_b128 v[204:207], v172 offset:23552
	global_load_lds_dwordx4 v[224:225], off
	v_lshl_add_u64 v[226:227], v[224:225], 0, s[0:1]
	s_mov_b32 m0, s28
	s_nop 0
	global_load_lds_dwordx4 v[226:227], off
	s_cmp_lg_u32 s23, -2
	s_cbranch_scc1 .Lzil_WIN_2
	v_mov_b64_e32 v[16:17], 0
	v_mov_b64_e32 v[18:19], 0
	v_mov_b64_e32 v[20:21], 0
	v_mov_b64_e32 v[22:23], 0
	v_mov_b64_e32 v[32:33], 0
	v_mov_b64_e32 v[34:35], 0
	v_mov_b64_e32 v[36:37], 0
	v_mov_b64_e32 v[38:39], 0
	v_mov_b64_e32 v[48:49], 0
	v_mov_b64_e32 v[50:51], 0
	v_mov_b64_e32 v[52:53], 0
	v_mov_b64_e32 v[54:55], 0
	v_mov_b64_e32 v[64:65], 0
	v_mov_b64_e32 v[66:67], 0
	v_mov_b64_e32 v[68:69], 0
	v_mov_b64_e32 v[70:71], 0
; #define G_STAGE(bufoff, gbase, o0, h64) do { \
;         __builtin_amdgcn_global_load_lds((const unsigned*)((const char*)(gbase) + (o0)), (LAS unsigned*)(lds + (bufoff) + ldsw), 16, 0, 0); \
;         __builtin_amdgcn_global_load_lds((const unsigned*)((const char*)(gbase) + (h64) + (o0)), (LAS unsigned*)(lds + (bufoff) + ldsw + 8192), 16, 0, 0); } while (0)
; #define G_LDA(dst, b, h) do { _Pragma("unroll") for (int m = 0; m < 4; ++m) _Pragma("unroll") for (int k = 0; k < 2; ++k) dst[m][k] = *(const LAS bf16x8*)(lds + G_SA(b, h) + aoff + m * 2048 + k * 1024); } while (0)
; #define G_LDB(dst, b, h) do { _Pragma("unroll") for (int n = 0; n < 2; ++n) _Pragma("unroll") for (int k = 0; k < 2; ++k) dst[n][k] = *(const LAS bf16x8*)(lds + G_SB(b, h) + boff + n * 2048 + k * 1024); } while (0)
; #define G_WAIT_V(n) asm volatile("s_waitcnt vmcnt(" #n ")" ::: "memory")
; #define G_WAIT_L(n) asm volatile("s_waitcnt lgkmcnt(" #n ")" ::: "memory")
; #define G_BAR __builtin_amdgcn_s_barrier()
; #define G_SCHED __builtin_amdgcn_sched_barrier(0)
;     ...
;             G_BAR; G_WAIT_L(0); G_MMA(0, 1, At, B1); G_BAR;
;             G_LDA(At, 0, 1); G_STAGE(G_SA(0, 0), a2, cA0, qA);
;             G_BAR; G_WAIT_L(0); G_MMA(1, 0, At, B0); G_BAR; G_SCHED;
;             G_STAGE(G_SB(0, 1), b2 + chB, cB0, qB);
;             G_WAIT_V(6); G_BAR; G_MMA(1, 1, At, B1); G_BAR;
;             G_LDB(B0, 1, 0); G_SCHED; G_LDA(At, 1, 0); G_STAGE(G_SA(0, 1), a2 + chA, cA0, qA);
;             G_WAIT_L(8); G_BAR; G_WAIT_L(0); G_MMA(0, 0, At, B0); G_BAR; G_SCHED;
.Lzil_WIN_2:
	s_barrier
	s_waitcnt lgkmcnt(0)
	v_mfma_f32_16x16x32_bf16 v[68:71], v[136:139], v[156:159], v[68:71]
	v_mfma_f32_16x16x32_bf16 v[64:67], v[148:151], v[156:159], v[64:67]
	v_mfma_f32_16x16x32_bf16 v[52:55], v[136:139], v[174:177], v[52:55]
	v_mfma_f32_16x16x32_bf16 v[48:51], v[148:151], v[174:177], v[48:51]
	v_mfma_f32_16x16x32_bf16 v[36:39], v[136:139], v[182:185], v[36:39]
	v_mfma_f32_16x16x32_bf16 v[32:35], v[148:151], v[182:185], v[32:35]
	v_mfma_f32_16x16x32_bf16 v[20:23], v[136:139], v[200:203], v[20:23]
	v_mfma_f32_16x16x32_bf16 v[16:19], v[148:151], v[200:203], v[16:19]
	v_mfma_f32_16x16x32_bf16 v[68:71], v[144:147], v[160:163], v[68:71]
	v_mfma_f32_16x16x32_bf16 v[64:67], v[152:155], v[160:163], v[64:67]
	v_mfma_f32_16x16x32_bf16 v[52:55], v[144:147], v[178:181], v[52:55]
	v_mfma_f32_16x16x32_bf16 v[48:51], v[152:155], v[178:181], v[48:51]
	v_mfma_f32_16x16x32_bf16 v[36:39], v[144:147], v[196:199], v[36:39]
	v_mfma_f32_16x16x32_bf16 v[32:35], v[152:155], v[196:199], v[32:35]
	v_mfma_f32_16x16x32_bf16 v[20:23], v[144:147], v[204:207], v[20:23]
	v_mfma_f32_16x16x32_bf16 v[16:19], v[152:155], v[204:207], v[16:19]
	s_barrier
	s_add_i32 s4, s4, s26
	v_lshl_add_u64 v[136:137], v[164:165], 0, s[52:53]
	s_mov_b32 m0, s4
	s_nop 0
	global_load_lds_dwordx4 v[136:137], off
	v_lshl_add_u64 v[136:137], v[164:165], 0, s[54:55]
	s_add_i32 m0, s4, 0x2000
	s_nop 0
	global_load_lds_dwordx4 v[136:137], off
	s_cmp_lg_u32 s23, -2
	s_cbranch_scc1 .Lzil_WIN_3
	v_mov_b64_e32 v[8:9], 0
	v_mov_b64_e32 v[10:11], 0
	v_mov_b64_e32 v[12:13], 0
	v_mov_b64_e32 v[14:15], 0
	v_mov_b64_e32 v[24:25], 0
	v_mov_b64_e32 v[26:27], 0
	v_mov_b64_e32 v[28:29], 0
	v_mov_b64_e32 v[30:31], 0
	v_mov_b64_e32 v[40:41], 0
	v_mov_b64_e32 v[42:43], 0
	v_mov_b64_e32 v[44:45], 0
	v_mov_b64_e32 v[46:47], 0
	v_mov_b64_e32 v[56:57], 0
	v_mov_b64_e32 v[58:59], 0
	v_mov_b64_e32 v[60:61], 0
	v_mov_b64_e32 v[62:63], 0
.Lzil_WIN_3:
	s_waitcnt vmcnt(6)
	s_barrier
	v_mfma_f32_16x16x32_bf16 v[60:63], v[208:211], v[156:159], v[60:63]
	v_mfma_f32_16x16x32_bf16 v[56:59], v[216:219], v[156:159], v[56:59]
	v_mfma_f32_16x16x32_bf16 v[44:47], v[208:211], v[174:177], v[44:47]
	v_mfma_f32_16x16x32_bf16 v[40:43], v[216:219], v[174:177], v[40:43]
	v_mfma_f32_16x16x32_bf16 v[28:31], v[208:211], v[182:185], v[28:31]
	v_mfma_f32_16x16x32_bf16 v[24:27], v[216:219], v[182:185], v[24:27]
	v_mfma_f32_16x16x32_bf16 v[12:15], v[208:211], v[200:203], v[12:15]
	v_mfma_f32_16x16x32_bf16 v[8:11], v[216:219], v[200:203], v[8:11]
	v_mfma_f32_16x16x32_bf16 v[60:63], v[212:215], v[160:163], v[60:63]
	v_mfma_f32_16x16x32_bf16 v[56:59], v[220:223], v[160:163], v[56:59]
	v_mfma_f32_16x16x32_bf16 v[44:47], v[212:215], v[178:181], v[44:47]
	v_mfma_f32_16x16x32_bf16 v[40:43], v[220:223], v[178:181], v[40:43]
	v_mfma_f32_16x16x32_bf16 v[28:31], v[212:215], v[196:199], v[28:31]
	v_mfma_f32_16x16x32_bf16 v[24:27], v[220:223], v[196:199], v[24:27]
	v_mfma_f32_16x16x32_bf16 v[12:15], v[212:215], v[204:207], v[12:15]
	v_mfma_f32_16x16x32_bf16 v[8:11], v[220:223], v[204:207], v[8:11]
	s_barrier
	s_add_i32 s4, 0, 0x18000
	v_add_u32_e32 v0, s4, v167
	ds_read_b128 v[136:139], v0
	ds_read_b128 v[144:147], v0 offset:1024
	ds_read_b128 v[148:151], v0 offset:2048
	ds_read_b128 v[152:155], v0 offset:3072
	s_mov_b32 m0, s29
	v_lshl_add_u64 v[208:209], v[224:225], 0, s[52:53]
	ds_read_b128 v[156:159], v172 offset:32768
	ds_read_b128 v[160:163], v172 offset:33792
	ds_read_b128 v[174:177], v172 offset:34816
	ds_read_b128 v[178:181], v172 offset:35840
	ds_read_b128 v[182:185], v172 offset:36864
	ds_read_b128 v[196:199], v172 offset:37888
	ds_read_b128 v[200:203], v172 offset:38912
	ds_read_b128 v[204:207], v172 offset:39936
	global_load_lds_dwordx4 v[208:209], off
	v_lshl_add_u64 v[208:209], v[224:225], 0, s[54:55]
	s_mov_b32 m0, s30
	s_nop 0
	global_load_lds_dwordx4 v[208:209], off
	s_waitcnt lgkmcnt(8)
	s_barrier
	s_waitcnt lgkmcnt(0)
	v_mfma_f32_16x16x32_bf16 v[132:135], v[136:139], v[156:159], v[132:135]
	v_mfma_f32_16x16x32_bf16 v[128:131], v[148:151], v[156:159], v[128:131]
	v_mfma_f32_16x16x32_bf16 v[116:119], v[136:139], v[174:177], v[116:119]
	v_mfma_f32_16x16x32_bf16 v[112:115], v[148:151], v[174:177], v[112:115]
	v_mfma_f32_16x16x32_bf16 v[100:103], v[136:139], v[182:185], v[100:103]
	v_mfma_f32_16x16x32_bf16 v[96:99], v[148:151], v[182:185], v[96:99]
	v_mfma_f32_16x16x32_bf16 v[84:87], v[136:139], v[200:203], v[84:87]
	v_mfma_f32_16x16x32_bf16 v[80:83], v[148:151], v[200:203], v[80:83]
	v_mfma_f32_16x16x32_bf16 v[132:135], v[144:147], v[160:163], v[132:135]
	v_mfma_f32_16x16x32_bf16 v[128:131], v[152:155], v[160:163], v[128:131]
	v_mfma_f32_16x16x32_bf16 v[116:119], v[144:147], v[178:181], v[116:119]
	v_mfma_f32_16x16x32_bf16 v[112:115], v[152:155], v[178:181], v[112:115]
	v_mfma_f32_16x16x32_bf16 v[100:103], v[144:147], v[196:199], v[100:103]
	v_mfma_f32_16x16x32_bf16 v[96:99], v[152:155], v[196:199], v[96:99]
	v_mfma_f32_16x16x32_bf16 v[84:87], v[144:147], v[204:207], v[84:87]
	v_mfma_f32_16x16x32_bf16 v[80:83], v[152:155], v[204:207], v[80:83]
	s_barrier
; #define G_STAGE(bufoff, gbase, o0, h64) do { \
;         __builtin_amdgcn_global_load_lds((const unsigned*)((const char*)(gbase) + (o0)), (LAS unsigned*)(lds + (bufoff) + ldsw), 16, 0, 0); \
;         __builtin_amdgcn_global_load_lds((const unsigned*)((const char*)(gbase) + (h64) + (o0)), (LAS unsigned*)(lds + (bufoff) + ldsw + 8192), 16, 0, 0); } while (0)
; #define G_LDA(dst, b, h) do { _Pragma("unroll") for (int m = 0; m < 4; ++m) _Pragma("unroll") for (int k = 0; k < 2; ++k) dst[m][k] = *(const LAS bf16x8*)(lds + G_SA(b, h) + aoff + m * 2048 + k * 1024); } while (0)
; #define G_LDB(dst, b, h) do { _Pragma("unroll") for (int n = 0; n < 2; ++n) _Pragma("unroll") for (int k = 0; k < 2; ++k) dst[n][k] = *(const LAS bf16x8*)(lds + G_SB(b, h) + boff + n * 2048 + k * 1024); } while (0)
; #define G_WAIT_V(n) asm volatile("s_waitcnt vmcnt(" #n ")" ::: "memory")
; #define G_WAIT_L(n) asm volatile("s_waitcnt lgkmcnt(" #n ")" ::: "memory")
; #define G_BAR __builtin_amdgcn_s_barrier()
; #define G_SCHED __builtin_amdgcn_sched_barrier(0)
;     ...
;             G_LDB(B1, 1, 1); G_STAGE(G_SB(1, 0), b3, cB0, qB);
;             G_BAR; G_WAIT_L(0); G_MMA(0, 1, At, B1); G_BAR;
;             G_LDA(At, 1, 1); G_STAGE(G_SA(1, 0), a3, cA0, qA);
;             G_BAR; G_WAIT_L(0); G_MMA(1, 0, At, B0); G_BAR; G_SCHED;
;             G_STAGE(G_SB(1, 1), b3 + chB, cB0, qB);
;             G_WAIT_V(6); G_BAR; G_MMA(1, 1, At, B1); G_BAR;
;         }
	s_add_i32 s5, 0, 0x1c000
	s_add_i32 s4, s4, s26
	v_add_u32_e32 v0, s5, v167
	v_lshl_add_u64 v[226:227], v[164:165], 0, s[46:47]
	s_mov_b32 m0, s4
	ds_read_b128 v[208:211], v0
	ds_read_b128 v[212:215], v0 offset:1024
	ds_read_b128 v[216:219], v0 offset:2048
	ds_read_b128 v[220:223], v0 offset:3072
	global_load_lds_dwordx4 v[226:227], off
	v_lshl_add_u64 v[226:227], v[164:165], 0, s[58:59]
	s_add_i32 m0, s4, 0x2000
	s_nop 0
	global_load_lds_dwordx4 v[226:227], off
	s_barrier
	s_waitcnt lgkmcnt(0)
	v_mfma_f32_16x16x32_bf16 v[124:127], v[208:211], v[156:159], v[124:127]
	v_mfma_f32_16x16x32_bf16 v[120:123], v[216:219], v[156:159], v[120:123]
	v_mfma_f32_16x16x32_bf16 v[108:111], v[208:211], v[174:177], v[108:111]
	v_mfma_f32_16x16x32_bf16 v[104:107], v[216:219], v[174:177], v[104:107]
	v_mfma_f32_16x16x32_bf16 v[92:95], v[208:211], v[182:185], v[92:95]
	v_mfma_f32_16x16x32_bf16 v[88:91], v[216:219], v[182:185], v[88:91]
	v_mfma_f32_16x16x32_bf16 v[76:79], v[208:211], v[200:203], v[76:79]
	v_mfma_f32_16x16x32_bf16 v[72:75], v[216:219], v[200:203], v[72:75]
	v_mfma_f32_16x16x32_bf16 v[124:127], v[212:215], v[160:163], v[124:127]
	v_mfma_f32_16x16x32_bf16 v[120:123], v[220:223], v[160:163], v[120:123]
	v_mfma_f32_16x16x32_bf16 v[108:111], v[212:215], v[178:181], v[108:111]
	v_mfma_f32_16x16x32_bf16 v[104:107], v[220:223], v[178:181], v[104:107]
	v_mfma_f32_16x16x32_bf16 v[92:95], v[212:215], v[196:199], v[92:95]
	v_mfma_f32_16x16x32_bf16 v[88:91], v[220:223], v[196:199], v[88:91]
	v_mfma_f32_16x16x32_bf16 v[76:79], v[212:215], v[204:207], v[76:79]
	v_mfma_f32_16x16x32_bf16 v[72:75], v[220:223], v[204:207], v[72:75]
	s_barrier
	s_mov_b32 m0, s31
	v_lshl_add_u64 v[226:227], v[224:225], 0, s[46:47]
	ds_read_b128 v[156:159], v172 offset:49152
	ds_read_b128 v[160:163], v172 offset:50176
	ds_read_b128 v[174:177], v172 offset:51200
	ds_read_b128 v[178:181], v172 offset:52224
	ds_read_b128 v[182:185], v172 offset:53248
	ds_read_b128 v[196:199], v172 offset:54272
	ds_read_b128 v[200:203], v172 offset:55296
	ds_read_b128 v[204:207], v172 offset:56320
	global_load_lds_dwordx4 v[226:227], off
	v_lshl_add_u64 v[224:225], v[224:225], 0, s[58:59]
	s_mov_b32 m0, s34
	s_nop 0
	global_load_lds_dwordx4 v[224:225], off
	s_barrier
	s_waitcnt lgkmcnt(0)
	v_mfma_f32_16x16x32_bf16 v[68:71], v[136:139], v[156:159], v[68:71]
	v_mfma_f32_16x16x32_bf16 v[64:67], v[148:151], v[156:159], v[64:67]
	v_mfma_f32_16x16x32_bf16 v[52:55], v[136:139], v[174:177], v[52:55]
	v_mfma_f32_16x16x32_bf16 v[48:51], v[148:151], v[174:177], v[48:51]
	v_mfma_f32_16x16x32_bf16 v[36:39], v[136:139], v[182:185], v[36:39]
	v_mfma_f32_16x16x32_bf16 v[32:35], v[148:151], v[182:185], v[32:35]
	v_mfma_f32_16x16x32_bf16 v[20:23], v[136:139], v[200:203], v[20:23]
	v_mfma_f32_16x16x32_bf16 v[16:19], v[148:151], v[200:203], v[16:19]
	v_mfma_f32_16x16x32_bf16 v[68:71], v[144:147], v[160:163], v[68:71]
	v_mfma_f32_16x16x32_bf16 v[64:67], v[152:155], v[160:163], v[64:67]
	v_mfma_f32_16x16x32_bf16 v[52:55], v[144:147], v[178:181], v[52:55]
	v_mfma_f32_16x16x32_bf16 v[48:51], v[152:155], v[178:181], v[48:51]
	v_mfma_f32_16x16x32_bf16 v[36:39], v[144:147], v[196:199], v[36:39]
	v_mfma_f32_16x16x32_bf16 v[32:35], v[152:155], v[196:199], v[32:35]
	v_mfma_f32_16x16x32_bf16 v[20:23], v[144:147], v[204:207], v[20:23]
	v_mfma_f32_16x16x32_bf16 v[16:19], v[152:155], v[204:207], v[16:19]
	s_barrier
	s_add_i32 s4, s5, s26
	v_lshl_add_u64 v[136:137], v[164:165], 0, s[62:63]
	s_mov_b32 m0, s4
	s_nop 0
	global_load_lds_dwordx4 v[136:137], off
	v_lshl_add_u64 v[136:137], v[164:165], 0, s[64:65]
	s_add_i32 m0, s4, 0x2000
	s_nop 0
	global_load_lds_dwordx4 v[136:137], off
	s_add_i32 s23, s23, 2
	s_add_u32 s2, s2, 0x100
	s_addc_u32 s3, s3, 0
	s_add_u32 s7, s7, 0x100
	s_addc_u32 s22, s22, 0
	s_cmp_gt_u32 s23, 13
	s_waitcnt vmcnt(6)
	s_barrier
	v_mfma_f32_16x16x32_bf16 v[60:63], v[208:211], v[156:159], v[60:63]
	v_mfma_f32_16x16x32_bf16 v[56:59], v[216:219], v[156:159], v[56:59]
	v_mfma_f32_16x16x32_bf16 v[44:47], v[208:211], v[174:177], v[44:47]
	v_mfma_f32_16x16x32_bf16 v[40:43], v[216:219], v[174:177], v[40:43]
	v_mfma_f32_16x16x32_bf16 v[28:31], v[208:211], v[182:185], v[28:31]
	v_mfma_f32_16x16x32_bf16 v[24:27], v[216:219], v[182:185], v[24:27]
	v_mfma_f32_16x16x32_bf16 v[12:15], v[208:211], v[200:203], v[12:15]
	v_mfma_f32_16x16x32_bf16 v[8:11], v[216:219], v[200:203], v[8:11]
	v_mfma_f32_16x16x32_bf16 v[60:63], v[212:215], v[160:163], v[60:63]
	v_mfma_f32_16x16x32_bf16 v[56:59], v[220:223], v[160:163], v[56:59]
	v_mfma_f32_16x16x32_bf16 v[44:47], v[212:215], v[178:181], v[44:47]
	v_mfma_f32_16x16x32_bf16 v[40:43], v[220:223], v[178:181], v[40:43]
	v_mfma_f32_16x16x32_bf16 v[28:31], v[212:215], v[196:199], v[28:31]
	v_mfma_f32_16x16x32_bf16 v[24:27], v[220:223], v[196:199], v[24:27]
	v_mfma_f32_16x16x32_bf16 v[12:15], v[212:215], v[204:207], v[12:15]
	v_mfma_f32_16x16x32_bf16 v[8:11], v[220:223], v[204:207], v[8:11]
	s_cbranch_scc0 .Ldb_WIN_cont
	v_readfirstlane_b32 s101, v186
	s_cmpk_gt_u32 s101, 0xff
	s_cbranch_scc1 .Ldb_WIN_young
	s_barrier
	s_mov_b32 s101, 1
	s_branch .Ldb_WIN_exit

; #define G_STAGE(bufoff, gbase, o0, h64) do { \
;         __builtin_amdgcn_global_load_lds((const unsigned*)((const char*)(gbase) + (o0)), (LAS unsigned*)(lds + (bufoff) + ldsw), 16, 0, 0); \
;         __builtin_amdgcn_global_load_lds((const unsigned*)((const char*)(gbase) + (h64) + (o0)), (LAS unsigned*)(lds + (bufoff) + ldsw + 8192), 16, 0, 0); } while (0)
; #define G_LDA(dst, b, h) do { _Pragma("unroll") for (int m = 0; m < 4; ++m) _Pragma("unroll") for (int k = 0; k < 2; ++k) dst[m][k] = *(const LAS bf16x8*)(lds + G_SA(b, h) + aoff + m * 2048 + k * 1024); } while (0)
; #define G_LDB(dst, b, h) do { _Pragma("unroll") for (int n = 0; n < 2; ++n) _Pragma("unroll") for (int k = 0; k < 2; ++k) dst[n][k] = *(const LAS bf16x8*)(lds + G_SB(b, h) + boff + n * 2048 + k * 1024); } while (0)
; #define G_SCHED __builtin_amdgcn_sched_barrier(0)
;     ...
;         for (int t = 0; t < nt; t += 2) {
;             const bool last = (t == nt - 2);
;             const char* a1 = cA + (size_t)(t + 1) * ckA;
;             const char* a2 = last ? nA : cA + (size_t)(t + 2) * ckA; const char* b2 = last ? nB : cB + (size_t)(t + 2) * kB;
;             const char* a3 = a2 + ckA; const char* b3 = b2 + kB;
;             G_LDB(B0, 0, 0); G_SCHED; G_LDA(At, 0, 0); G_STAGE(G_SA(1, 1), a1 + chA, cA0, qA);
;     ...
;         if (!(cs.kind == K_MG_B && cur.aux < 2))
; #pragma unroll
;         for (int a = 0; a < 2; ++a)
; #pragma unroll
;             for (int b = 0; b < 2; ++b)
; #pragma unroll
;                 for (int m = 0; m < 4; ++m)
; #pragma unroll
;                     for (int n = 0; n < 2; ++n) acc[a][b][m][n] = (f32x4){0.f, 0.f, 0.f, 0.f};
;         cur = nxt; cA = nA; cB = nB; ++ui;
.LBB0_449:
	s_add_u32 s6, s22, 0x20080
	s_addc_u32 s7, s23, 0
	s_add_u32 s19, s20, 0x100
	s_addc_u32 s20, s21, 0
	s_mov_b32 s21, -2
	s_mov_b64 s[50:51], 0x20080
	s_mov_b64 s[52:53], 0x10000
	s_mov_b64 s[54:55], 0x30000
	s_mov_b64 s[58:59], 0x10080
	s_mov_b64 s[62:63], 0x30080
	s_cmp_eq_u32 s101, 2
	s_cselect_b32 s101, 0, s101
.LBB0_450:
	s_add_u32 s4, s6, 0xfffe0080
	s_addc_u32 s5, s7, -1
	s_add_i32 s41, 0, 0x10000
	v_add_u32_e32 v0, s41, v145
	ds_read_b128 v[140:143], v0
	ds_read_b128 v[148:151], v0 offset:1024
	ds_read_b128 v[152:155], v0 offset:2048
	ds_read_b128 v[156:159], v0 offset:3072
	s_cmp_eq_u32 s21, 4
	s_cselect_b32 s23, s11, s5
	s_cselect_b32 s22, s10, s4
	s_cselect_b32 s43, s17, s20
	s_cselect_b32 s42, s16, s19
	v_lshl_add_u64 v[184:185], s[6:7], 0, v[138:139]
	s_add_i32 m0, s27, 0xc000
	ds_read_b128 v[160:163], v146
	ds_read_b128 v[164:167], v146 offset:1024
	ds_read_b128 v[172:175], v146 offset:2048
	ds_read_b128 v[176:179], v146 offset:3072
	ds_read_b128 v[180:183], v146 offset:4096
	ds_read_b128 v[196:199], v146 offset:5120
	ds_read_b128 v[200:203], v146 offset:6144
	ds_read_b128 v[204:207], v146 offset:7168
	global_load_lds_dwordx4 v[184:185], off
	v_lshl_add_u64 v[184:185], v[184:185], 0, s[52:53]
	s_add_i32 m0, s27, 0xe000
	s_nop 0
	global_load_lds_dwordx4 v[184:185], off
	s_cmp_lg_u32 s21, -2
	s_cbranch_scc1 .Lzil_SSM1_0
	v_mov_b64_e32 v[80:81], 0
	v_mov_b64_e32 v[82:83], 0
	v_mov_b64_e32 v[84:85], 0
	v_mov_b64_e32 v[86:87], 0
	v_mov_b64_e32 v[96:97], 0
	v_mov_b64_e32 v[98:99], 0
	v_mov_b64_e32 v[100:101], 0
	v_mov_b64_e32 v[102:103], 0
	v_mov_b64_e32 v[112:113], 0
	v_mov_b64_e32 v[114:115], 0
	v_mov_b64_e32 v[116:117], 0
	v_mov_b64_e32 v[118:119], 0
	v_mov_b64_e32 v[128:129], 0
	v_mov_b64_e32 v[130:131], 0
	v_mov_b64_e32 v[132:133], 0
	v_mov_b64_e32 v[134:135], 0

; #define G_STAGE(bufoff, gbase, o0, h64) do { \
;         __builtin_amdgcn_global_load_lds((const unsigned*)((const char*)(gbase) + (o0)), (LAS unsigned*)(lds + (bufoff) + ldsw), 16, 0, 0); \
;         __builtin_amdgcn_global_load_lds((const unsigned*)((const char*)(gbase) + (h64) + (o0)), (LAS unsigned*)(lds + (bufoff) + ldsw + 8192), 16, 0, 0); } while (0)
; #define G_LDA(dst, b, h) do { _Pragma("unroll") for (int m = 0; m < 4; ++m) _Pragma("unroll") for (int k = 0; k < 2; ++k) dst[m][k] = *(const LAS bf16x8*)(lds + G_SA(b, h) + aoff + m * 2048 + k * 1024); } while (0)
; #define G_LDB(dst, b, h) do { _Pragma("unroll") for (int n = 0; n < 2; ++n) _Pragma("unroll") for (int k = 0; k < 2; ++k) dst[n][k] = *(const LAS bf16x8*)(lds + G_SB(b, h) + boff + n * 2048 + k * 1024); } while (0)
; #define G_WAIT_L(n) asm volatile("s_waitcnt lgkmcnt(" #n ")" ::: "memory")
; #define G_BAR __builtin_amdgcn_s_barrier()
; #define G_SCHED __builtin_amdgcn_sched_barrier(0)
;     ...
;             G_LDB(B0, 0, 0); G_SCHED; G_LDA(At, 0, 0); G_STAGE(G_SA(1, 1), a1 + chA, cA0, qA);
;             G_WAIT_L(8); G_BAR; G_WAIT_L(0); G_MMA(0, 0, At, B0); G_BAR; G_SCHED;
;             G_LDB(B1, 0, 1); G_STAGE(G_SB(0, 0), b2, cB0, qB);
;             G_BAR; G_WAIT_L(0); G_MMA(0, 1, At, B1); G_BAR;
;             G_LDA(At, 0, 1); G_STAGE(G_SA(0, 0), a2, cA0, qA);
;             G_BAR; G_WAIT_L(0); G_MMA(1, 0, At, B0); G_BAR; G_SCHED;
;             G_STAGE(G_SB(0, 1), b2 + chB, cB0, qB);
;     ...
;         for (int a = 0; a < 2; ++a)
; #pragma unroll
;             for (int b = 0; b < 2; ++b)
; #pragma unroll
;                 for (int m = 0; m < 4; ++m)
; #pragma unroll
;                     for (int n = 0; n < 2; ++n) acc[a][b][m][n] = (f32x4){0.f, 0.f, 0.f, 0.f};
.Ldb_SSM1_sk:
	s_mov_b32 s101, 0
	s_waitcnt lgkmcnt(0)
	v_mfma_f32_16x16x32_bf16 v[132:135], v[140:143], v[160:163], v[132:135]
	v_mfma_f32_16x16x32_bf16 v[128:131], v[152:155], v[160:163], v[128:131]
	v_mfma_f32_16x16x32_bf16 v[116:119], v[140:143], v[172:175], v[116:119]
	v_mfma_f32_16x16x32_bf16 v[112:115], v[152:155], v[172:175], v[112:115]
	v_mfma_f32_16x16x32_bf16 v[100:103], v[140:143], v[180:183], v[100:103]
	v_mfma_f32_16x16x32_bf16 v[96:99], v[152:155], v[180:183], v[96:99]
	v_mfma_f32_16x16x32_bf16 v[84:87], v[140:143], v[200:203], v[84:87]
	v_mfma_f32_16x16x32_bf16 v[80:83], v[152:155], v[200:203], v[80:83]
	v_mfma_f32_16x16x32_bf16 v[132:135], v[148:151], v[164:167], v[132:135]
	v_mfma_f32_16x16x32_bf16 v[128:131], v[156:159], v[164:167], v[128:131]
	v_mfma_f32_16x16x32_bf16 v[116:119], v[148:151], v[176:179], v[116:119]
	v_mfma_f32_16x16x32_bf16 v[112:115], v[156:159], v[176:179], v[112:115]
	v_mfma_f32_16x16x32_bf16 v[100:103], v[148:151], v[196:199], v[100:103]
	v_mfma_f32_16x16x32_bf16 v[96:99], v[156:159], v[196:199], v[96:99]
	v_mfma_f32_16x16x32_bf16 v[84:87], v[148:151], v[204:207], v[84:87]
	v_mfma_f32_16x16x32_bf16 v[80:83], v[156:159], v[204:207], v[80:83]
	s_barrier
	s_add_i32 s4, 0, 0x14000
	s_add_i32 s5, s41, s26
	v_add_u32_e32 v0, s4, v145
	v_lshl_add_u64 v[184:185], s[42:43], 0, v[136:137]
	s_mov_b32 m0, s5
	ds_read_b128 v[208:211], v0
	ds_read_b128 v[212:215], v0 offset:1024
	ds_read_b128 v[216:219], v0 offset:2048
	ds_read_b128 v[220:223], v0 offset:3072
	global_load_lds_dwordx4 v[184:185], off
	v_lshl_add_u64 v[224:225], v[184:185], 0, s[52:53]
	s_add_i32 m0, s5, 0x2000
	s_nop 0
	global_load_lds_dwordx4 v[224:225], off
	s_cmp_lg_u32 s21, -2
	s_cbranch_scc1 .Lzil_SSM1_1
	v_mov_b64_e32 v[72:73], 0
	v_mov_b64_e32 v[74:75], 0
	v_mov_b64_e32 v[76:77], 0
	v_mov_b64_e32 v[78:79], 0
	v_mov_b64_e32 v[88:89], 0
	v_mov_b64_e32 v[90:91], 0
	v_mov_b64_e32 v[92:93], 0
	v_mov_b64_e32 v[94:95], 0
	v_mov_b64_e32 v[104:105], 0
	v_mov_b64_e32 v[106:107], 0
	v_mov_b64_e32 v[108:109], 0
	v_mov_b64_e32 v[110:111], 0
	v_mov_b64_e32 v[120:121], 0
	v_mov_b64_e32 v[122:123], 0
	v_mov_b64_e32 v[124:125], 0
	v_mov_b64_e32 v[126:127], 0
.Lzil_SSM1_1:
	s_barrier
	s_waitcnt lgkmcnt(0)
	v_mfma_f32_16x16x32_bf16 v[124:127], v[208:211], v[160:163], v[124:127]
	v_mfma_f32_16x16x32_bf16 v[120:123], v[216:219], v[160:163], v[120:123]
	v_mfma_f32_16x16x32_bf16 v[108:111], v[208:211], v[172:175], v[108:111]
	v_mfma_f32_16x16x32_bf16 v[104:107], v[216:219], v[172:175], v[104:107]
	v_mfma_f32_16x16x32_bf16 v[92:95], v[208:211], v[180:183], v[92:95]
	v_mfma_f32_16x16x32_bf16 v[88:91], v[216:219], v[180:183], v[88:91]
	v_mfma_f32_16x16x32_bf16 v[76:79], v[208:211], v[200:203], v[76:79]
	v_mfma_f32_16x16x32_bf16 v[72:75], v[216:219], v[200:203], v[72:75]
	v_mfma_f32_16x16x32_bf16 v[124:127], v[212:215], v[164:167], v[124:127]
	v_mfma_f32_16x16x32_bf16 v[120:123], v[220:223], v[164:167], v[120:123]
	v_mfma_f32_16x16x32_bf16 v[108:111], v[212:215], v[176:179], v[108:111]
	v_mfma_f32_16x16x32_bf16 v[104:107], v[220:223], v[176:179], v[104:107]
	v_mfma_f32_16x16x32_bf16 v[92:95], v[212:215], v[196:199], v[92:95]
	v_mfma_f32_16x16x32_bf16 v[88:91], v[220:223], v[196:199], v[88:91]
	v_mfma_f32_16x16x32_bf16 v[76:79], v[212:215], v[204:207], v[76:79]
	v_mfma_f32_16x16x32_bf16 v[72:75], v[220:223], v[204:207], v[72:75]
	s_barrier
	s_mov_b32 m0, s27
	v_lshl_add_u64 v[224:225], s[22:23], 0, v[2:3]
	ds_read_b128 v[160:163], v146 offset:16384
	ds_read_b128 v[164:167], v146 offset:17408
	ds_read_b128 v[172:175], v146 offset:18432
	ds_read_b128 v[176:179], v146 offset:19456
	ds_read_b128 v[180:183], v146 offset:20480
	ds_read_b128 v[196:199], v146 offset:21504
	ds_read_b128 v[200:203], v146 offset:22528
	ds_read_b128 v[204:207], v146 offset:23552
	global_load_lds_dwordx4 v[224:225], off
	v_lshl_add_u64 v[226:227], v[224:225], 0, s[52:53]
	s_mov_b32 m0, s28
	s_nop 0
	global_load_lds_dwordx4 v[226:227], off
	s_cmp_lg_u32 s21, -2
	s_cbranch_scc1 .Lzil_SSM1_2
	v_mov_b64_e32 v[16:17], 0
	v_mov_b64_e32 v[18:19], 0
	v_mov_b64_e32 v[20:21], 0
	v_mov_b64_e32 v[22:23], 0
	v_mov_b64_e32 v[32:33], 0
	v_mov_b64_e32 v[34:35], 0
	v_mov_b64_e32 v[36:37], 0
	v_mov_b64_e32 v[38:39], 0
	v_mov_b64_e32 v[48:49], 0
	v_mov_b64_e32 v[50:51], 0
	v_mov_b64_e32 v[52:53], 0
	v_mov_b64_e32 v[54:55], 0
	v_mov_b64_e32 v[64:65], 0
	v_mov_b64_e32 v[66:67], 0
	v_mov_b64_e32 v[68:69], 0
	v_mov_b64_e32 v[70:71], 0
.Lzil_SSM1_2:
	s_barrier
	s_waitcnt lgkmcnt(0)
	v_mfma_f32_16x16x32_bf16 v[68:71], v[140:143], v[160:163], v[68:71]
	v_mfma_f32_16x16x32_bf16 v[64:67], v[152:155], v[160:163], v[64:67]
	v_mfma_f32_16x16x32_bf16 v[52:55], v[140:143], v[172:175], v[52:55]
	v_mfma_f32_16x16x32_bf16 v[48:51], v[152:155], v[172:175], v[48:51]
	v_mfma_f32_16x16x32_bf16 v[36:39], v[140:143], v[180:183], v[36:39]
	v_mfma_f32_16x16x32_bf16 v[32:35], v[152:155], v[180:183], v[32:35]
	v_mfma_f32_16x16x32_bf16 v[20:23], v[140:143], v[200:203], v[20:23]
	v_mfma_f32_16x16x32_bf16 v[16:19], v[152:155], v[200:203], v[16:19]
	v_mfma_f32_16x16x32_bf16 v[68:71], v[148:151], v[164:167], v[68:71]
	v_mfma_f32_16x16x32_bf16 v[64:67], v[156:159], v[164:167], v[64:67]
	v_mfma_f32_16x16x32_bf16 v[52:55], v[148:151], v[176:179], v[52:55]
	v_mfma_f32_16x16x32_bf16 v[48:51], v[156:159], v[176:179], v[48:51]
	v_mfma_f32_16x16x32_bf16 v[36:39], v[148:151], v[196:199], v[36:39]
	v_mfma_f32_16x16x32_bf16 v[32:35], v[156:159], v[196:199], v[32:35]
	v_mfma_f32_16x16x32_bf16 v[20:23], v[148:151], v[204:207], v[20:23]
	v_mfma_f32_16x16x32_bf16 v[16:19], v[156:159], v[204:207], v[16:19]
	s_barrier
	s_add_i32 s4, s4, s26
	v_lshl_add_u64 v[140:141], v[184:185], 0, s[0:1]
	s_mov_b32 m0, s4
	s_nop 0
	global_load_lds_dwordx4 v[140:141], off
	v_lshl_add_u64 v[140:141], v[184:185], 0, s[54:55]
	s_add_i32 m0, s4, 0x2000
	s_nop 0
	global_load_lds_dwordx4 v[140:141], off
	s_cmp_lg_u32 s21, -2
	s_cbranch_scc1 .Lzil_SSM1_3
	v_mov_b64_e32 v[8:9], 0
	v_mov_b64_e32 v[10:11], 0
	v_mov_b64_e32 v[12:13], 0
	v_mov_b64_e32 v[14:15], 0
	v_mov_b64_e32 v[24:25], 0
	v_mov_b64_e32 v[26:27], 0
	v_mov_b64_e32 v[28:29], 0
	v_mov_b64_e32 v[30:31], 0
	v_mov_b64_e32 v[40:41], 0
	v_mov_b64_e32 v[42:43], 0
	v_mov_b64_e32 v[44:45], 0
	v_mov_b64_e32 v[46:47], 0
	v_mov_b64_e32 v[56:57], 0
	v_mov_b64_e32 v[58:59], 0
	v_mov_b64_e32 v[60:61], 0
	v_mov_b64_e32 v[62:63], 0
; #define G_STAGE(bufoff, gbase, o0, h64) do { \
;         __builtin_amdgcn_global_load_lds((const unsigned*)((const char*)(gbase) + (o0)), (LAS unsigned*)(lds + (bufoff) + ldsw), 16, 0, 0); \
;         __builtin_amdgcn_global_load_lds((const unsigned*)((const char*)(gbase) + (h64) + (o0)), (LAS unsigned*)(lds + (bufoff) + ldsw + 8192), 16, 0, 0); } while (0)
; #define G_LDA(dst, b, h) do { _Pragma("unroll") for (int m = 0; m < 4; ++m) _Pragma("unroll") for (int k = 0; k < 2; ++k) dst[m][k] = *(const LAS bf16x8*)(lds + G_SA(b, h) + aoff + m * 2048 + k * 1024); } while (0)
; #define G_LDB(dst, b, h) do { _Pragma("unroll") for (int n = 0; n < 2; ++n) _Pragma("unroll") for (int k = 0; k < 2; ++k) dst[n][k] = *(const LAS bf16x8*)(lds + G_SB(b, h) + boff + n * 2048 + k * 1024); } while (0)
; #define G_WAIT_V(n) asm volatile("s_waitcnt vmcnt(" #n ")" ::: "memory")
; #define G_WAIT_L(n) asm volatile("s_waitcnt lgkmcnt(" #n ")" ::: "memory")
; #define G_BAR __builtin_amdgcn_s_barrier()
; #define G_SCHED __builtin_amdgcn_sched_barrier(0)
;     ...
;             G_STAGE(G_SB(0, 1), b2 + chB, cB0, qB);
;             G_WAIT_V(6); G_BAR; G_MMA(1, 1, At, B1); G_BAR;
;             G_LDB(B0, 1, 0); G_SCHED; G_LDA(At, 1, 0); G_STAGE(G_SA(0, 1), a2 + chA, cA0, qA);
;             G_WAIT_L(8); G_BAR; G_WAIT_L(0); G_MMA(0, 0, At, B0); G_BAR; G_SCHED;
;             G_LDB(B1, 1, 1); G_STAGE(G_SB(1, 0), b3, cB0, qB);
;             G_BAR; G_WAIT_L(0); G_MMA(0, 1, At, B1); G_BAR;
;             G_LDA(At, 1, 1); G_STAGE(G_SA(1, 0), a3, cA0, qA);
.Lzil_SSM1_3:
	s_waitcnt vmcnt(6)
	s_barrier
	v_mfma_f32_16x16x32_bf16 v[60:63], v[208:211], v[160:163], v[60:63]
	v_mfma_f32_16x16x32_bf16 v[56:59], v[216:219], v[160:163], v[56:59]
	v_mfma_f32_16x16x32_bf16 v[44:47], v[208:211], v[172:175], v[44:47]
	v_mfma_f32_16x16x32_bf16 v[40:43], v[216:219], v[172:175], v[40:43]
	v_mfma_f32_16x16x32_bf16 v[28:31], v[208:211], v[180:183], v[28:31]
	v_mfma_f32_16x16x32_bf16 v[24:27], v[216:219], v[180:183], v[24:27]
	v_mfma_f32_16x16x32_bf16 v[12:15], v[208:211], v[200:203], v[12:15]
	v_mfma_f32_16x16x32_bf16 v[8:11], v[216:219], v[200:203], v[8:11]
	v_mfma_f32_16x16x32_bf16 v[60:63], v[212:215], v[164:167], v[60:63]
	v_mfma_f32_16x16x32_bf16 v[56:59], v[220:223], v[164:167], v[56:59]
	v_mfma_f32_16x16x32_bf16 v[44:47], v[212:215], v[176:179], v[44:47]
	v_mfma_f32_16x16x32_bf16 v[40:43], v[220:223], v[176:179], v[40:43]
	v_mfma_f32_16x16x32_bf16 v[28:31], v[212:215], v[196:199], v[28:31]
	v_mfma_f32_16x16x32_bf16 v[24:27], v[220:223], v[196:199], v[24:27]
	v_mfma_f32_16x16x32_bf16 v[12:15], v[212:215], v[204:207], v[12:15]
	v_mfma_f32_16x16x32_bf16 v[8:11], v[220:223], v[204:207], v[8:11]
	s_barrier
	s_add_i32 s4, 0, 0x18000
	v_add_u32_e32 v0, s4, v145
	ds_read_b128 v[140:143], v0
	ds_read_b128 v[148:151], v0 offset:1024
	ds_read_b128 v[152:155], v0 offset:2048
	ds_read_b128 v[156:159], v0 offset:3072
	s_mov_b32 m0, s29
	v_lshl_add_u64 v[208:209], v[224:225], 0, s[0:1]
	ds_read_b128 v[160:163], v146 offset:32768
	ds_read_b128 v[164:167], v146 offset:33792
	ds_read_b128 v[172:175], v146 offset:34816
	ds_read_b128 v[176:179], v146 offset:35840
	ds_read_b128 v[180:183], v146 offset:36864
	ds_read_b128 v[196:199], v146 offset:37888
	ds_read_b128 v[200:203], v146 offset:38912
	ds_read_b128 v[204:207], v146 offset:39936
	global_load_lds_dwordx4 v[208:209], off
	v_lshl_add_u64 v[208:209], v[224:225], 0, s[54:55]
	s_mov_b32 m0, s30
	s_nop 0
	global_load_lds_dwordx4 v[208:209], off
	s_waitcnt lgkmcnt(8)
	s_barrier
	s_waitcnt lgkmcnt(0)
	v_mfma_f32_16x16x32_bf16 v[132:135], v[140:143], v[160:163], v[132:135]
	v_mfma_f32_16x16x32_bf16 v[128:131], v[152:155], v[160:163], v[128:131]
	v_mfma_f32_16x16x32_bf16 v[116:119], v[140:143], v[172:175], v[116:119]
	v_mfma_f32_16x16x32_bf16 v[112:115], v[152:155], v[172:175], v[112:115]
	v_mfma_f32_16x16x32_bf16 v[100:103], v[140:143], v[180:183], v[100:103]
	v_mfma_f32_16x16x32_bf16 v[96:99], v[152:155], v[180:183], v[96:99]
	v_mfma_f32_16x16x32_bf16 v[84:87], v[140:143], v[200:203], v[84:87]
	v_mfma_f32_16x16x32_bf16 v[80:83], v[152:155], v[200:203], v[80:83]
	v_mfma_f32_16x16x32_bf16 v[132:135], v[148:151], v[164:167], v[132:135]
	v_mfma_f32_16x16x32_bf16 v[128:131], v[156:159], v[164:167], v[128:131]
	v_mfma_f32_16x16x32_bf16 v[116:119], v[148:151], v[176:179], v[116:119]
	v_mfma_f32_16x16x32_bf16 v[112:115], v[156:159], v[176:179], v[112:115]
	v_mfma_f32_16x16x32_bf16 v[100:103], v[148:151], v[196:199], v[100:103]
	v_mfma_f32_16x16x32_bf16 v[96:99], v[156:159], v[196:199], v[96:99]
	v_mfma_f32_16x16x32_bf16 v[84:87], v[148:151], v[204:207], v[84:87]
	v_mfma_f32_16x16x32_bf16 v[80:83], v[156:159], v[204:207], v[80:83]
	s_barrier
	s_add_i32 s5, 0, 0x1c000
	s_add_i32 s4, s4, s26
	v_add_u32_e32 v0, s5, v145
	v_lshl_add_u64 v[226:227], v[184:185], 0, s[46:47]
	s_mov_b32 m0, s4
	ds_read_b128 v[208:211], v0
	ds_read_b128 v[212:215], v0 offset:1024
	ds_read_b128 v[216:219], v0 offset:2048
	ds_read_b128 v[220:223], v0 offset:3072
	global_load_lds_dwordx4 v[226:227], off
	v_lshl_add_u64 v[226:227], v[184:185], 0, s[58:59]
	s_add_i32 m0, s4, 0x2000
	s_nop 0
	global_load_lds_dwordx4 v[226:227], off
	s_barrier
; #define G_STAGE(bufoff, gbase, o0, h64) do { \
;         __builtin_amdgcn_global_load_lds((const unsigned*)((const char*)(gbase) + (o0)), (LAS unsigned*)(lds + (bufoff) + ldsw), 16, 0, 0); \
;         __builtin_amdgcn_global_load_lds((const unsigned*)((const char*)(gbase) + (h64) + (o0)), (LAS unsigned*)(lds + (bufoff) + ldsw + 8192), 16, 0, 0); } while (0)
; #define G_LDA(dst, b, h) do { _Pragma("unroll") for (int m = 0; m < 4; ++m) _Pragma("unroll") for (int k = 0; k < 2; ++k) dst[m][k] = *(const LAS bf16x8*)(lds + G_SA(b, h) + aoff + m * 2048 + k * 1024); } while (0)
; #define G_WAIT_V(n) asm volatile("s_waitcnt vmcnt(" #n ")" ::: "memory")
; #define G_WAIT_L(n) asm volatile("s_waitcnt lgkmcnt(" #n ")" ::: "memory")
; #define G_BAR __builtin_amdgcn_s_barrier()
; #define G_SCHED __builtin_amdgcn_sched_barrier(0)
;     ...
;             G_LDA(At, 1, 1); G_STAGE(G_SA(1, 0), a3, cA0, qA);
;             G_BAR; G_WAIT_L(0); G_MMA(1, 0, At, B0); G_BAR; G_SCHED;
;             G_STAGE(G_SB(1, 1), b3 + chB, cB0, qB);
;             G_WAIT_V(6); G_BAR; G_MMA(1, 1, At, B1); G_BAR;
;         }
	s_waitcnt lgkmcnt(0)
	v_mfma_f32_16x16x32_bf16 v[124:127], v[208:211], v[160:163], v[124:127]
	v_mfma_f32_16x16x32_bf16 v[120:123], v[216:219], v[160:163], v[120:123]
	v_mfma_f32_16x16x32_bf16 v[108:111], v[208:211], v[172:175], v[108:111]
	v_mfma_f32_16x16x32_bf16 v[104:107], v[216:219], v[172:175], v[104:107]
	v_mfma_f32_16x16x32_bf16 v[92:95], v[208:211], v[180:183], v[92:95]
	v_mfma_f32_16x16x32_bf16 v[88:91], v[216:219], v[180:183], v[88:91]
	v_mfma_f32_16x16x32_bf16 v[76:79], v[208:211], v[200:203], v[76:79]
	v_mfma_f32_16x16x32_bf16 v[72:75], v[216:219], v[200:203], v[72:75]
	v_mfma_f32_16x16x32_bf16 v[124:127], v[212:215], v[164:167], v[124:127]
	v_mfma_f32_16x16x32_bf16 v[120:123], v[220:223], v[164:167], v[120:123]
	v_mfma_f32_16x16x32_bf16 v[108:111], v[212:215], v[176:179], v[108:111]
	v_mfma_f32_16x16x32_bf16 v[104:107], v[220:223], v[176:179], v[104:107]
	v_mfma_f32_16x16x32_bf16 v[92:95], v[212:215], v[196:199], v[92:95]
	v_mfma_f32_16x16x32_bf16 v[88:91], v[220:223], v[196:199], v[88:91]
	v_mfma_f32_16x16x32_bf16 v[76:79], v[212:215], v[204:207], v[76:79]
	v_mfma_f32_16x16x32_bf16 v[72:75], v[220:223], v[204:207], v[72:75]
	s_barrier
	s_mov_b32 m0, s31
	v_lshl_add_u64 v[226:227], v[224:225], 0, s[46:47]
	ds_read_b128 v[160:163], v146 offset:49152
	ds_read_b128 v[164:167], v146 offset:50176
	ds_read_b128 v[172:175], v146 offset:51200
	ds_read_b128 v[176:179], v146 offset:52224
	ds_read_b128 v[180:183], v146 offset:53248
	ds_read_b128 v[196:199], v146 offset:54272
	ds_read_b128 v[200:203], v146 offset:55296
	ds_read_b128 v[204:207], v146 offset:56320
	global_load_lds_dwordx4 v[226:227], off
	v_lshl_add_u64 v[224:225], v[224:225], 0, s[58:59]
	s_mov_b32 m0, s33
	s_nop 0
	global_load_lds_dwordx4 v[224:225], off
	s_barrier
	s_waitcnt lgkmcnt(0)
	v_mfma_f32_16x16x32_bf16 v[68:71], v[140:143], v[160:163], v[68:71]
	v_mfma_f32_16x16x32_bf16 v[64:67], v[152:155], v[160:163], v[64:67]
	v_mfma_f32_16x16x32_bf16 v[52:55], v[140:143], v[172:175], v[52:55]
	v_mfma_f32_16x16x32_bf16 v[48:51], v[152:155], v[172:175], v[48:51]
	v_mfma_f32_16x16x32_bf16 v[36:39], v[140:143], v[180:183], v[36:39]
	v_mfma_f32_16x16x32_bf16 v[32:35], v[152:155], v[180:183], v[32:35]
	v_mfma_f32_16x16x32_bf16 v[20:23], v[140:143], v[200:203], v[20:23]
	v_mfma_f32_16x16x32_bf16 v[16:19], v[152:155], v[200:203], v[16:19]
	v_mfma_f32_16x16x32_bf16 v[68:71], v[148:151], v[164:167], v[68:71]
	v_mfma_f32_16x16x32_bf16 v[64:67], v[156:159], v[164:167], v[64:67]
	v_mfma_f32_16x16x32_bf16 v[52:55], v[148:151], v[176:179], v[52:55]
	v_mfma_f32_16x16x32_bf16 v[48:51], v[156:159], v[176:179], v[48:51]
	v_mfma_f32_16x16x32_bf16 v[36:39], v[148:151], v[196:199], v[36:39]
	v_mfma_f32_16x16x32_bf16 v[32:35], v[156:159], v[196:199], v[32:35]
	v_mfma_f32_16x16x32_bf16 v[20:23], v[148:151], v[204:207], v[20:23]
	v_mfma_f32_16x16x32_bf16 v[16:19], v[156:159], v[204:207], v[16:19]
	s_barrier
	s_add_i32 s4, s5, s26
	v_lshl_add_u64 v[140:141], v[184:185], 0, s[50:51]
	s_mov_b32 m0, s4
	s_nop 0
	global_load_lds_dwordx4 v[140:141], off
	v_lshl_add_u64 v[140:141], v[184:185], 0, s[62:63]
	s_add_i32 m0, s4, 0x2000
	s_nop 0
	global_load_lds_dwordx4 v[140:141], off
	s_add_i32 s21, s21, 2
	s_add_u32 s6, s6, 0x100
	s_addc_u32 s7, s7, 0
	s_add_u32 s19, s19, 0x100
	s_addc_u32 s20, s20, 0
	s_cmp_gt_u32 s21, 5
	s_waitcnt vmcnt(6)
	s_barrier
	v_mfma_f32_16x16x32_bf16 v[60:63], v[208:211], v[160:163], v[60:63]
	v_mfma_f32_16x16x32_bf16 v[56:59], v[216:219], v[160:163], v[56:59]
	v_mfma_f32_16x16x32_bf16 v[44:47], v[208:211], v[172:175], v[44:47]
	v_mfma_f32_16x16x32_bf16 v[40:43], v[216:219], v[172:175], v[40:43]
	v_mfma_f32_16x16x32_bf16 v[28:31], v[208:211], v[180:183], v[28:31]
	v_mfma_f32_16x16x32_bf16 v[24:27], v[216:219], v[180:183], v[24:27]
	v_mfma_f32_16x16x32_bf16 v[12:15], v[208:211], v[200:203], v[12:15]
	v_mfma_f32_16x16x32_bf16 v[8:11], v[216:219], v[200:203], v[8:11]
	v_mfma_f32_16x16x32_bf16 v[60:63], v[212:215], v[164:167], v[60:63]
	v_mfma_f32_16x16x32_bf16 v[56:59], v[220:223], v[164:167], v[56:59]
	v_mfma_f32_16x16x32_bf16 v[44:47], v[212:215], v[176:179], v[44:47]
	v_mfma_f32_16x16x32_bf16 v[40:43], v[220:223], v[176:179], v[40:43]
	v_mfma_f32_16x16x32_bf16 v[28:31], v[212:215], v[196:199], v[28:31]
	v_mfma_f32_16x16x32_bf16 v[24:27], v[220:223], v[196:199], v[24:27]
	v_mfma_f32_16x16x32_bf16 v[12:15], v[212:215], v[204:207], v[12:15]
	v_mfma_f32_16x16x32_bf16 v[8:11], v[220:223], v[204:207], v[8:11]
	s_cbranch_scc0 .Ldb_SSM1_cont
	v_readfirstlane_b32 s101, v186
	s_cmpk_gt_u32 s101, 0xff
	s_cbranch_scc1 .Ldb_SSM1_young
	s_barrier
	s_mov_b32 s101, 1
	s_branch .Ldb_SSM1_exit

; #define G_STAGE(bufoff, gbase, o0, h64) do { \
;         __builtin_amdgcn_global_load_lds((const unsigned*)((const char*)(gbase) + (o0)), (LAS unsigned*)(lds + (bufoff) + ldsw), 16, 0, 0); \
;         __builtin_amdgcn_global_load_lds((const unsigned*)((const char*)(gbase) + (h64) + (o0)), (LAS unsigned*)(lds + (bufoff) + ldsw + 8192), 16, 0, 0); } while (0)
; #define G_LDA(dst, b, h) do { _Pragma("unroll") for (int m = 0; m < 4; ++m) _Pragma("unroll") for (int k = 0; k < 2; ++k) dst[m][k] = *(const LAS bf16x8*)(lds + G_SA(b, h) + aoff + m * 2048 + k * 1024); } while (0)
; #define G_LDB(dst, b, h) do { _Pragma("unroll") for (int n = 0; n < 2; ++n) _Pragma("unroll") for (int k = 0; k < 2; ++k) dst[n][k] = *(const LAS bf16x8*)(lds + G_SB(b, h) + boff + n * 2048 + k * 1024); } while (0)
; #define G_SCHED __builtin_amdgcn_sched_barrier(0)
;     ...
;         for (int t = 0; t < nt; t += 2) {
;             const bool last = (t == nt - 2);
;             const char* a1 = cA + (size_t)(t + 1) * ckA;
;             const char* a2 = last ? nA : cA + (size_t)(t + 2) * ckA; const char* b2 = last ? nB : cB + (size_t)(t + 2) * kB;
;             const char* a3 = a2 + ckA; const char* b3 = b2 + kB;
;             G_LDB(B0, 0, 0); G_SCHED; G_LDA(At, 0, 0); G_STAGE(G_SA(1, 1), a1 + chA, cA0, qA);
;     ...
;         if (!(cs.kind == K_MG_B && cur.aux < 2))
; #pragma unroll
;         for (int a = 0; a < 2; ++a)
; #pragma unroll
;             for (int b = 0; b < 2; ++b)
; #pragma unroll
;                 for (int m = 0; m < 4; ++m)
; #pragma unroll
;                     for (int n = 0; n < 2; ++n) acc[a][b][m][n] = (f32x4){0.f, 0.f, 0.f, 0.f};
;         cur = nxt; cA = nA; cB = nB; ++ui;
.LBB0_803:
	s_add_u32 s13, s18, 0x100
	s_addc_u32 s18, s19, 0
	s_add_u32 s2, s2, 0x800000
	s_addc_u32 s3, s3, 0
	s_mov_b32 s19, -2
	s_mov_b64 s[42:43], 0x20080
	s_mov_b64 s[50:51], 0x10000
	s_mov_b64 s[52:53], 0x30000
	s_mov_b64 s[54:55], 0x10080
	s_mov_b64 s[58:59], 0x30080
	s_mov_b64 s[62:63], 0x400000
	s_cmp_eq_u32 s101, 2
	s_cselect_b32 s101, 0, s101
.LBB0_804:
	s_add_i32 s40, 0, 0x10000
	v_add_u32_e32 v0, s40, v196
	ds_read_b128 v[112:115], v0
	ds_read_b128 v[124:127], v0 offset:1024
	ds_read_b128 v[136:139], v0 offset:2048
	ds_read_b128 v[148:151], v0 offset:3072
	s_cmp_eq_u32 s19, 4
	s_cselect_b32 s5, s15, s3
	s_cselect_b32 s4, s14, s2
	s_cselect_b32 s37, s17, s18
	s_cselect_b32 s36, s16, s13
	s_mov_b32 s38, 0xffc01000
	v_lshl_add_u64 v[184:185], s[2:3], 0, v[166:167]
	s_mov_b32 s39, -1
	v_lshl_add_u64 v[206:207], v[184:185], 0, s[38:39]
	s_mov_b32 s38, 0xffc01800
	s_add_i32 m0, s24, 0xc000
	s_mov_b32 s39, -1
	ds_read_b128 v[152:155], v197
	ds_read_b128 v[156:159], v197 offset:1024
	ds_read_b128 v[160:163], v197 offset:2048
	ds_read_b128 v[172:175], v197 offset:3072
	ds_read_b128 v[176:179], v197 offset:4096
	ds_read_b128 v[180:183], v197 offset:5120
	ds_read_b128 v[198:201], v197 offset:6144
	ds_read_b128 v[202:205], v197 offset:7168
	global_load_lds_dwordx4 v[206:207], off
	v_lshl_add_u64 v[184:185], v[184:185], 0, s[38:39]
	s_add_i32 m0, s24, 0xe000
	s_nop 0
	global_load_lds_dwordx4 v[184:185], off
	s_cmp_lg_u32 s19, -2
	s_cbranch_scc1 .Lzil_GLU_0
	v_mov_b64_e32 v[80:81], 0
	v_mov_b64_e32 v[82:83], 0
	v_mov_b64_e32 v[84:85], 0
	v_mov_b64_e32 v[86:87], 0
	v_mov_b64_e32 v[96:97], 0
	v_mov_b64_e32 v[98:99], 0
	v_mov_b64_e32 v[100:101], 0
	v_mov_b64_e32 v[102:103], 0
	v_mov_b64_e32 v[116:117], 0
	v_mov_b64_e32 v[118:119], 0
	v_mov_b64_e32 v[120:121], 0
	v_mov_b64_e32 v[122:123], 0
	v_mov_b64_e32 v[140:141], 0
	v_mov_b64_e32 v[142:143], 0
	v_mov_b64_e32 v[144:145], 0
	v_mov_b64_e32 v[146:147], 0

; #define G_STAGE(bufoff, gbase, o0, h64) do { \
;         __builtin_amdgcn_global_load_lds((const unsigned*)((const char*)(gbase) + (o0)), (LAS unsigned*)(lds + (bufoff) + ldsw), 16, 0, 0); \
;         __builtin_amdgcn_global_load_lds((const unsigned*)((const char*)(gbase) + (h64) + (o0)), (LAS unsigned*)(lds + (bufoff) + ldsw + 8192), 16, 0, 0); } while (0)
; #define G_LDA(dst, b, h) do { _Pragma("unroll") for (int m = 0; m < 4; ++m) _Pragma("unroll") for (int k = 0; k < 2; ++k) dst[m][k] = *(const LAS bf16x8*)(lds + G_SA(b, h) + aoff + m * 2048 + k * 1024); } while (0)
; #define G_LDB(dst, b, h) do { _Pragma("unroll") for (int n = 0; n < 2; ++n) _Pragma("unroll") for (int k = 0; k < 2; ++k) dst[n][k] = *(const LAS bf16x8*)(lds + G_SB(b, h) + boff + n * 2048 + k * 1024); } while (0)
; #define G_WAIT_L(n) asm volatile("s_waitcnt lgkmcnt(" #n ")" ::: "memory")
; #define G_BAR __builtin_amdgcn_s_barrier()
; #define G_SCHED __builtin_amdgcn_sched_barrier(0)
;     ...
;             G_LDB(B0, 0, 0); G_SCHED; G_LDA(At, 0, 0); G_STAGE(G_SA(1, 1), a1 + chA, cA0, qA);
;             G_WAIT_L(8); G_BAR; G_WAIT_L(0); G_MMA(0, 0, At, B0); G_BAR; G_SCHED;
;             G_LDB(B1, 0, 1); G_STAGE(G_SB(0, 0), b2, cB0, qB);
;             G_BAR; G_WAIT_L(0); G_MMA(0, 1, At, B1); G_BAR;
;             G_LDA(At, 0, 1); G_STAGE(G_SA(0, 0), a2, cA0, qA);
;             G_BAR; G_WAIT_L(0); G_MMA(1, 0, At, B0); G_BAR; G_SCHED;
;             G_STAGE(G_SB(0, 1), b2 + chB, cB0, qB);
;     ...
;         for (int a = 0; a < 2; ++a)
; #pragma unroll
;             for (int b = 0; b < 2; ++b)
; #pragma unroll
;                 for (int m = 0; m < 4; ++m)
; #pragma unroll
;                     for (int n = 0; n < 2; ++n) acc[a][b][m][n] = (f32x4){0.f, 0.f, 0.f, 0.f};
.Ldb_GLU_sk:
	s_mov_b32 s101, 0
	s_waitcnt lgkmcnt(0)
	v_mfma_f32_16x16x32_bf16 v[144:147], v[112:115], v[152:155], v[144:147]
	v_mfma_f32_16x16x32_bf16 v[140:143], v[136:139], v[152:155], v[140:143]
	v_mfma_f32_16x16x32_bf16 v[120:123], v[112:115], v[160:163], v[120:123]
	v_mfma_f32_16x16x32_bf16 v[116:119], v[136:139], v[160:163], v[116:119]
	v_mfma_f32_16x16x32_bf16 v[100:103], v[112:115], v[176:179], v[100:103]
	v_mfma_f32_16x16x32_bf16 v[96:99], v[136:139], v[176:179], v[96:99]
	v_mfma_f32_16x16x32_bf16 v[84:87], v[112:115], v[198:201], v[84:87]
	v_mfma_f32_16x16x32_bf16 v[80:83], v[136:139], v[198:201], v[80:83]
	v_mfma_f32_16x16x32_bf16 v[144:147], v[124:127], v[156:159], v[144:147]
	v_mfma_f32_16x16x32_bf16 v[140:143], v[148:151], v[156:159], v[140:143]
	v_mfma_f32_16x16x32_bf16 v[120:123], v[124:127], v[172:175], v[120:123]
	v_mfma_f32_16x16x32_bf16 v[116:119], v[148:151], v[172:175], v[116:119]
	v_mfma_f32_16x16x32_bf16 v[100:103], v[124:127], v[180:183], v[100:103]
	v_mfma_f32_16x16x32_bf16 v[96:99], v[148:151], v[180:183], v[96:99]
	v_mfma_f32_16x16x32_bf16 v[84:87], v[124:127], v[202:205], v[84:87]
	v_mfma_f32_16x16x32_bf16 v[80:83], v[148:151], v[202:205], v[80:83]
	s_barrier
	s_add_i32 s38, 0, 0x14000
	v_lshl_add_u64 v[184:185], s[36:37], 0, v[2:3]
	s_add_i32 s36, s40, s21
	v_add_u32_e32 v0, s38, v196
	s_mov_b32 m0, s36
	ds_read_b128 v[206:209], v0
	ds_read_b128 v[210:213], v0 offset:1024
	ds_read_b128 v[214:217], v0 offset:2048
	ds_read_b128 v[218:221], v0 offset:3072
	global_load_lds_dwordx4 v[184:185], off
	v_lshl_add_u64 v[222:223], v[184:185], 0, s[50:51]
	s_add_i32 m0, s36, 0x2000
	s_nop 0
	global_load_lds_dwordx4 v[222:223], off
	s_cmp_lg_u32 s19, -2
	s_cbranch_scc1 .Lzil_GLU_1
	v_mov_b64_e32 v[72:73], 0
	v_mov_b64_e32 v[74:75], 0
	v_mov_b64_e32 v[76:77], 0
	v_mov_b64_e32 v[78:79], 0
	v_mov_b64_e32 v[88:89], 0
	v_mov_b64_e32 v[90:91], 0
	v_mov_b64_e32 v[92:93], 0
	v_mov_b64_e32 v[94:95], 0
	v_mov_b64_e32 v[104:105], 0
	v_mov_b64_e32 v[106:107], 0
	v_mov_b64_e32 v[108:109], 0
	v_mov_b64_e32 v[110:111], 0
	v_mov_b64_e32 v[128:129], 0
	v_mov_b64_e32 v[130:131], 0
	v_mov_b64_e32 v[132:133], 0
	v_mov_b64_e32 v[134:135], 0
.Lzil_GLU_1:
	s_barrier
	s_waitcnt lgkmcnt(0)
	v_mfma_f32_16x16x32_bf16 v[132:135], v[206:209], v[152:155], v[132:135]
	v_mfma_f32_16x16x32_bf16 v[128:131], v[214:217], v[152:155], v[128:131]
	v_mfma_f32_16x16x32_bf16 v[108:111], v[206:209], v[160:163], v[108:111]
	v_mfma_f32_16x16x32_bf16 v[104:107], v[214:217], v[160:163], v[104:107]
	v_mfma_f32_16x16x32_bf16 v[92:95], v[206:209], v[176:179], v[92:95]
	v_mfma_f32_16x16x32_bf16 v[88:91], v[214:217], v[176:179], v[88:91]
	v_mfma_f32_16x16x32_bf16 v[76:79], v[206:209], v[198:201], v[76:79]
	v_mfma_f32_16x16x32_bf16 v[72:75], v[214:217], v[198:201], v[72:75]
	v_mfma_f32_16x16x32_bf16 v[132:135], v[210:213], v[156:159], v[132:135]
	v_mfma_f32_16x16x32_bf16 v[128:131], v[218:221], v[156:159], v[128:131]
	v_mfma_f32_16x16x32_bf16 v[108:111], v[210:213], v[172:175], v[108:111]
	v_mfma_f32_16x16x32_bf16 v[104:107], v[218:221], v[172:175], v[104:107]
	v_mfma_f32_16x16x32_bf16 v[92:95], v[210:213], v[180:183], v[92:95]
	v_mfma_f32_16x16x32_bf16 v[88:91], v[218:221], v[180:183], v[88:91]
	v_mfma_f32_16x16x32_bf16 v[76:79], v[210:213], v[202:205], v[76:79]
	v_mfma_f32_16x16x32_bf16 v[72:75], v[218:221], v[202:205], v[72:75]
	s_barrier
	s_mov_b32 m0, s24
	v_lshl_add_u64 v[222:223], s[4:5], 0, v[164:165]
	ds_read_b128 v[152:155], v197 offset:16384
	ds_read_b128 v[156:159], v197 offset:17408
	ds_read_b128 v[160:163], v197 offset:18432
	ds_read_b128 v[172:175], v197 offset:19456
	ds_read_b128 v[176:179], v197 offset:20480
	ds_read_b128 v[180:183], v197 offset:21504
	ds_read_b128 v[198:201], v197 offset:22528
	ds_read_b128 v[202:205], v197 offset:23552
	global_load_lds_dwordx4 v[222:223], off
	v_lshl_add_u64 v[224:225], v[222:223], 0, s[70:71]
	s_mov_b32 m0, s25
	s_nop 0
	global_load_lds_dwordx4 v[224:225], off
	s_cmp_lg_u32 s19, -2
	s_cbranch_scc1 .Lzil_GLU_2
	v_mov_b64_e32 v[16:17], 0
	v_mov_b64_e32 v[18:19], 0
	v_mov_b64_e32 v[20:21], 0
	v_mov_b64_e32 v[22:23], 0
	v_mov_b64_e32 v[32:33], 0
	v_mov_b64_e32 v[34:35], 0
	v_mov_b64_e32 v[36:37], 0
	v_mov_b64_e32 v[38:39], 0
	v_mov_b64_e32 v[48:49], 0
	v_mov_b64_e32 v[50:51], 0
	v_mov_b64_e32 v[52:53], 0
	v_mov_b64_e32 v[54:55], 0
	v_mov_b64_e32 v[64:65], 0
	v_mov_b64_e32 v[66:67], 0
	v_mov_b64_e32 v[68:69], 0
	v_mov_b64_e32 v[70:71], 0
.Lzil_GLU_2:
	s_barrier
	s_waitcnt lgkmcnt(0)
	v_mfma_f32_16x16x32_bf16 v[68:71], v[112:115], v[152:155], v[68:71]
	v_mfma_f32_16x16x32_bf16 v[64:67], v[136:139], v[152:155], v[64:67]
	v_mfma_f32_16x16x32_bf16 v[52:55], v[112:115], v[160:163], v[52:55]
	v_mfma_f32_16x16x32_bf16 v[48:51], v[136:139], v[160:163], v[48:51]
	v_mfma_f32_16x16x32_bf16 v[36:39], v[112:115], v[176:179], v[36:39]
	v_mfma_f32_16x16x32_bf16 v[32:35], v[136:139], v[176:179], v[32:35]
	v_mfma_f32_16x16x32_bf16 v[20:23], v[112:115], v[198:201], v[20:23]
	v_mfma_f32_16x16x32_bf16 v[16:19], v[136:139], v[198:201], v[16:19]
	v_mfma_f32_16x16x32_bf16 v[68:71], v[124:127], v[156:159], v[68:71]
	v_mfma_f32_16x16x32_bf16 v[64:67], v[148:151], v[156:159], v[64:67]
	v_mfma_f32_16x16x32_bf16 v[52:55], v[124:127], v[172:175], v[52:55]
	v_mfma_f32_16x16x32_bf16 v[48:51], v[148:151], v[172:175], v[48:51]
	v_mfma_f32_16x16x32_bf16 v[36:39], v[124:127], v[180:183], v[36:39]
	v_mfma_f32_16x16x32_bf16 v[32:35], v[148:151], v[180:183], v[32:35]
	v_mfma_f32_16x16x32_bf16 v[20:23], v[124:127], v[202:205], v[20:23]
	v_mfma_f32_16x16x32_bf16 v[16:19], v[148:151], v[202:205], v[16:19]
	s_barrier
	s_add_i32 s4, s38, s21
	v_lshl_add_u64 v[112:113], v[184:185], 0, s[0:1]
	s_mov_b32 m0, s4
	s_nop 0
	global_load_lds_dwordx4 v[112:113], off
	v_lshl_add_u64 v[112:113], v[184:185], 0, s[52:53]
	s_add_i32 m0, s4, 0x2000
	s_nop 0
	global_load_lds_dwordx4 v[112:113], off
	s_cmp_lg_u32 s19, -2
	s_cbranch_scc1 .Lzil_GLU_3
	v_mov_b64_e32 v[8:9], 0
	v_mov_b64_e32 v[10:11], 0
	v_mov_b64_e32 v[12:13], 0
	v_mov_b64_e32 v[14:15], 0
	v_mov_b64_e32 v[24:25], 0
	v_mov_b64_e32 v[26:27], 0
	v_mov_b64_e32 v[28:29], 0
	v_mov_b64_e32 v[30:31], 0
	v_mov_b64_e32 v[40:41], 0
	v_mov_b64_e32 v[42:43], 0
	v_mov_b64_e32 v[44:45], 0
	v_mov_b64_e32 v[46:47], 0
	v_mov_b64_e32 v[56:57], 0
	v_mov_b64_e32 v[58:59], 0
	v_mov_b64_e32 v[60:61], 0
	v_mov_b64_e32 v[62:63], 0
; #define G_STAGE(bufoff, gbase, o0, h64) do { \
;         __builtin_amdgcn_global_load_lds((const unsigned*)((const char*)(gbase) + (o0)), (LAS unsigned*)(lds + (bufoff) + ldsw), 16, 0, 0); \
;         __builtin_amdgcn_global_load_lds((const unsigned*)((const char*)(gbase) + (h64) + (o0)), (LAS unsigned*)(lds + (bufoff) + ldsw + 8192), 16, 0, 0); } while (0)
; #define G_LDA(dst, b, h) do { _Pragma("unroll") for (int m = 0; m < 4; ++m) _Pragma("unroll") for (int k = 0; k < 2; ++k) dst[m][k] = *(const LAS bf16x8*)(lds + G_SA(b, h) + aoff + m * 2048 + k * 1024); } while (0)
; #define G_LDB(dst, b, h) do { _Pragma("unroll") for (int n = 0; n < 2; ++n) _Pragma("unroll") for (int k = 0; k < 2; ++k) dst[n][k] = *(const LAS bf16x8*)(lds + G_SB(b, h) + boff + n * 2048 + k * 1024); } while (0)
; #define G_WAIT_V(n) asm volatile("s_waitcnt vmcnt(" #n ")" ::: "memory")
; #define G_WAIT_L(n) asm volatile("s_waitcnt lgkmcnt(" #n ")" ::: "memory")
; #define G_BAR __builtin_amdgcn_s_barrier()
; #define G_SCHED __builtin_amdgcn_sched_barrier(0)
;     ...
;             G_STAGE(G_SB(0, 1), b2 + chB, cB0, qB);
;             G_WAIT_V(6); G_BAR; G_MMA(1, 1, At, B1); G_BAR;
;             G_LDB(B0, 1, 0); G_SCHED; G_LDA(At, 1, 0); G_STAGE(G_SA(0, 1), a2 + chA, cA0, qA);
;             G_WAIT_L(8); G_BAR; G_WAIT_L(0); G_MMA(0, 0, At, B0); G_BAR; G_SCHED;
;             G_LDB(B1, 1, 1); G_STAGE(G_SB(1, 0), b3, cB0, qB);
;             G_BAR; G_WAIT_L(0); G_MMA(0, 1, At, B1); G_BAR;
;             G_LDA(At, 1, 1); G_STAGE(G_SA(1, 0), a3, cA0, qA);
.Lzil_GLU_3:
	s_waitcnt vmcnt(6)
	s_barrier
	v_mfma_f32_16x16x32_bf16 v[60:63], v[206:209], v[152:155], v[60:63]
	v_mfma_f32_16x16x32_bf16 v[56:59], v[214:217], v[152:155], v[56:59]
	v_mfma_f32_16x16x32_bf16 v[44:47], v[206:209], v[160:163], v[44:47]
	v_mfma_f32_16x16x32_bf16 v[40:43], v[214:217], v[160:163], v[40:43]
	v_mfma_f32_16x16x32_bf16 v[28:31], v[206:209], v[176:179], v[28:31]
	v_mfma_f32_16x16x32_bf16 v[24:27], v[214:217], v[176:179], v[24:27]
	v_mfma_f32_16x16x32_bf16 v[12:15], v[206:209], v[198:201], v[12:15]
	v_mfma_f32_16x16x32_bf16 v[8:11], v[214:217], v[198:201], v[8:11]
	v_mfma_f32_16x16x32_bf16 v[60:63], v[210:213], v[156:159], v[60:63]
	v_mfma_f32_16x16x32_bf16 v[56:59], v[218:221], v[156:159], v[56:59]
	v_mfma_f32_16x16x32_bf16 v[44:47], v[210:213], v[172:175], v[44:47]
	v_mfma_f32_16x16x32_bf16 v[40:43], v[218:221], v[172:175], v[40:43]
	v_mfma_f32_16x16x32_bf16 v[28:31], v[210:213], v[180:183], v[28:31]
	v_mfma_f32_16x16x32_bf16 v[24:27], v[218:221], v[180:183], v[24:27]
	v_mfma_f32_16x16x32_bf16 v[12:15], v[210:213], v[202:205], v[12:15]
	v_mfma_f32_16x16x32_bf16 v[8:11], v[218:221], v[202:205], v[8:11]
	s_barrier
	s_add_i32 s4, 0, 0x18000
	v_add_u32_e32 v0, s4, v196
	ds_read_b128 v[112:115], v0
	ds_read_b128 v[124:127], v0 offset:1024
	ds_read_b128 v[136:139], v0 offset:2048
	ds_read_b128 v[148:151], v0 offset:3072
	s_mov_b32 m0, s26
	v_lshl_add_u64 v[206:207], v[222:223], 0, s[80:81]
	ds_read_b128 v[152:155], v197 offset:32768
	ds_read_b128 v[156:159], v197 offset:33792
	ds_read_b128 v[160:163], v197 offset:34816
	ds_read_b128 v[172:175], v197 offset:35840
	ds_read_b128 v[176:179], v197 offset:36864
	ds_read_b128 v[180:183], v197 offset:37888
	ds_read_b128 v[198:201], v197 offset:38912
	ds_read_b128 v[202:205], v197 offset:39936
	global_load_lds_dwordx4 v[206:207], off
	v_lshl_add_u64 v[206:207], v[222:223], 0, s[82:83]
	s_mov_b32 m0, s27
	s_nop 0
	global_load_lds_dwordx4 v[206:207], off
	s_waitcnt lgkmcnt(8)
	s_barrier
	s_waitcnt lgkmcnt(0)
	v_mfma_f32_16x16x32_bf16 v[144:147], v[112:115], v[152:155], v[144:147]
	v_mfma_f32_16x16x32_bf16 v[140:143], v[136:139], v[152:155], v[140:143]
	v_mfma_f32_16x16x32_bf16 v[120:123], v[112:115], v[160:163], v[120:123]
	v_mfma_f32_16x16x32_bf16 v[116:119], v[136:139], v[160:163], v[116:119]
	v_mfma_f32_16x16x32_bf16 v[100:103], v[112:115], v[176:179], v[100:103]
	v_mfma_f32_16x16x32_bf16 v[96:99], v[136:139], v[176:179], v[96:99]
	v_mfma_f32_16x16x32_bf16 v[84:87], v[112:115], v[198:201], v[84:87]
	v_mfma_f32_16x16x32_bf16 v[80:83], v[136:139], v[198:201], v[80:83]
	v_mfma_f32_16x16x32_bf16 v[144:147], v[124:127], v[156:159], v[144:147]
	v_mfma_f32_16x16x32_bf16 v[140:143], v[148:151], v[156:159], v[140:143]
	v_mfma_f32_16x16x32_bf16 v[120:123], v[124:127], v[172:175], v[120:123]
	v_mfma_f32_16x16x32_bf16 v[116:119], v[148:151], v[172:175], v[116:119]
	v_mfma_f32_16x16x32_bf16 v[100:103], v[124:127], v[180:183], v[100:103]
	v_mfma_f32_16x16x32_bf16 v[96:99], v[148:151], v[180:183], v[96:99]
	v_mfma_f32_16x16x32_bf16 v[84:87], v[124:127], v[202:205], v[84:87]
	v_mfma_f32_16x16x32_bf16 v[80:83], v[148:151], v[202:205], v[80:83]
	s_barrier
	s_add_i32 s5, 0, 0x1c000
	s_add_i32 s4, s4, s21
	v_add_u32_e32 v0, s5, v196
	v_lshl_add_u64 v[224:225], v[184:185], 0, s[46:47]
	s_mov_b32 m0, s4
	ds_read_b128 v[206:209], v0
	ds_read_b128 v[210:213], v0 offset:1024
	ds_read_b128 v[214:217], v0 offset:2048
	ds_read_b128 v[218:221], v0 offset:3072
	global_load_lds_dwordx4 v[224:225], off
	v_lshl_add_u64 v[224:225], v[184:185], 0, s[54:55]
	s_add_i32 m0, s4, 0x2000
	s_nop 0
	global_load_lds_dwordx4 v[224:225], off
	s_barrier
; #define G_STAGE(bufoff, gbase, o0, h64) do { \
;         __builtin_amdgcn_global_load_lds((const unsigned*)((const char*)(gbase) + (o0)), (LAS unsigned*)(lds + (bufoff) + ldsw), 16, 0, 0); \
;         __builtin_amdgcn_global_load_lds((const unsigned*)((const char*)(gbase) + (h64) + (o0)), (LAS unsigned*)(lds + (bufoff) + ldsw + 8192), 16, 0, 0); } while (0)
; #define G_LDA(dst, b, h) do { _Pragma("unroll") for (int m = 0; m < 4; ++m) _Pragma("unroll") for (int k = 0; k < 2; ++k) dst[m][k] = *(const LAS bf16x8*)(lds + G_SA(b, h) + aoff + m * 2048 + k * 1024); } while (0)
; #define G_WAIT_V(n) asm volatile("s_waitcnt vmcnt(" #n ")" ::: "memory")
; #define G_WAIT_L(n) asm volatile("s_waitcnt lgkmcnt(" #n ")" ::: "memory")
; #define G_BAR __builtin_amdgcn_s_barrier()
; #define G_SCHED __builtin_amdgcn_sched_barrier(0)
;     ...
;             G_LDA(At, 1, 1); G_STAGE(G_SA(1, 0), a3, cA0, qA);
;             G_BAR; G_WAIT_L(0); G_MMA(1, 0, At, B0); G_BAR; G_SCHED;
;             G_STAGE(G_SB(1, 1), b3 + chB, cB0, qB);
;             G_WAIT_V(6); G_BAR; G_MMA(1, 1, At, B1); G_BAR;
;         }
	s_waitcnt lgkmcnt(0)
	v_mfma_f32_16x16x32_bf16 v[132:135], v[206:209], v[152:155], v[132:135]
	v_mfma_f32_16x16x32_bf16 v[128:131], v[214:217], v[152:155], v[128:131]
	v_mfma_f32_16x16x32_bf16 v[108:111], v[206:209], v[160:163], v[108:111]
	v_mfma_f32_16x16x32_bf16 v[104:107], v[214:217], v[160:163], v[104:107]
	v_mfma_f32_16x16x32_bf16 v[92:95], v[206:209], v[176:179], v[92:95]
	v_mfma_f32_16x16x32_bf16 v[88:91], v[214:217], v[176:179], v[88:91]
	v_mfma_f32_16x16x32_bf16 v[76:79], v[206:209], v[198:201], v[76:79]
	v_mfma_f32_16x16x32_bf16 v[72:75], v[214:217], v[198:201], v[72:75]
	v_mfma_f32_16x16x32_bf16 v[132:135], v[210:213], v[156:159], v[132:135]
	v_mfma_f32_16x16x32_bf16 v[128:131], v[218:221], v[156:159], v[128:131]
	v_mfma_f32_16x16x32_bf16 v[108:111], v[210:213], v[172:175], v[108:111]
	v_mfma_f32_16x16x32_bf16 v[104:107], v[218:221], v[172:175], v[104:107]
	v_mfma_f32_16x16x32_bf16 v[92:95], v[210:213], v[180:183], v[92:95]
	v_mfma_f32_16x16x32_bf16 v[88:91], v[218:221], v[180:183], v[88:91]
	v_mfma_f32_16x16x32_bf16 v[76:79], v[210:213], v[202:205], v[76:79]
	v_mfma_f32_16x16x32_bf16 v[72:75], v[218:221], v[202:205], v[72:75]
	s_barrier
	s_mov_b32 m0, s29
	v_lshl_add_u64 v[224:225], v[222:223], 0, s[62:63]
	ds_read_b128 v[152:155], v197 offset:49152
	ds_read_b128 v[156:159], v197 offset:50176
	ds_read_b128 v[160:163], v197 offset:51200
	ds_read_b128 v[172:175], v197 offset:52224
	ds_read_b128 v[176:179], v197 offset:53248
	ds_read_b128 v[180:183], v197 offset:54272
	ds_read_b128 v[198:201], v197 offset:55296
	ds_read_b128 v[202:205], v197 offset:56320
	global_load_lds_dwordx4 v[224:225], off
	v_lshl_add_u64 v[222:223], v[222:223], 0, s[84:85]
	s_mov_b32 m0, s30
	s_nop 0
	global_load_lds_dwordx4 v[222:223], off
	s_barrier
	s_waitcnt lgkmcnt(0)
	v_mfma_f32_16x16x32_bf16 v[68:71], v[112:115], v[152:155], v[68:71]
	v_mfma_f32_16x16x32_bf16 v[64:67], v[136:139], v[152:155], v[64:67]
	v_mfma_f32_16x16x32_bf16 v[52:55], v[112:115], v[160:163], v[52:55]
	v_mfma_f32_16x16x32_bf16 v[48:51], v[136:139], v[160:163], v[48:51]
	v_mfma_f32_16x16x32_bf16 v[36:39], v[112:115], v[176:179], v[36:39]
	v_mfma_f32_16x16x32_bf16 v[32:35], v[136:139], v[176:179], v[32:35]
	v_mfma_f32_16x16x32_bf16 v[20:23], v[112:115], v[198:201], v[20:23]
	v_mfma_f32_16x16x32_bf16 v[16:19], v[136:139], v[198:201], v[16:19]
	v_mfma_f32_16x16x32_bf16 v[68:71], v[124:127], v[156:159], v[68:71]
	v_mfma_f32_16x16x32_bf16 v[64:67], v[148:151], v[156:159], v[64:67]
	v_mfma_f32_16x16x32_bf16 v[52:55], v[124:127], v[172:175], v[52:55]
	v_mfma_f32_16x16x32_bf16 v[48:51], v[148:151], v[172:175], v[48:51]
	v_mfma_f32_16x16x32_bf16 v[36:39], v[124:127], v[180:183], v[36:39]
	v_mfma_f32_16x16x32_bf16 v[32:35], v[148:151], v[180:183], v[32:35]
	v_mfma_f32_16x16x32_bf16 v[20:23], v[124:127], v[202:205], v[20:23]
	v_mfma_f32_16x16x32_bf16 v[16:19], v[148:151], v[202:205], v[16:19]
	s_barrier
	s_add_i32 s4, s5, s21
	v_lshl_add_u64 v[112:113], v[184:185], 0, s[42:43]
	s_mov_b32 m0, s4
	s_nop 0
	global_load_lds_dwordx4 v[112:113], off
	v_lshl_add_u64 v[112:113], v[184:185], 0, s[58:59]
	s_add_i32 m0, s4, 0x2000
	s_nop 0
	global_load_lds_dwordx4 v[112:113], off
	s_add_i32 s19, s19, 2
	s_add_u32 s13, s13, 0x100
	s_addc_u32 s18, s18, 0
	s_add_u32 s2, s2, 0x800000
	s_addc_u32 s3, s3, 0
	s_cmp_gt_u32 s19, 5
	s_waitcnt vmcnt(6)
	s_barrier
	v_mfma_f32_16x16x32_bf16 v[60:63], v[206:209], v[152:155], v[60:63]
	v_mfma_f32_16x16x32_bf16 v[56:59], v[214:217], v[152:155], v[56:59]
	v_mfma_f32_16x16x32_bf16 v[44:47], v[206:209], v[160:163], v[44:47]
	v_mfma_f32_16x16x32_bf16 v[40:43], v[214:217], v[160:163], v[40:43]
	v_mfma_f32_16x16x32_bf16 v[28:31], v[206:209], v[176:179], v[28:31]
	v_mfma_f32_16x16x32_bf16 v[24:27], v[214:217], v[176:179], v[24:27]
	v_mfma_f32_16x16x32_bf16 v[12:15], v[206:209], v[198:201], v[12:15]
	v_mfma_f32_16x16x32_bf16 v[8:11], v[214:217], v[198:201], v[8:11]
	v_mfma_f32_16x16x32_bf16 v[60:63], v[210:213], v[156:159], v[60:63]
	v_mfma_f32_16x16x32_bf16 v[56:59], v[218:221], v[156:159], v[56:59]
	v_mfma_f32_16x16x32_bf16 v[44:47], v[210:213], v[172:175], v[44:47]
	v_mfma_f32_16x16x32_bf16 v[40:43], v[218:221], v[172:175], v[40:43]
	v_mfma_f32_16x16x32_bf16 v[28:31], v[210:213], v[180:183], v[28:31]
	v_mfma_f32_16x16x32_bf16 v[24:27], v[218:221], v[180:183], v[24:27]
	v_mfma_f32_16x16x32_bf16 v[12:15], v[210:213], v[202:205], v[12:15]
	v_mfma_f32_16x16x32_bf16 v[8:11], v[218:221], v[202:205], v[8:11]
	s_cbranch_scc0 .Ldb_GLU_cont
	v_readfirstlane_b32 s101, v186
	s_cmpk_gt_u32 s101, 0xff
	s_cbranch_scc1 .Ldb_GLU_young
	s_barrier
	s_mov_b32 s101, 1
	s_branch .Ldb_GLU_exit

; #define G_STAGE(bufoff, gbase, o0, h64) do { \
;         __builtin_amdgcn_global_load_lds((const unsigned*)((const char*)(gbase) + (o0)), (LAS unsigned*)(lds + (bufoff) + ldsw), 16, 0, 0); \
;         __builtin_amdgcn_global_load_lds((const unsigned*)((const char*)(gbase) + (h64) + (o0)), (LAS unsigned*)(lds + (bufoff) + ldsw + 8192), 16, 0, 0); } while (0)
; #define G_LDA(dst, b, h) do { _Pragma("unroll") for (int m = 0; m < 4; ++m) _Pragma("unroll") for (int k = 0; k < 2; ++k) dst[m][k] = *(const LAS bf16x8*)(lds + G_SA(b, h) + aoff + m * 2048 + k * 1024); } while (0)
; #define G_LDB(dst, b, h) do { _Pragma("unroll") for (int n = 0; n < 2; ++n) _Pragma("unroll") for (int k = 0; k < 2; ++k) dst[n][k] = *(const LAS bf16x8*)(lds + G_SB(b, h) + boff + n * 2048 + k * 1024); } while (0)
; #define G_SCHED __builtin_amdgcn_sched_barrier(0)
;     ...
;         for (int t = 0; t < nt; t += 2) {
;             const bool last = (t == nt - 2);
;             const char* a1 = cA + (size_t)(t + 1) * ckA;
;             const char* a2 = last ? nA : cA + (size_t)(t + 2) * ckA; const char* b2 = last ? nB : cB + (size_t)(t + 2) * kB;
;             const char* a3 = a2 + ckA; const char* b3 = b2 + kB;
;             G_LDB(B0, 0, 0); G_SCHED; G_LDA(At, 0, 0); G_STAGE(G_SA(1, 1), a1 + chA, cA0, qA);
;     ...
;         if (!(cs.kind == K_MG_B && cur.aux < 2))
; #pragma unroll
;         for (int a = 0; a < 2; ++a)
; #pragma unroll
;             for (int b = 0; b < 2; ++b)
; #pragma unroll
;                 for (int m = 0; m < 4; ++m)
; #pragma unroll
;                     for (int n = 0; n < 2; ++n) acc[a][b][m][n] = (f32x4){0.f, 0.f, 0.f, 0.f};
;         cur = nxt; cA = nA; cB = nB; ++ui;
.LBB0_871:
	s_add_u32 s2, s2, 0xb0080
	s_addc_u32 s3, s3, 0
	s_add_u32 s37, s12, 0x100
	s_addc_u32 s38, s13, 0
	s_mov_b32 s39, -2
	s_mov_b64 s[42:43], 0x20080
	s_mov_b64 s[50:51], 0x10000
	s_mov_b64 s[52:53], 0x30000
	s_mov_b64 s[54:55], 0x10080
	s_mov_b64 s[58:59], 0x30080
	s_cmp_eq_u32 s101, 2
	s_cselect_b32 s101, 0, s101
.LBB0_872:
	s_add_u32 s4, s2, 0xfff50080
	s_addc_u32 s5, s3, -1
	s_add_i32 s40, 0, 0x10000
	v_add_u32_e32 v140, s40, v159
	ds_read_b128 v[144:147], v140
	ds_read_b128 v[148:151], v140 offset:1024
	ds_read_b128 v[136:139], v140 offset:2048
	ds_read_b128 v[140:143], v140 offset:3072
	s_cmp_eq_u32 s39, 4
	s_cselect_b32 s13, s9, s5
	s_cselect_b32 s12, s8, s4
	s_cselect_b32 s15, s11, s38
	s_cselect_b32 s14, s10, s37
	v_lshl_add_u64 v[154:155], s[2:3], 0, v[152:153]
	s_add_i32 m0, s22, 0xc000
	ds_read_b128 v[160:163], v236
	ds_read_b128 v[164:167], v236 offset:1024
	ds_read_b128 v[176:179], v236 offset:2048
	ds_read_b128 v[180:183], v236 offset:3072
	ds_read_b128 v[196:199], v236 offset:4096
	ds_read_b128 v[200:203], v236 offset:5120
	ds_read_b128 v[204:207], v236 offset:6144
	ds_read_b128 v[208:211], v236 offset:7168
	global_load_lds_dwordx4 v[154:155], off
	v_lshl_add_u64 v[154:155], v[154:155], 0, s[86:87]
	s_add_i32 m0, s22, 0xe000
	s_nop 0
	global_load_lds_dwordx4 v[154:155], off
	s_cmp_lg_u32 s39, -2
	s_cbranch_scc1 .Lzil_MG0_0
	v_mov_b64_e32 v[80:81], 0
	v_mov_b64_e32 v[82:83], 0
	v_mov_b64_e32 v[84:85], 0
	v_mov_b64_e32 v[86:87], 0
	v_mov_b64_e32 v[96:97], 0
	v_mov_b64_e32 v[98:99], 0
	v_mov_b64_e32 v[100:101], 0
	v_mov_b64_e32 v[102:103], 0
	v_mov_b64_e32 v[112:113], 0
	v_mov_b64_e32 v[114:115], 0
	v_mov_b64_e32 v[116:117], 0
	v_mov_b64_e32 v[118:119], 0
	v_mov_b64_e32 v[128:129], 0
	v_mov_b64_e32 v[130:131], 0
	v_mov_b64_e32 v[132:133], 0
	v_mov_b64_e32 v[134:135], 0

; #define G_STAGE(bufoff, gbase, o0, h64) do { \
;         __builtin_amdgcn_global_load_lds((const unsigned*)((const char*)(gbase) + (o0)), (LAS unsigned*)(lds + (bufoff) + ldsw), 16, 0, 0); \
;         __builtin_amdgcn_global_load_lds((const unsigned*)((const char*)(gbase) + (h64) + (o0)), (LAS unsigned*)(lds + (bufoff) + ldsw + 8192), 16, 0, 0); } while (0)
; #define G_LDA(dst, b, h) do { _Pragma("unroll") for (int m = 0; m < 4; ++m) _Pragma("unroll") for (int k = 0; k < 2; ++k) dst[m][k] = *(const LAS bf16x8*)(lds + G_SA(b, h) + aoff + m * 2048 + k * 1024); } while (0)
; #define G_LDB(dst, b, h) do { _Pragma("unroll") for (int n = 0; n < 2; ++n) _Pragma("unroll") for (int k = 0; k < 2; ++k) dst[n][k] = *(const LAS bf16x8*)(lds + G_SB(b, h) + boff + n * 2048 + k * 1024); } while (0)
; #define G_WAIT_L(n) asm volatile("s_waitcnt lgkmcnt(" #n ")" ::: "memory")
; #define G_BAR __builtin_amdgcn_s_barrier()
; #define G_SCHED __builtin_amdgcn_sched_barrier(0)
; __device__ __forceinline__ f32x4 mma_fp8(const bf16x8 b, const bf16x8 a, f32x4 c) { i64x2 bb, aa; __builtin_memcpy(&bb, &b, 16); __builtin_memcpy(&aa, &a, 16);
;     c = __builtin_amdgcn_mfma_f32_16x16x32_fp8_fp8(bb.x, aa.x, c, 0, 0, 0); c = __builtin_amdgcn_mfma_f32_16x16x32_fp8_fp8(bb.y, aa.y, c, 0, 0, 0); return c; }
;     ...
;             G_LDB(B0, 0, 0); G_SCHED; G_LDA(At, 0, 0); G_STAGE(G_SA(1, 1), a1 + chA, cA0, qA);
;             G_WAIT_L(8); G_BAR; G_WAIT_L(0); G_MMA(0, 0, At, B0); G_BAR; G_SCHED;
;             G_LDB(B1, 0, 1); G_STAGE(G_SB(0, 0), b2, cB0, qB);
;             G_BAR; G_WAIT_L(0); G_MMA(0, 1, At, B1); G_BAR;
;             G_LDA(At, 0, 1); G_STAGE(G_SA(0, 0), a2, cA0, qA);
;             G_BAR; G_WAIT_L(0); G_MMA(1, 0, At, B0); G_BAR; G_SCHED;
;             G_STAGE(G_SB(0, 1), b2 + chB, cB0, qB);
.Ldb_MG0_sk:
	s_mov_b32 s101, 0
	s_waitcnt lgkmcnt(0)
	v_mfma_f32_16x16x128_f8f6f4 v[128:131], v[144:151], v[160:167], v[128:131]
	v_mfma_f32_16x16x128_f8f6f4 v[132:135], v[136:143], v[160:167], v[132:135]
	v_mfma_f32_16x16x128_f8f6f4 v[112:115], v[144:151], v[176:183], v[112:115]
	v_mfma_f32_16x16x128_f8f6f4 v[116:119], v[136:143], v[176:183], v[116:119]
	v_mfma_f32_16x16x128_f8f6f4 v[96:99], v[144:151], v[196:203], v[96:99]
	v_mfma_f32_16x16x128_f8f6f4 v[100:103], v[136:143], v[196:203], v[100:103]
	v_mfma_f32_16x16x128_f8f6f4 v[80:83], v[144:151], v[204:211], v[80:83]
	v_mfma_f32_16x16x128_f8f6f4 v[84:87], v[136:143], v[204:211], v[84:87]
	s_barrier
	s_add_i32 s4, 0, 0x14000
	v_add_u32_e32 v154, s4, v159
	s_add_i32 s5, s40, s17
	ds_read_b128 v[212:215], v154
	ds_read_b128 v[216:219], v154 offset:1024
	ds_read_b128 v[220:223], v154 offset:2048
	ds_read_b128 v[224:227], v154 offset:3072
	v_lshl_add_u64 v[154:155], s[14:15], 0, v[0:1]
	s_mov_b32 m0, s5
	v_lshl_add_u64 v[156:157], v[154:155], 0, s[50:51]
	global_load_lds_dwordx4 v[154:155], off
	s_add_i32 m0, s5, 0x2000
	s_nop 0
	global_load_lds_dwordx4 v[156:157], off
	s_cmp_lg_u32 s39, -2
	s_cbranch_scc1 .Lzil_MG0_1
	v_mov_b64_e32 v[72:73], 0
	v_mov_b64_e32 v[74:75], 0
	v_mov_b64_e32 v[76:77], 0
	v_mov_b64_e32 v[78:79], 0
	v_mov_b64_e32 v[88:89], 0
	v_mov_b64_e32 v[90:91], 0
	v_mov_b64_e32 v[92:93], 0
	v_mov_b64_e32 v[94:95], 0
	v_mov_b64_e32 v[104:105], 0
	v_mov_b64_e32 v[106:107], 0
	v_mov_b64_e32 v[108:109], 0
	v_mov_b64_e32 v[110:111], 0
	v_mov_b64_e32 v[120:121], 0
	v_mov_b64_e32 v[122:123], 0
	v_mov_b64_e32 v[124:125], 0
	v_mov_b64_e32 v[126:127], 0
.Lzil_MG0_1:
	s_barrier
	s_waitcnt lgkmcnt(0)
	v_mfma_f32_16x16x128_f8f6f4 v[124:127], v[212:219], v[160:167], v[124:127]
	v_mfma_f32_16x16x128_f8f6f4 v[120:123], v[220:227], v[160:167], v[120:123]
	v_mfma_f32_16x16x128_f8f6f4 v[108:111], v[212:219], v[176:183], v[108:111]
	v_mfma_f32_16x16x128_f8f6f4 v[104:107], v[220:227], v[176:183], v[104:107]
	v_mfma_f32_16x16x128_f8f6f4 v[92:95], v[212:219], v[196:203], v[92:95]
	v_mfma_f32_16x16x128_f8f6f4 v[88:91], v[220:227], v[196:203], v[88:91]
	v_mfma_f32_16x16x128_f8f6f4 v[76:79], v[212:219], v[204:211], v[76:79]
	v_mfma_f32_16x16x128_f8f6f4 v[72:75], v[220:227], v[204:211], v[72:75]
	s_barrier
	s_mov_b32 m0, s22
	v_lshl_add_u64 v[156:157], s[12:13], 0, v[2:3]
	ds_read_b128 v[160:163], v236 offset:16384
	ds_read_b128 v[164:167], v236 offset:17408
	ds_read_b128 v[176:179], v236 offset:18432
	ds_read_b128 v[180:183], v236 offset:19456
	ds_read_b128 v[196:199], v236 offset:20480
	ds_read_b128 v[200:203], v236 offset:21504
	ds_read_b128 v[204:207], v236 offset:22528
	ds_read_b128 v[208:211], v236 offset:23552
	global_load_lds_dwordx4 v[156:157], off
	v_lshl_add_u64 v[234:235], v[156:157], 0, s[86:87]
	s_mov_b32 m0, s23
	s_nop 0
	global_load_lds_dwordx4 v[234:235], off
	s_cmp_lg_u32 s39, -2
	s_cbranch_scc1 .Lzil_MG0_2
	v_mov_b64_e32 v[16:17], 0
	v_mov_b64_e32 v[18:19], 0
	v_mov_b64_e32 v[20:21], 0
	v_mov_b64_e32 v[22:23], 0
	v_mov_b64_e32 v[32:33], 0
	v_mov_b64_e32 v[34:35], 0
	v_mov_b64_e32 v[36:37], 0
	v_mov_b64_e32 v[38:39], 0
	v_mov_b64_e32 v[48:49], 0
	v_mov_b64_e32 v[50:51], 0
	v_mov_b64_e32 v[52:53], 0
	v_mov_b64_e32 v[54:55], 0
	v_mov_b64_e32 v[64:65], 0
	v_mov_b64_e32 v[66:67], 0
	v_mov_b64_e32 v[68:69], 0
	v_mov_b64_e32 v[70:71], 0
.Lzil_MG0_2:
	s_barrier
	s_waitcnt lgkmcnt(0)
	v_mfma_f32_16x16x128_f8f6f4 v[64:67], v[144:151], v[160:167], v[64:67]
	v_mfma_f32_16x16x128_f8f6f4 v[68:71], v[136:143], v[160:167], v[68:71]
	v_mfma_f32_16x16x128_f8f6f4 v[48:51], v[144:151], v[176:183], v[48:51]
	v_mfma_f32_16x16x128_f8f6f4 v[52:55], v[136:143], v[176:183], v[52:55]
	v_mfma_f32_16x16x128_f8f6f4 v[32:35], v[144:151], v[196:203], v[32:35]
	v_mfma_f32_16x16x128_f8f6f4 v[36:39], v[136:143], v[196:203], v[36:39]
	v_mfma_f32_16x16x128_f8f6f4 v[20:23], v[144:151], v[204:211], v[20:23]
	v_mfma_f32_16x16x128_f8f6f4 v[16:19], v[136:143], v[204:211], v[16:19]
	s_barrier
	s_add_i32 s4, s4, s17
	v_lshl_add_u64 v[140:141], v[154:155], 0, s[0:1]
	s_mov_b32 m0, s4
	s_nop 0
	global_load_lds_dwordx4 v[140:141], off
	v_lshl_add_u64 v[140:141], v[154:155], 0, s[52:53]
	s_add_i32 m0, s4, 0x2000
	s_nop 0
	global_load_lds_dwordx4 v[140:141], off
	s_cmp_lg_u32 s39, -2
	s_cbranch_scc1 .Lzil_MG0_3
	v_mov_b64_e32 v[8:9], 0
	v_mov_b64_e32 v[10:11], 0
	v_mov_b64_e32 v[12:13], 0
	v_mov_b64_e32 v[14:15], 0
	v_mov_b64_e32 v[24:25], 0
	v_mov_b64_e32 v[26:27], 0
	v_mov_b64_e32 v[28:29], 0
	v_mov_b64_e32 v[30:31], 0
	v_mov_b64_e32 v[40:41], 0
	v_mov_b64_e32 v[42:43], 0
	v_mov_b64_e32 v[44:45], 0
	v_mov_b64_e32 v[46:47], 0
	v_mov_b64_e32 v[56:57], 0
	v_mov_b64_e32 v[58:59], 0
	v_mov_b64_e32 v[60:61], 0
	v_mov_b64_e32 v[62:63], 0
; #define G_STAGE(bufoff, gbase, o0, h64) do { \
;         __builtin_amdgcn_global_load_lds((const unsigned*)((const char*)(gbase) + (o0)), (LAS unsigned*)(lds + (bufoff) + ldsw), 16, 0, 0); \
;         __builtin_amdgcn_global_load_lds((const unsigned*)((const char*)(gbase) + (h64) + (o0)), (LAS unsigned*)(lds + (bufoff) + ldsw + 8192), 16, 0, 0); } while (0)
; #define G_LDA(dst, b, h) do { _Pragma("unroll") for (int m = 0; m < 4; ++m) _Pragma("unroll") for (int k = 0; k < 2; ++k) dst[m][k] = *(const LAS bf16x8*)(lds + G_SA(b, h) + aoff + m * 2048 + k * 1024); } while (0)
; #define G_LDB(dst, b, h) do { _Pragma("unroll") for (int n = 0; n < 2; ++n) _Pragma("unroll") for (int k = 0; k < 2; ++k) dst[n][k] = *(const LAS bf16x8*)(lds + G_SB(b, h) + boff + n * 2048 + k * 1024); } while (0)
; #define G_WAIT_V(n) asm volatile("s_waitcnt vmcnt(" #n ")" ::: "memory")
; #define G_WAIT_L(n) asm volatile("s_waitcnt lgkmcnt(" #n ")" ::: "memory")
; #define G_BAR __builtin_amdgcn_s_barrier()
; #define G_SCHED __builtin_amdgcn_sched_barrier(0)
;     ...
;             G_STAGE(G_SB(0, 1), b2 + chB, cB0, qB);
;             G_WAIT_V(6); G_BAR; G_MMA(1, 1, At, B1); G_BAR;
;             G_LDB(B0, 1, 0); G_SCHED; G_LDA(At, 1, 0); G_STAGE(G_SA(0, 1), a2 + chA, cA0, qA);
;             G_WAIT_L(8); G_BAR; G_WAIT_L(0); G_MMA(0, 0, At, B0); G_BAR; G_SCHED;
;             G_LDB(B1, 1, 1); G_STAGE(G_SB(1, 0), b3, cB0, qB);
;             G_BAR; G_WAIT_L(0); G_MMA(0, 1, At, B1); G_BAR;
;             G_LDA(At, 1, 1); G_STAGE(G_SA(1, 0), a3, cA0, qA);
;             G_BAR; G_WAIT_L(0); G_MMA(1, 0, At, B0); G_BAR; G_SCHED;
;             G_STAGE(G_SB(1, 1), b3 + chB, cB0, qB);
;             G_WAIT_V(6); G_BAR; G_MMA(1, 1, At, B1); G_BAR;
;         }
.Lzil_MG0_3:
	s_waitcnt vmcnt(6)
	s_barrier
	v_mfma_f32_16x16x128_f8f6f4 v[60:63], v[212:219], v[160:167], v[60:63]
	v_mfma_f32_16x16x128_f8f6f4 v[56:59], v[220:227], v[160:167], v[56:59]
	v_mfma_f32_16x16x128_f8f6f4 v[44:47], v[212:219], v[176:183], v[44:47]
	v_mfma_f32_16x16x128_f8f6f4 v[40:43], v[220:227], v[176:183], v[40:43]
	v_mfma_f32_16x16x128_f8f6f4 v[28:31], v[212:219], v[196:203], v[28:31]
	v_mfma_f32_16x16x128_f8f6f4 v[24:27], v[220:227], v[196:203], v[24:27]
	v_mfma_f32_16x16x128_f8f6f4 v[12:15], v[212:219], v[204:211], v[12:15]
	v_mfma_f32_16x16x128_f8f6f4 v[8:11], v[220:227], v[204:211], v[8:11]
	s_barrier
	s_add_i32 s4, 0, 0x18000
	v_add_u32_e32 v140, s4, v159
	ds_read_b128 v[144:147], v140
	ds_read_b128 v[148:151], v140 offset:1024
	ds_read_b128 v[136:139], v140 offset:2048
	ds_read_b128 v[140:143], v140 offset:3072
	s_mov_b32 m0, s24
	v_lshl_add_u64 v[234:235], v[156:157], 0, s[88:89]
	ds_read_b128 v[160:163], v236 offset:32768
	ds_read_b128 v[164:167], v236 offset:33792
	ds_read_b128 v[176:179], v236 offset:34816
	ds_read_b128 v[180:183], v236 offset:35840
	ds_read_b128 v[196:199], v236 offset:36864
	ds_read_b128 v[200:203], v236 offset:37888
	ds_read_b128 v[204:207], v236 offset:38912
	ds_read_b128 v[208:211], v236 offset:39936
	global_load_lds_dwordx4 v[234:235], off
	v_lshl_add_u64 v[234:235], v[156:157], 0, s[64:65]
	s_mov_b32 m0, s25
	s_nop 0
	global_load_lds_dwordx4 v[234:235], off
	s_waitcnt lgkmcnt(8)
	s_barrier
	s_waitcnt lgkmcnt(0)
	v_mfma_f32_16x16x128_f8f6f4 v[128:131], v[144:151], v[160:167], v[128:131]
	v_mfma_f32_16x16x128_f8f6f4 v[132:135], v[136:143], v[160:167], v[132:135]
	v_mfma_f32_16x16x128_f8f6f4 v[112:115], v[144:151], v[176:183], v[112:115]
	v_mfma_f32_16x16x128_f8f6f4 v[116:119], v[136:143], v[176:183], v[116:119]
	v_mfma_f32_16x16x128_f8f6f4 v[96:99], v[144:151], v[196:203], v[96:99]
	v_mfma_f32_16x16x128_f8f6f4 v[100:103], v[136:143], v[196:203], v[100:103]
	v_mfma_f32_16x16x128_f8f6f4 v[80:83], v[144:151], v[204:211], v[80:83]
	v_mfma_f32_16x16x128_f8f6f4 v[84:87], v[136:143], v[204:211], v[84:87]
	s_barrier
	s_add_i32 s5, 0, 0x1c000
	s_add_i32 s4, s4, s17
	v_add_u32_e32 v237, s5, v159
	v_lshl_add_u64 v[234:235], v[154:155], 0, s[46:47]
	s_mov_b32 m0, s4
	ds_read_b128 v[212:215], v237
	ds_read_b128 v[216:219], v237 offset:1024
	ds_read_b128 v[220:223], v237 offset:2048
	ds_read_b128 v[224:227], v237 offset:3072
	global_load_lds_dwordx4 v[234:235], off
	v_lshl_add_u64 v[234:235], v[154:155], 0, s[54:55]
	s_add_i32 m0, s4, 0x2000
	s_nop 0
	global_load_lds_dwordx4 v[234:235], off
	s_barrier
	s_waitcnt lgkmcnt(0)
	v_mfma_f32_16x16x128_f8f6f4 v[124:127], v[212:219], v[160:167], v[124:127]
	v_mfma_f32_16x16x128_f8f6f4 v[120:123], v[220:227], v[160:167], v[120:123]
	v_mfma_f32_16x16x128_f8f6f4 v[108:111], v[212:219], v[176:183], v[108:111]
	v_mfma_f32_16x16x128_f8f6f4 v[104:107], v[220:227], v[176:183], v[104:107]
	v_mfma_f32_16x16x128_f8f6f4 v[92:95], v[212:219], v[196:203], v[92:95]
	v_mfma_f32_16x16x128_f8f6f4 v[88:91], v[220:227], v[196:203], v[88:91]
	v_mfma_f32_16x16x128_f8f6f4 v[76:79], v[212:219], v[204:211], v[76:79]
	v_mfma_f32_16x16x128_f8f6f4 v[72:75], v[220:227], v[204:211], v[72:75]
	s_barrier
	s_mov_b32 m0, s26
	v_lshl_add_u64 v[234:235], v[156:157], 0, s[46:47]
	ds_read_b128 v[160:163], v236 offset:49152
	ds_read_b128 v[164:167], v236 offset:50176
	ds_read_b128 v[176:179], v236 offset:51200
	ds_read_b128 v[180:183], v236 offset:52224
	ds_read_b128 v[196:199], v236 offset:53248
	ds_read_b128 v[200:203], v236 offset:54272
	ds_read_b128 v[204:207], v236 offset:55296
	ds_read_b128 v[208:211], v236 offset:56320
	global_load_lds_dwordx4 v[234:235], off
	v_lshl_add_u64 v[156:157], v[156:157], 0, s[66:67]
	s_mov_b32 m0, s27
	s_nop 0
	global_load_lds_dwordx4 v[156:157], off
	s_barrier
	s_waitcnt lgkmcnt(0)
	v_mfma_f32_16x16x128_f8f6f4 v[64:67], v[144:151], v[160:167], v[64:67]
	v_mfma_f32_16x16x128_f8f6f4 v[68:71], v[136:143], v[160:167], v[68:71]
	v_mfma_f32_16x16x128_f8f6f4 v[48:51], v[144:151], v[176:183], v[48:51]
	v_mfma_f32_16x16x128_f8f6f4 v[52:55], v[136:143], v[176:183], v[52:55]
	v_mfma_f32_16x16x128_f8f6f4 v[32:35], v[144:151], v[196:203], v[32:35]
	v_mfma_f32_16x16x128_f8f6f4 v[36:39], v[136:143], v[196:203], v[36:39]
	v_mfma_f32_16x16x128_f8f6f4 v[20:23], v[144:151], v[204:211], v[20:23]
	v_mfma_f32_16x16x128_f8f6f4 v[16:19], v[136:143], v[204:211], v[16:19]
	s_barrier
	s_add_i32 s4, s5, s17
	v_lshl_add_u64 v[140:141], v[154:155], 0, s[42:43]
	s_mov_b32 m0, s4
	s_nop 0
	global_load_lds_dwordx4 v[140:141], off
	v_lshl_add_u64 v[140:141], v[154:155], 0, s[58:59]
	s_add_i32 m0, s4, 0x2000
	s_nop 0
	global_load_lds_dwordx4 v[140:141], off
	s_add_i32 s39, s39, 2
	s_add_u32 s2, s2, 0x100
	s_addc_u32 s3, s3, 0
	s_add_u32 s37, s37, 0x100
	s_addc_u32 s38, s38, 0
	s_cmp_gt_u32 s39, 5
	s_waitcnt vmcnt(6)
	s_barrier
	v_mfma_f32_16x16x128_f8f6f4 v[60:63], v[212:219], v[160:167], v[60:63]
	v_mfma_f32_16x16x128_f8f6f4 v[56:59], v[220:227], v[160:167], v[56:59]
	v_mfma_f32_16x16x128_f8f6f4 v[44:47], v[212:219], v[176:183], v[44:47]
	v_mfma_f32_16x16x128_f8f6f4 v[40:43], v[220:227], v[176:183], v[40:43]
	v_mfma_f32_16x16x128_f8f6f4 v[28:31], v[212:219], v[196:203], v[28:31]
	v_mfma_f32_16x16x128_f8f6f4 v[24:27], v[220:227], v[196:203], v[24:27]
	v_mfma_f32_16x16x128_f8f6f4 v[12:15], v[212:219], v[204:211], v[12:15]
	v_mfma_f32_16x16x128_f8f6f4 v[8:11], v[220:227], v[204:211], v[8:11]
	s_cbranch_scc0 .Ldb_MG0_cont
	v_readfirstlane_b32 s101, v186
	s_cmpk_gt_u32 s101, 0xff
	s_cbranch_scc1 .Ldb_MG0_young
	s_barrier
	s_mov_b32 s101, 1
	s_branch .Ldb_MG0_exit

; #define G_STAGE(bufoff, gbase, o0, h64) do { \
;         __builtin_amdgcn_global_load_lds((const unsigned*)((const char*)(gbase) + (o0)), (LAS unsigned*)(lds + (bufoff) + ldsw), 16, 0, 0); \
;         __builtin_amdgcn_global_load_lds((const unsigned*)((const char*)(gbase) + (h64) + (o0)), (LAS unsigned*)(lds + (bufoff) + ldsw + 8192), 16, 0, 0); } while (0)
; #define G_LDA(dst, b, h) do { _Pragma("unroll") for (int m = 0; m < 4; ++m) _Pragma("unroll") for (int k = 0; k < 2; ++k) dst[m][k] = *(const LAS bf16x8*)(lds + G_SA(b, h) + aoff + m * 2048 + k * 1024); } while (0)
; #define G_LDB(dst, b, h) do { _Pragma("unroll") for (int n = 0; n < 2; ++n) _Pragma("unroll") for (int k = 0; k < 2; ++k) dst[n][k] = *(const LAS bf16x8*)(lds + G_SB(b, h) + boff + n * 2048 + k * 1024); } while (0)
; #define G_SCHED __builtin_amdgcn_sched_barrier(0)
;     ...
;         for (int t = 0; t < nt; t += 2) {
;             const bool last = (t == nt - 2);
;             const char* a1 = cA + (size_t)(t + 1) * ckA;
;             const char* a2 = last ? nA : cA + (size_t)(t + 2) * ckA; const char* b2 = last ? nB : cB + (size_t)(t + 2) * kB;
;             const char* a3 = a2 + ckA; const char* b3 = b2 + kB;
;             G_LDB(B0, 0, 0); G_SCHED; G_LDA(At, 0, 0); G_STAGE(G_SA(1, 1), a1 + chA, cA0, qA);
;     ...
;         if (!(cs.kind == K_MG_B && cur.aux < 2))
; #pragma unroll
;         for (int a = 0; a < 2; ++a)
; #pragma unroll
;             for (int b = 0; b < 2; ++b)
; #pragma unroll
;                 for (int m = 0; m < 4; ++m)
; #pragma unroll
;                     for (int n = 0; n < 2; ++n) acc[a][b][m][n] = (f32x4){0.f, 0.f, 0.f, 0.f};
;         cur = nxt; cA = nA; cB = nB; ++ui;
.LBB0_1036:
	s_add_u32 s2, s2, 0x40080
	s_addc_u32 s3, s3, 0
	s_add_u32 s6, s6, 0x100
	s_waitcnt lgkmcnt(0)
	s_addc_u32 s7, s7, 0
	s_mov_b32 s15, -2
	s_mov_b64 s[42:43], 0x40000
	s_mov_b64 s[50:51], 0x60000
	s_mov_b64 s[52:53], 0x20080
	s_mov_b64 s[54:55], 0x40080
	s_mov_b64 s[58:59], 0x60080
	s_cmp_eq_u32 s101, 2
	s_cselect_b32 s101, 0, s101
.LBB0_1037:
	s_add_u32 s4, s2, 0xfffc0080
	s_addc_u32 s5, s3, -1
	s_add_i32 s33, 0, 0x10000
	v_add_u32_e32 v0, s33, v181
	ds_read_b128 v[136:139], v0
	ds_read_b128 v[140:143], v0 offset:1024
	ds_read_b128 v[144:147], v0 offset:2048
	ds_read_b128 v[148:151], v0 offset:3072
	s_cmp_eq_u32 s15, 12
	s_cselect_b32 s5, s17, s5
	s_cselect_b32 s4, s16, s4
	s_cselect_b32 s21, s19, s7
	s_cselect_b32 s20, s18, s6
	v_lshl_add_u64 v[184:185], s[2:3], 0, v[166:167]
	s_add_i32 m0, s24, 0xc000
	ds_read_b128 v[152:155], v182
	ds_read_b128 v[156:159], v182 offset:1024
	ds_read_b128 v[160:163], v182 offset:2048
	ds_read_b128 v[172:175], v182 offset:3072
	ds_read_b128 v[176:179], v182 offset:4096
	ds_read_b128 v[196:199], v182 offset:5120
	ds_read_b128 v[200:203], v182 offset:6144
	ds_read_b128 v[204:207], v182 offset:7168
	global_load_lds_dwordx4 v[184:185], off
	v_lshl_add_u64 v[184:185], v[184:185], 0, s[0:1]
	s_add_i32 m0, s24, 0xe000
	s_nop 0
	global_load_lds_dwordx4 v[184:185], off
	s_cmp_lg_u32 s15, -2
	s_cbranch_scc1 .Lzil_WOUT_0
	v_mov_b64_e32 v[80:81], 0
	v_mov_b64_e32 v[82:83], 0
	v_mov_b64_e32 v[84:85], 0
	v_mov_b64_e32 v[86:87], 0
	v_mov_b64_e32 v[96:97], 0
	v_mov_b64_e32 v[98:99], 0
	v_mov_b64_e32 v[100:101], 0
	v_mov_b64_e32 v[102:103], 0
	v_mov_b64_e32 v[112:113], 0
	v_mov_b64_e32 v[114:115], 0
	v_mov_b64_e32 v[116:117], 0
	v_mov_b64_e32 v[118:119], 0
	v_mov_b64_e32 v[128:129], 0
	v_mov_b64_e32 v[130:131], 0
	v_mov_b64_e32 v[132:133], 0
	v_mov_b64_e32 v[134:135], 0

; #define G_STAGE(bufoff, gbase, o0, h64) do { \
;         __builtin_amdgcn_global_load_lds((const unsigned*)((const char*)(gbase) + (o0)), (LAS unsigned*)(lds + (bufoff) + ldsw), 16, 0, 0); \
;         __builtin_amdgcn_global_load_lds((const unsigned*)((const char*)(gbase) + (h64) + (o0)), (LAS unsigned*)(lds + (bufoff) + ldsw + 8192), 16, 0, 0); } while (0)
; #define G_LDA(dst, b, h) do { _Pragma("unroll") for (int m = 0; m < 4; ++m) _Pragma("unroll") for (int k = 0; k < 2; ++k) dst[m][k] = *(const LAS bf16x8*)(lds + G_SA(b, h) + aoff + m * 2048 + k * 1024); } while (0)
; #define G_LDB(dst, b, h) do { _Pragma("unroll") for (int n = 0; n < 2; ++n) _Pragma("unroll") for (int k = 0; k < 2; ++k) dst[n][k] = *(const LAS bf16x8*)(lds + G_SB(b, h) + boff + n * 2048 + k * 1024); } while (0)
; #define G_WAIT_L(n) asm volatile("s_waitcnt lgkmcnt(" #n ")" ::: "memory")
; #define G_BAR __builtin_amdgcn_s_barrier()
; #define G_SCHED __builtin_amdgcn_sched_barrier(0)
;     ...
;             G_LDB(B0, 0, 0); G_SCHED; G_LDA(At, 0, 0); G_STAGE(G_SA(1, 1), a1 + chA, cA0, qA);
;             G_WAIT_L(8); G_BAR; G_WAIT_L(0); G_MMA(0, 0, At, B0); G_BAR; G_SCHED;
;             G_LDB(B1, 0, 1); G_STAGE(G_SB(0, 0), b2, cB0, qB);
;             G_BAR; G_WAIT_L(0); G_MMA(0, 1, At, B1); G_BAR;
;             G_LDA(At, 0, 1); G_STAGE(G_SA(0, 0), a2, cA0, qA);
;             G_BAR; G_WAIT_L(0); G_MMA(1, 0, At, B0); G_BAR; G_SCHED;
;             G_STAGE(G_SB(0, 1), b2 + chB, cB0, qB);
;     ...
;         for (int a = 0; a < 2; ++a)
; #pragma unroll
;             for (int b = 0; b < 2; ++b)
; #pragma unroll
;                 for (int m = 0; m < 4; ++m)
; #pragma unroll
;                     for (int n = 0; n < 2; ++n) acc[a][b][m][n] = (f32x4){0.f, 0.f, 0.f, 0.f};
.Ldb_WOUT_sk:
	s_mov_b32 s101, 0
	s_waitcnt lgkmcnt(0)
	v_mfma_f32_16x16x32_bf16 v[132:135], v[136:139], v[152:155], v[132:135]
	v_mfma_f32_16x16x32_bf16 v[128:131], v[144:147], v[152:155], v[128:131]
	v_mfma_f32_16x16x32_bf16 v[116:119], v[136:139], v[160:163], v[116:119]
	v_mfma_f32_16x16x32_bf16 v[112:115], v[144:147], v[160:163], v[112:115]
	v_mfma_f32_16x16x32_bf16 v[100:103], v[136:139], v[176:179], v[100:103]
	v_mfma_f32_16x16x32_bf16 v[96:99], v[144:147], v[176:179], v[96:99]
	v_mfma_f32_16x16x32_bf16 v[84:87], v[136:139], v[200:203], v[84:87]
	v_mfma_f32_16x16x32_bf16 v[80:83], v[144:147], v[200:203], v[80:83]
	v_mfma_f32_16x16x32_bf16 v[132:135], v[140:143], v[156:159], v[132:135]
	v_mfma_f32_16x16x32_bf16 v[128:131], v[148:151], v[156:159], v[128:131]
	v_mfma_f32_16x16x32_bf16 v[116:119], v[140:143], v[172:175], v[116:119]
	v_mfma_f32_16x16x32_bf16 v[112:115], v[148:151], v[172:175], v[112:115]
	v_mfma_f32_16x16x32_bf16 v[100:103], v[140:143], v[196:199], v[100:103]
	v_mfma_f32_16x16x32_bf16 v[96:99], v[148:151], v[196:199], v[96:99]
	v_mfma_f32_16x16x32_bf16 v[84:87], v[140:143], v[204:207], v[84:87]
	v_mfma_f32_16x16x32_bf16 v[80:83], v[148:151], v[204:207], v[80:83]
	s_barrier
	s_add_i32 s41, 0, 0x14000
	v_lshl_add_u64 v[184:185], s[20:21], 0, v[164:165]
	s_add_i32 s20, s33, s23
	v_add_u32_e32 v0, s41, v181
	s_mov_b32 m0, s20
	ds_read_b128 v[208:211], v0
	ds_read_b128 v[212:215], v0 offset:1024
	ds_read_b128 v[216:219], v0 offset:2048
	ds_read_b128 v[220:223], v0 offset:3072
	global_load_lds_dwordx4 v[184:185], off
	v_lshl_add_u64 v[224:225], v[184:185], 0, s[0:1]
	s_add_i32 m0, s20, 0x2000
	s_nop 0
	global_load_lds_dwordx4 v[224:225], off
	s_cmp_lg_u32 s15, -2
	s_cbranch_scc1 .Lzil_WOUT_1
	v_mov_b64_e32 v[72:73], 0
	v_mov_b64_e32 v[74:75], 0
	v_mov_b64_e32 v[76:77], 0
	v_mov_b64_e32 v[78:79], 0
	v_mov_b64_e32 v[88:89], 0
	v_mov_b64_e32 v[90:91], 0
	v_mov_b64_e32 v[92:93], 0
	v_mov_b64_e32 v[94:95], 0
	v_mov_b64_e32 v[104:105], 0
	v_mov_b64_e32 v[106:107], 0
	v_mov_b64_e32 v[108:109], 0
	v_mov_b64_e32 v[110:111], 0
	v_mov_b64_e32 v[120:121], 0
	v_mov_b64_e32 v[122:123], 0
	v_mov_b64_e32 v[124:125], 0
	v_mov_b64_e32 v[126:127], 0
.Lzil_WOUT_1:
	s_barrier
	s_waitcnt lgkmcnt(0)
	v_mfma_f32_16x16x32_bf16 v[124:127], v[208:211], v[152:155], v[124:127]
	v_mfma_f32_16x16x32_bf16 v[120:123], v[216:219], v[152:155], v[120:123]
	v_mfma_f32_16x16x32_bf16 v[108:111], v[208:211], v[160:163], v[108:111]
	v_mfma_f32_16x16x32_bf16 v[104:107], v[216:219], v[160:163], v[104:107]
	v_mfma_f32_16x16x32_bf16 v[92:95], v[208:211], v[176:179], v[92:95]
	v_mfma_f32_16x16x32_bf16 v[88:91], v[216:219], v[176:179], v[88:91]
	v_mfma_f32_16x16x32_bf16 v[76:79], v[208:211], v[200:203], v[76:79]
	v_mfma_f32_16x16x32_bf16 v[72:75], v[216:219], v[200:203], v[72:75]
	v_mfma_f32_16x16x32_bf16 v[124:127], v[212:215], v[156:159], v[124:127]
	v_mfma_f32_16x16x32_bf16 v[120:123], v[220:223], v[156:159], v[120:123]
	v_mfma_f32_16x16x32_bf16 v[108:111], v[212:215], v[172:175], v[108:111]
	v_mfma_f32_16x16x32_bf16 v[104:107], v[220:223], v[172:175], v[104:107]
	v_mfma_f32_16x16x32_bf16 v[92:95], v[212:215], v[196:199], v[92:95]
	v_mfma_f32_16x16x32_bf16 v[88:91], v[220:223], v[196:199], v[88:91]
	v_mfma_f32_16x16x32_bf16 v[76:79], v[212:215], v[204:207], v[76:79]
	v_mfma_f32_16x16x32_bf16 v[72:75], v[220:223], v[204:207], v[72:75]
	s_barrier
	s_mov_b32 m0, s24
	v_lshl_add_u64 v[224:225], s[4:5], 0, v[2:3]
	ds_read_b128 v[152:155], v182 offset:16384
	ds_read_b128 v[156:159], v182 offset:17408
	ds_read_b128 v[160:163], v182 offset:18432
	ds_read_b128 v[172:175], v182 offset:19456
	ds_read_b128 v[176:179], v182 offset:20480
	ds_read_b128 v[196:199], v182 offset:21504
	ds_read_b128 v[200:203], v182 offset:22528
	ds_read_b128 v[204:207], v182 offset:23552
	global_load_lds_dwordx4 v[224:225], off
	v_lshl_add_u64 v[226:227], v[224:225], 0, s[0:1]
	s_mov_b32 m0, s25
	s_nop 0
	global_load_lds_dwordx4 v[226:227], off
	s_cmp_lg_u32 s15, -2
	s_cbranch_scc1 .Lzil_WOUT_2
	v_mov_b64_e32 v[16:17], 0
	v_mov_b64_e32 v[18:19], 0
	v_mov_b64_e32 v[20:21], 0
	v_mov_b64_e32 v[22:23], 0
	v_mov_b64_e32 v[32:33], 0
	v_mov_b64_e32 v[34:35], 0
	v_mov_b64_e32 v[36:37], 0
	v_mov_b64_e32 v[38:39], 0
	v_mov_b64_e32 v[48:49], 0
	v_mov_b64_e32 v[50:51], 0
	v_mov_b64_e32 v[52:53], 0
	v_mov_b64_e32 v[54:55], 0
	v_mov_b64_e32 v[64:65], 0
	v_mov_b64_e32 v[66:67], 0
	v_mov_b64_e32 v[68:69], 0
	v_mov_b64_e32 v[70:71], 0
.Lzil_WOUT_2:
	s_barrier
	s_waitcnt lgkmcnt(0)
	v_mfma_f32_16x16x32_bf16 v[68:71], v[136:139], v[152:155], v[68:71]
	v_mfma_f32_16x16x32_bf16 v[64:67], v[144:147], v[152:155], v[64:67]
	v_mfma_f32_16x16x32_bf16 v[52:55], v[136:139], v[160:163], v[52:55]
	v_mfma_f32_16x16x32_bf16 v[48:51], v[144:147], v[160:163], v[48:51]
	v_mfma_f32_16x16x32_bf16 v[36:39], v[136:139], v[176:179], v[36:39]
	v_mfma_f32_16x16x32_bf16 v[32:35], v[144:147], v[176:179], v[32:35]
	v_mfma_f32_16x16x32_bf16 v[20:23], v[136:139], v[200:203], v[20:23]
	v_mfma_f32_16x16x32_bf16 v[16:19], v[144:147], v[200:203], v[16:19]
	v_mfma_f32_16x16x32_bf16 v[68:71], v[140:143], v[156:159], v[68:71]
	v_mfma_f32_16x16x32_bf16 v[64:67], v[148:151], v[156:159], v[64:67]
	v_mfma_f32_16x16x32_bf16 v[52:55], v[140:143], v[172:175], v[52:55]
	v_mfma_f32_16x16x32_bf16 v[48:51], v[148:151], v[172:175], v[48:51]
	v_mfma_f32_16x16x32_bf16 v[36:39], v[140:143], v[196:199], v[36:39]
	v_mfma_f32_16x16x32_bf16 v[32:35], v[148:151], v[196:199], v[32:35]
	v_mfma_f32_16x16x32_bf16 v[20:23], v[140:143], v[204:207], v[20:23]
	v_mfma_f32_16x16x32_bf16 v[16:19], v[148:151], v[204:207], v[16:19]
	s_barrier
	s_add_i32 s4, s41, s23
	v_lshl_add_u64 v[136:137], v[184:185], 0, s[42:43]
	s_mov_b32 m0, s4
	s_nop 0
	global_load_lds_dwordx4 v[136:137], off
	v_lshl_add_u64 v[136:137], v[184:185], 0, s[50:51]
	s_add_i32 m0, s4, 0x2000
	s_nop 0
	global_load_lds_dwordx4 v[136:137], off
	s_cmp_lg_u32 s15, -2
	s_cbranch_scc1 .Lzil_WOUT_3
	v_mov_b64_e32 v[8:9], 0
	v_mov_b64_e32 v[10:11], 0
	v_mov_b64_e32 v[12:13], 0
	v_mov_b64_e32 v[14:15], 0
	v_mov_b64_e32 v[24:25], 0
	v_mov_b64_e32 v[26:27], 0
	v_mov_b64_e32 v[28:29], 0
	v_mov_b64_e32 v[30:31], 0
	v_mov_b64_e32 v[40:41], 0
	v_mov_b64_e32 v[42:43], 0
	v_mov_b64_e32 v[44:45], 0
	v_mov_b64_e32 v[46:47], 0
	v_mov_b64_e32 v[56:57], 0
	v_mov_b64_e32 v[58:59], 0
	v_mov_b64_e32 v[60:61], 0
	v_mov_b64_e32 v[62:63], 0
; #define G_STAGE(bufoff, gbase, o0, h64) do { \
;         __builtin_amdgcn_global_load_lds((const unsigned*)((const char*)(gbase) + (o0)), (LAS unsigned*)(lds + (bufoff) + ldsw), 16, 0, 0); \
;         __builtin_amdgcn_global_load_lds((const unsigned*)((const char*)(gbase) + (h64) + (o0)), (LAS unsigned*)(lds + (bufoff) + ldsw + 8192), 16, 0, 0); } while (0)
; #define G_LDA(dst, b, h) do { _Pragma("unroll") for (int m = 0; m < 4; ++m) _Pragma("unroll") for (int k = 0; k < 2; ++k) dst[m][k] = *(const LAS bf16x8*)(lds + G_SA(b, h) + aoff + m * 2048 + k * 1024); } while (0)
; #define G_LDB(dst, b, h) do { _Pragma("unroll") for (int n = 0; n < 2; ++n) _Pragma("unroll") for (int k = 0; k < 2; ++k) dst[n][k] = *(const LAS bf16x8*)(lds + G_SB(b, h) + boff + n * 2048 + k * 1024); } while (0)
; #define G_WAIT_V(n) asm volatile("s_waitcnt vmcnt(" #n ")" ::: "memory")
; #define G_WAIT_L(n) asm volatile("s_waitcnt lgkmcnt(" #n ")" ::: "memory")
; #define G_BAR __builtin_amdgcn_s_barrier()
; #define G_SCHED __builtin_amdgcn_sched_barrier(0)
;     ...
;             G_STAGE(G_SB(0, 1), b2 + chB, cB0, qB);
;             G_WAIT_V(6); G_BAR; G_MMA(1, 1, At, B1); G_BAR;
;             G_LDB(B0, 1, 0); G_SCHED; G_LDA(At, 1, 0); G_STAGE(G_SA(0, 1), a2 + chA, cA0, qA);
;             G_WAIT_L(8); G_BAR; G_WAIT_L(0); G_MMA(0, 0, At, B0); G_BAR; G_SCHED;
;             G_LDB(B1, 1, 1); G_STAGE(G_SB(1, 0), b3, cB0, qB);
;             G_BAR; G_WAIT_L(0); G_MMA(0, 1, At, B1); G_BAR;
;             G_LDA(At, 1, 1); G_STAGE(G_SA(1, 0), a3, cA0, qA);
.Lzil_WOUT_3:
	s_waitcnt vmcnt(6)
	s_barrier
	v_mfma_f32_16x16x32_bf16 v[60:63], v[208:211], v[152:155], v[60:63]
	v_mfma_f32_16x16x32_bf16 v[56:59], v[216:219], v[152:155], v[56:59]
	v_mfma_f32_16x16x32_bf16 v[44:47], v[208:211], v[160:163], v[44:47]
	v_mfma_f32_16x16x32_bf16 v[40:43], v[216:219], v[160:163], v[40:43]
	v_mfma_f32_16x16x32_bf16 v[28:31], v[208:211], v[176:179], v[28:31]
	v_mfma_f32_16x16x32_bf16 v[24:27], v[216:219], v[176:179], v[24:27]
	v_mfma_f32_16x16x32_bf16 v[12:15], v[208:211], v[200:203], v[12:15]
	v_mfma_f32_16x16x32_bf16 v[8:11], v[216:219], v[200:203], v[8:11]
	v_mfma_f32_16x16x32_bf16 v[60:63], v[212:215], v[156:159], v[60:63]
	v_mfma_f32_16x16x32_bf16 v[56:59], v[220:223], v[156:159], v[56:59]
	v_mfma_f32_16x16x32_bf16 v[44:47], v[212:215], v[172:175], v[44:47]
	v_mfma_f32_16x16x32_bf16 v[40:43], v[220:223], v[172:175], v[40:43]
	v_mfma_f32_16x16x32_bf16 v[28:31], v[212:215], v[196:199], v[28:31]
	v_mfma_f32_16x16x32_bf16 v[24:27], v[220:223], v[196:199], v[24:27]
	v_mfma_f32_16x16x32_bf16 v[12:15], v[212:215], v[204:207], v[12:15]
	v_mfma_f32_16x16x32_bf16 v[8:11], v[220:223], v[204:207], v[8:11]
	s_barrier
	s_add_i32 s4, 0, 0x18000
	v_add_u32_e32 v0, s4, v181
	ds_read_b128 v[136:139], v0
	ds_read_b128 v[140:143], v0 offset:1024
	ds_read_b128 v[144:147], v0 offset:2048
	ds_read_b128 v[148:151], v0 offset:3072
	s_mov_b32 m0, s26
	v_lshl_add_u64 v[208:209], v[224:225], 0, s[42:43]
	ds_read_b128 v[152:155], v182 offset:32768
	ds_read_b128 v[156:159], v182 offset:33792
	ds_read_b128 v[160:163], v182 offset:34816
	ds_read_b128 v[172:175], v182 offset:35840
	ds_read_b128 v[176:179], v182 offset:36864
	ds_read_b128 v[196:199], v182 offset:37888
	ds_read_b128 v[200:203], v182 offset:38912
	ds_read_b128 v[204:207], v182 offset:39936
	global_load_lds_dwordx4 v[208:209], off
	v_lshl_add_u64 v[208:209], v[224:225], 0, s[50:51]
	s_mov_b32 m0, s27
	s_nop 0
	global_load_lds_dwordx4 v[208:209], off
	s_waitcnt lgkmcnt(8)
	s_barrier
	s_waitcnt lgkmcnt(0)
	v_mfma_f32_16x16x32_bf16 v[132:135], v[136:139], v[152:155], v[132:135]
	v_mfma_f32_16x16x32_bf16 v[128:131], v[144:147], v[152:155], v[128:131]
	v_mfma_f32_16x16x32_bf16 v[116:119], v[136:139], v[160:163], v[116:119]
	v_mfma_f32_16x16x32_bf16 v[112:115], v[144:147], v[160:163], v[112:115]
	v_mfma_f32_16x16x32_bf16 v[100:103], v[136:139], v[176:179], v[100:103]
	v_mfma_f32_16x16x32_bf16 v[96:99], v[144:147], v[176:179], v[96:99]
	v_mfma_f32_16x16x32_bf16 v[84:87], v[136:139], v[200:203], v[84:87]
	v_mfma_f32_16x16x32_bf16 v[80:83], v[144:147], v[200:203], v[80:83]
	v_mfma_f32_16x16x32_bf16 v[132:135], v[140:143], v[156:159], v[132:135]
	v_mfma_f32_16x16x32_bf16 v[128:131], v[148:151], v[156:159], v[128:131]
	v_mfma_f32_16x16x32_bf16 v[116:119], v[140:143], v[172:175], v[116:119]
	v_mfma_f32_16x16x32_bf16 v[112:115], v[148:151], v[172:175], v[112:115]
	v_mfma_f32_16x16x32_bf16 v[100:103], v[140:143], v[196:199], v[100:103]
	v_mfma_f32_16x16x32_bf16 v[96:99], v[148:151], v[196:199], v[96:99]
	v_mfma_f32_16x16x32_bf16 v[84:87], v[140:143], v[204:207], v[84:87]
	v_mfma_f32_16x16x32_bf16 v[80:83], v[148:151], v[204:207], v[80:83]
	s_barrier
	s_add_i32 s5, 0, 0x1c000
	s_add_i32 s4, s4, s23
	v_add_u32_e32 v0, s5, v181
	v_lshl_add_u64 v[226:227], v[184:185], 0, s[46:47]
	s_mov_b32 m0, s4
	ds_read_b128 v[208:211], v0
	ds_read_b128 v[212:215], v0 offset:1024
	ds_read_b128 v[216:219], v0 offset:2048
	ds_read_b128 v[220:223], v0 offset:3072
	global_load_lds_dwordx4 v[226:227], off
	v_lshl_add_u64 v[226:227], v[184:185], 0, s[52:53]
	s_add_i32 m0, s4, 0x2000
	s_nop 0
	global_load_lds_dwordx4 v[226:227], off
	s_barrier
; #define G_STAGE(bufoff, gbase, o0, h64) do { \
;         __builtin_amdgcn_global_load_lds((const unsigned*)((const char*)(gbase) + (o0)), (LAS unsigned*)(lds + (bufoff) + ldsw), 16, 0, 0); \
;         __builtin_amdgcn_global_load_lds((const unsigned*)((const char*)(gbase) + (h64) + (o0)), (LAS unsigned*)(lds + (bufoff) + ldsw + 8192), 16, 0, 0); } while (0)
; #define G_LDA(dst, b, h) do { _Pragma("unroll") for (int m = 0; m < 4; ++m) _Pragma("unroll") for (int k = 0; k < 2; ++k) dst[m][k] = *(const LAS bf16x8*)(lds + G_SA(b, h) + aoff + m * 2048 + k * 1024); } while (0)
; #define G_WAIT_V(n) asm volatile("s_waitcnt vmcnt(" #n ")" ::: "memory")
; #define G_WAIT_L(n) asm volatile("s_waitcnt lgkmcnt(" #n ")" ::: "memory")
; #define G_BAR __builtin_amdgcn_s_barrier()
; #define G_SCHED __builtin_amdgcn_sched_barrier(0)
;     ...
;             G_LDA(At, 1, 1); G_STAGE(G_SA(1, 0), a3, cA0, qA);
;             G_BAR; G_WAIT_L(0); G_MMA(1, 0, At, B0); G_BAR; G_SCHED;
;             G_STAGE(G_SB(1, 1), b3 + chB, cB0, qB);
;             G_WAIT_V(6); G_BAR; G_MMA(1, 1, At, B1); G_BAR;
;         }
	s_waitcnt lgkmcnt(0)
	v_mfma_f32_16x16x32_bf16 v[124:127], v[208:211], v[152:155], v[124:127]
	v_mfma_f32_16x16x32_bf16 v[120:123], v[216:219], v[152:155], v[120:123]
	v_mfma_f32_16x16x32_bf16 v[108:111], v[208:211], v[160:163], v[108:111]
	v_mfma_f32_16x16x32_bf16 v[104:107], v[216:219], v[160:163], v[104:107]
	v_mfma_f32_16x16x32_bf16 v[92:95], v[208:211], v[176:179], v[92:95]
	v_mfma_f32_16x16x32_bf16 v[88:91], v[216:219], v[176:179], v[88:91]
	v_mfma_f32_16x16x32_bf16 v[76:79], v[208:211], v[200:203], v[76:79]
	v_mfma_f32_16x16x32_bf16 v[72:75], v[216:219], v[200:203], v[72:75]
	v_mfma_f32_16x16x32_bf16 v[124:127], v[212:215], v[156:159], v[124:127]
	v_mfma_f32_16x16x32_bf16 v[120:123], v[220:223], v[156:159], v[120:123]
	v_mfma_f32_16x16x32_bf16 v[108:111], v[212:215], v[172:175], v[108:111]
	v_mfma_f32_16x16x32_bf16 v[104:107], v[220:223], v[172:175], v[104:107]
	v_mfma_f32_16x16x32_bf16 v[92:95], v[212:215], v[196:199], v[92:95]
	v_mfma_f32_16x16x32_bf16 v[88:91], v[220:223], v[196:199], v[88:91]
	v_mfma_f32_16x16x32_bf16 v[76:79], v[212:215], v[204:207], v[76:79]
	v_mfma_f32_16x16x32_bf16 v[72:75], v[220:223], v[204:207], v[72:75]
	s_barrier
	s_mov_b32 m0, s29
	v_lshl_add_u64 v[226:227], v[224:225], 0, s[46:47]
	ds_read_b128 v[152:155], v182 offset:49152
	ds_read_b128 v[156:159], v182 offset:50176
	ds_read_b128 v[160:163], v182 offset:51200
	ds_read_b128 v[172:175], v182 offset:52224
	ds_read_b128 v[176:179], v182 offset:53248
	ds_read_b128 v[196:199], v182 offset:54272
	ds_read_b128 v[200:203], v182 offset:55296
	ds_read_b128 v[204:207], v182 offset:56320
	global_load_lds_dwordx4 v[226:227], off
	v_lshl_add_u64 v[224:225], v[224:225], 0, s[52:53]
	s_mov_b32 m0, s30
	s_nop 0
	global_load_lds_dwordx4 v[224:225], off
	s_barrier
	s_waitcnt lgkmcnt(0)
	v_mfma_f32_16x16x32_bf16 v[68:71], v[136:139], v[152:155], v[68:71]
	v_mfma_f32_16x16x32_bf16 v[64:67], v[144:147], v[152:155], v[64:67]
	v_mfma_f32_16x16x32_bf16 v[52:55], v[136:139], v[160:163], v[52:55]
	v_mfma_f32_16x16x32_bf16 v[48:51], v[144:147], v[160:163], v[48:51]
	v_mfma_f32_16x16x32_bf16 v[36:39], v[136:139], v[176:179], v[36:39]
	v_mfma_f32_16x16x32_bf16 v[32:35], v[144:147], v[176:179], v[32:35]
	v_mfma_f32_16x16x32_bf16 v[20:23], v[136:139], v[200:203], v[20:23]
	v_mfma_f32_16x16x32_bf16 v[16:19], v[144:147], v[200:203], v[16:19]
	v_mfma_f32_16x16x32_bf16 v[68:71], v[140:143], v[156:159], v[68:71]
	v_mfma_f32_16x16x32_bf16 v[64:67], v[148:151], v[156:159], v[64:67]
	v_mfma_f32_16x16x32_bf16 v[52:55], v[140:143], v[172:175], v[52:55]
	v_mfma_f32_16x16x32_bf16 v[48:51], v[148:151], v[172:175], v[48:51]
	v_mfma_f32_16x16x32_bf16 v[36:39], v[140:143], v[196:199], v[36:39]
	v_mfma_f32_16x16x32_bf16 v[32:35], v[148:151], v[196:199], v[32:35]
	v_mfma_f32_16x16x32_bf16 v[20:23], v[140:143], v[204:207], v[20:23]
	v_mfma_f32_16x16x32_bf16 v[16:19], v[148:151], v[204:207], v[16:19]
	s_barrier
	s_add_i32 s4, s5, s23
	v_lshl_add_u64 v[136:137], v[184:185], 0, s[54:55]
	s_mov_b32 m0, s4
	s_nop 0
	global_load_lds_dwordx4 v[136:137], off
	v_lshl_add_u64 v[136:137], v[184:185], 0, s[58:59]
	s_add_i32 m0, s4, 0x2000
	s_nop 0
	global_load_lds_dwordx4 v[136:137], off
	s_add_i32 s15, s15, 2
	s_add_u32 s2, s2, 0x100
	s_addc_u32 s3, s3, 0
	s_add_u32 s6, s6, 0x100
	s_addc_u32 s7, s7, 0
	s_cmp_gt_u32 s15, 13
	s_waitcnt vmcnt(6)
	s_barrier
	v_mfma_f32_16x16x32_bf16 v[60:63], v[208:211], v[152:155], v[60:63]
	v_mfma_f32_16x16x32_bf16 v[56:59], v[216:219], v[152:155], v[56:59]
	v_mfma_f32_16x16x32_bf16 v[44:47], v[208:211], v[160:163], v[44:47]
	v_mfma_f32_16x16x32_bf16 v[40:43], v[216:219], v[160:163], v[40:43]
	v_mfma_f32_16x16x32_bf16 v[28:31], v[208:211], v[176:179], v[28:31]
	v_mfma_f32_16x16x32_bf16 v[24:27], v[216:219], v[176:179], v[24:27]
	v_mfma_f32_16x16x32_bf16 v[12:15], v[208:211], v[200:203], v[12:15]
	v_mfma_f32_16x16x32_bf16 v[8:11], v[216:219], v[200:203], v[8:11]
	v_mfma_f32_16x16x32_bf16 v[60:63], v[212:215], v[156:159], v[60:63]
	v_mfma_f32_16x16x32_bf16 v[56:59], v[220:223], v[156:159], v[56:59]
	v_mfma_f32_16x16x32_bf16 v[44:47], v[212:215], v[172:175], v[44:47]
	v_mfma_f32_16x16x32_bf16 v[40:43], v[220:223], v[172:175], v[40:43]
	v_mfma_f32_16x16x32_bf16 v[28:31], v[212:215], v[196:199], v[28:31]
	v_mfma_f32_16x16x32_bf16 v[24:27], v[220:223], v[196:199], v[24:27]
	v_mfma_f32_16x16x32_bf16 v[12:15], v[212:215], v[204:207], v[12:15]
	v_mfma_f32_16x16x32_bf16 v[8:11], v[220:223], v[204:207], v[8:11]
	s_cbranch_scc0 .Ldb_WOUT_cont
	v_readfirstlane_b32 s101, v186
	s_cmpk_gt_u32 s101, 0xff
	s_cbranch_scc1 .Ldb_WOUT_young
	s_barrier
	s_mov_b32 s101, 1
	s_branch .Ldb_WOUT_exit

; #define G_STAGE(bufoff, gbase, o0, h64) do { \
;         __builtin_amdgcn_global_load_lds((const unsigned*)((const char*)(gbase) + (o0)), (LAS unsigned*)(lds + (bufoff) + ldsw), 16, 0, 0); \
;         __builtin_amdgcn_global_load_lds((const unsigned*)((const char*)(gbase) + (h64) + (o0)), (LAS unsigned*)(lds + (bufoff) + ldsw + 8192), 16, 0, 0); } while (0)
; #define G_LDA(dst, b, h) do { _Pragma("unroll") for (int m = 0; m < 4; ++m) _Pragma("unroll") for (int k = 0; k < 2; ++k) dst[m][k] = *(const LAS bf16x8*)(lds + G_SA(b, h) + aoff + m * 2048 + k * 1024); } while (0)
; #define G_LDB(dst, b, h) do { _Pragma("unroll") for (int n = 0; n < 2; ++n) _Pragma("unroll") for (int k = 0; k < 2; ++k) dst[n][k] = *(const LAS bf16x8*)(lds + G_SB(b, h) + boff + n * 2048 + k * 1024); } while (0)
; #define G_SCHED __builtin_amdgcn_sched_barrier(0)
;     ...
;         for (int t = 0; t < nt; t += 2) {
;             const bool last = (t == nt - 2);
;             const char* a1 = cA + (size_t)(t + 1) * ckA;
;             const char* a2 = last ? nA : cA + (size_t)(t + 2) * ckA; const char* b2 = last ? nB : cB + (size_t)(t + 2) * kB;
;             const char* a3 = a2 + ckA; const char* b3 = b2 + kB;
;             G_LDB(B0, 0, 0); G_SCHED; G_LDA(At, 0, 0); G_STAGE(G_SA(1, 1), a1 + chA, cA0, qA);
;     ...
;         if (!(cs.kind == K_MG_B && cur.aux < 2))
; #pragma unroll
;         for (int a = 0; a < 2; ++a)
; #pragma unroll
;             for (int b = 0; b < 2; ++b)
; #pragma unroll
;                 for (int m = 0; m < 4; ++m)
; #pragma unroll
;                     for (int n = 0; n < 2; ++n) acc[a][b][m][n] = (f32x4){0.f, 0.f, 0.f, 0.f};
;         cur = nxt; cA = nA; cB = nB; ++ui;
.LBB0_1119:
	s_add_u32 s2, s16, 0x40080
	s_addc_u32 s3, s17, 0
	s_add_u32 s16, s18, 0x100
	s_addc_u32 s17, s19, 0
	s_mov_b32 s18, -2
	s_mov_b64 s[42:43], 0x40000
	s_mov_b64 s[50:51], 0x60000
	s_mov_b64 s[52:53], 0x20080
	s_mov_b64 s[54:55], 0x40080
	s_mov_b64 s[58:59], 0x60080
	s_cmp_eq_u32 s101, 2
	s_cselect_b32 s101, 0, s101
.LBB0_1120:
	s_add_u32 s4, s2, 0xfffc0080
	s_addc_u32 s5, s3, -1
	s_add_i32 s19, 0, 0x10000
	v_add_u32_e32 v0, s19, v149
	ds_read_b128 v[140:143], v0
	ds_read_b128 v[144:147], v0 offset:1024
	ds_read_b128 v[152:155], v0 offset:2048
	ds_read_b128 v[156:159], v0 offset:3072
	s_cmp_eq_u32 s18, 12
	s_cselect_b32 s5, s13, s5
	s_cselect_b32 s4, s12, s4
	s_cselect_b32 s41, s15, s17
	s_cselect_b32 s40, s14, s16
	v_lshl_add_u64 v[184:185], s[2:3], 0, v[138:139]
	s_add_i32 m0, s26, 0xc000
	ds_read_b128 v[160:163], v150
	ds_read_b128 v[164:167], v150 offset:1024
	ds_read_b128 v[172:175], v150 offset:2048
	ds_read_b128 v[176:179], v150 offset:3072
	ds_read_b128 v[180:183], v150 offset:4096
	ds_read_b128 v[196:199], v150 offset:5120
	ds_read_b128 v[200:203], v150 offset:6144
	ds_read_b128 v[204:207], v150 offset:7168
	global_load_lds_dwordx4 v[184:185], off
	v_lshl_add_u64 v[184:185], v[184:185], 0, s[0:1]
	s_add_i32 m0, s26, 0xe000
	s_nop 0
	global_load_lds_dwordx4 v[184:185], off
	s_cmp_lg_u32 s18, -2
	s_cbranch_scc1 .Lzil_FFI_0
	v_mov_b64_e32 v[76:77], 0
	v_mov_b64_e32 v[78:79], 0
	v_mov_b64_e32 v[84:85], 0
	v_mov_b64_e32 v[86:87], 0
	v_mov_b64_e32 v[92:93], 0
	v_mov_b64_e32 v[94:95], 0
	v_mov_b64_e32 v[100:101], 0
	v_mov_b64_e32 v[102:103], 0
	v_mov_b64_e32 v[108:109], 0
	v_mov_b64_e32 v[110:111], 0
	v_mov_b64_e32 v[116:117], 0
	v_mov_b64_e32 v[118:119], 0
	v_mov_b64_e32 v[124:125], 0
	v_mov_b64_e32 v[126:127], 0
	v_mov_b64_e32 v[132:133], 0
	v_mov_b64_e32 v[134:135], 0

; #define G_STAGE(bufoff, gbase, o0, h64) do { \
;         __builtin_amdgcn_global_load_lds((const unsigned*)((const char*)(gbase) + (o0)), (LAS unsigned*)(lds + (bufoff) + ldsw), 16, 0, 0); \
;         __builtin_amdgcn_global_load_lds((const unsigned*)((const char*)(gbase) + (h64) + (o0)), (LAS unsigned*)(lds + (bufoff) + ldsw + 8192), 16, 0, 0); } while (0)
; #define G_LDA(dst, b, h) do { _Pragma("unroll") for (int m = 0; m < 4; ++m) _Pragma("unroll") for (int k = 0; k < 2; ++k) dst[m][k] = *(const LAS bf16x8*)(lds + G_SA(b, h) + aoff + m * 2048 + k * 1024); } while (0)
; #define G_LDB(dst, b, h) do { _Pragma("unroll") for (int n = 0; n < 2; ++n) _Pragma("unroll") for (int k = 0; k < 2; ++k) dst[n][k] = *(const LAS bf16x8*)(lds + G_SB(b, h) + boff + n * 2048 + k * 1024); } while (0)
; #define G_WAIT_L(n) asm volatile("s_waitcnt lgkmcnt(" #n ")" ::: "memory")
; #define G_BAR __builtin_amdgcn_s_barrier()
; #define G_SCHED __builtin_amdgcn_sched_barrier(0)
;     ...
;             G_LDB(B0, 0, 0); G_SCHED; G_LDA(At, 0, 0); G_STAGE(G_SA(1, 1), a1 + chA, cA0, qA);
;             G_WAIT_L(8); G_BAR; G_WAIT_L(0); G_MMA(0, 0, At, B0); G_BAR; G_SCHED;
;             G_LDB(B1, 0, 1); G_STAGE(G_SB(0, 0), b2, cB0, qB);
;             G_BAR; G_WAIT_L(0); G_MMA(0, 1, At, B1); G_BAR;
;             G_LDA(At, 0, 1); G_STAGE(G_SA(0, 0), a2, cA0, qA);
;             G_BAR; G_WAIT_L(0); G_MMA(1, 0, At, B0); G_BAR; G_SCHED;
;             G_STAGE(G_SB(0, 1), b2 + chB, cB0, qB);
;     ...
;         for (int a = 0; a < 2; ++a)
; #pragma unroll
;             for (int b = 0; b < 2; ++b)
; #pragma unroll
;                 for (int m = 0; m < 4; ++m)
; #pragma unroll
;                     for (int n = 0; n < 2; ++n) acc[a][b][m][n] = (f32x4){0.f, 0.f, 0.f, 0.f};
.Ldb_FFI_sk:
	s_mov_b32 s101, 0
	s_waitcnt lgkmcnt(0)
	v_mfma_f32_16x16x32_bf16 v[132:135], v[140:143], v[160:163], v[132:135]
	v_mfma_f32_16x16x32_bf16 v[124:127], v[152:155], v[160:163], v[124:127]
	v_mfma_f32_16x16x32_bf16 v[116:119], v[140:143], v[172:175], v[116:119]
	v_mfma_f32_16x16x32_bf16 v[108:111], v[152:155], v[172:175], v[108:111]
	v_mfma_f32_16x16x32_bf16 v[100:103], v[140:143], v[180:183], v[100:103]
	v_mfma_f32_16x16x32_bf16 v[92:95], v[152:155], v[180:183], v[92:95]
	v_mfma_f32_16x16x32_bf16 v[84:87], v[140:143], v[200:203], v[84:87]
	v_mfma_f32_16x16x32_bf16 v[76:79], v[152:155], v[200:203], v[76:79]
	v_mfma_f32_16x16x32_bf16 v[132:135], v[144:147], v[164:167], v[132:135]
	v_mfma_f32_16x16x32_bf16 v[124:127], v[156:159], v[164:167], v[124:127]
	v_mfma_f32_16x16x32_bf16 v[116:119], v[144:147], v[176:179], v[116:119]
	v_mfma_f32_16x16x32_bf16 v[108:111], v[156:159], v[176:179], v[108:111]
	v_mfma_f32_16x16x32_bf16 v[100:103], v[144:147], v[196:199], v[100:103]
	v_mfma_f32_16x16x32_bf16 v[92:95], v[156:159], v[196:199], v[92:95]
	v_mfma_f32_16x16x32_bf16 v[84:87], v[144:147], v[204:207], v[84:87]
	v_mfma_f32_16x16x32_bf16 v[76:79], v[156:159], v[204:207], v[76:79]
	s_barrier
	s_add_i32 s39, 0, 0x14000
	s_add_i32 s19, s19, s21
	v_add_u32_e32 v0, s39, v149
	v_lshl_add_u64 v[184:185], s[40:41], 0, v[2:3]
	s_mov_b32 m0, s19
	ds_read_b128 v[208:211], v0
	ds_read_b128 v[212:215], v0 offset:1024
	ds_read_b128 v[216:219], v0 offset:2048
	ds_read_b128 v[220:223], v0 offset:3072
	global_load_lds_dwordx4 v[184:185], off
	v_lshl_add_u64 v[224:225], v[184:185], 0, s[0:1]
	s_add_i32 m0, s19, 0x2000
	s_nop 0
	global_load_lds_dwordx4 v[224:225], off
	s_cmp_lg_u32 s18, -2
	s_cbranch_scc1 .Lzil_FFI_1
	v_mov_b64_e32 v[72:73], 0
	v_mov_b64_e32 v[74:75], 0
	v_mov_b64_e32 v[80:81], 0
	v_mov_b64_e32 v[82:83], 0
	v_mov_b64_e32 v[88:89], 0
	v_mov_b64_e32 v[90:91], 0
	v_mov_b64_e32 v[96:97], 0
	v_mov_b64_e32 v[98:99], 0
	v_mov_b64_e32 v[104:105], 0
	v_mov_b64_e32 v[106:107], 0
	v_mov_b64_e32 v[112:113], 0
	v_mov_b64_e32 v[114:115], 0
	v_mov_b64_e32 v[120:121], 0
	v_mov_b64_e32 v[122:123], 0
	v_mov_b64_e32 v[128:129], 0
	v_mov_b64_e32 v[130:131], 0
.Lzil_FFI_1:
	s_barrier
	s_waitcnt lgkmcnt(0)
	v_mfma_f32_16x16x32_bf16 v[128:131], v[208:211], v[160:163], v[128:131]
	v_mfma_f32_16x16x32_bf16 v[120:123], v[216:219], v[160:163], v[120:123]
	v_mfma_f32_16x16x32_bf16 v[112:115], v[208:211], v[172:175], v[112:115]
	v_mfma_f32_16x16x32_bf16 v[104:107], v[216:219], v[172:175], v[104:107]
	v_mfma_f32_16x16x32_bf16 v[96:99], v[208:211], v[180:183], v[96:99]
	v_mfma_f32_16x16x32_bf16 v[88:91], v[216:219], v[180:183], v[88:91]
	v_mfma_f32_16x16x32_bf16 v[80:83], v[208:211], v[200:203], v[80:83]
	v_mfma_f32_16x16x32_bf16 v[72:75], v[216:219], v[200:203], v[72:75]
	v_mfma_f32_16x16x32_bf16 v[128:131], v[212:215], v[164:167], v[128:131]
	v_mfma_f32_16x16x32_bf16 v[120:123], v[220:223], v[164:167], v[120:123]
	v_mfma_f32_16x16x32_bf16 v[112:115], v[212:215], v[176:179], v[112:115]
	v_mfma_f32_16x16x32_bf16 v[104:107], v[220:223], v[176:179], v[104:107]
	v_mfma_f32_16x16x32_bf16 v[96:99], v[212:215], v[196:199], v[96:99]
	v_mfma_f32_16x16x32_bf16 v[88:91], v[220:223], v[196:199], v[88:91]
	v_mfma_f32_16x16x32_bf16 v[80:83], v[212:215], v[204:207], v[80:83]
	v_mfma_f32_16x16x32_bf16 v[72:75], v[220:223], v[204:207], v[72:75]
	s_barrier
	s_mov_b32 m0, s26
	v_lshl_add_u64 v[224:225], s[4:5], 0, v[136:137]
	ds_read_b128 v[160:163], v150 offset:16384
	ds_read_b128 v[164:167], v150 offset:17408
	ds_read_b128 v[172:175], v150 offset:18432
	ds_read_b128 v[176:179], v150 offset:19456
	ds_read_b128 v[180:183], v150 offset:20480
	ds_read_b128 v[196:199], v150 offset:21504
	ds_read_b128 v[200:203], v150 offset:22528
	ds_read_b128 v[204:207], v150 offset:23552
	global_load_lds_dwordx4 v[224:225], off
	v_lshl_add_u64 v[226:227], v[224:225], 0, s[0:1]
	s_mov_b32 m0, s27
	s_nop 0
	global_load_lds_dwordx4 v[226:227], off
	s_cmp_lg_u32 s18, -2
	s_cbranch_scc1 .Lzil_FFI_2
	v_mov_b64_e32 v[12:13], 0
	v_mov_b64_e32 v[14:15], 0
	v_mov_b64_e32 v[20:21], 0
	v_mov_b64_e32 v[22:23], 0
	v_mov_b64_e32 v[28:29], 0
	v_mov_b64_e32 v[30:31], 0
	v_mov_b64_e32 v[36:37], 0
	v_mov_b64_e32 v[38:39], 0
	v_mov_b64_e32 v[44:45], 0
	v_mov_b64_e32 v[46:47], 0
	v_mov_b64_e32 v[52:53], 0
	v_mov_b64_e32 v[54:55], 0
	v_mov_b64_e32 v[60:61], 0
	v_mov_b64_e32 v[62:63], 0
	v_mov_b64_e32 v[68:69], 0
	v_mov_b64_e32 v[70:71], 0
.Lzil_FFI_2:
	s_barrier
	s_waitcnt lgkmcnt(0)
	v_mfma_f32_16x16x32_bf16 v[68:71], v[140:143], v[160:163], v[68:71]
	v_mfma_f32_16x16x32_bf16 v[60:63], v[152:155], v[160:163], v[60:63]
	v_mfma_f32_16x16x32_bf16 v[52:55], v[140:143], v[172:175], v[52:55]
	v_mfma_f32_16x16x32_bf16 v[44:47], v[152:155], v[172:175], v[44:47]
	v_mfma_f32_16x16x32_bf16 v[36:39], v[140:143], v[180:183], v[36:39]
	v_mfma_f32_16x16x32_bf16 v[28:31], v[152:155], v[180:183], v[28:31]
	v_mfma_f32_16x16x32_bf16 v[20:23], v[140:143], v[200:203], v[20:23]
	v_mfma_f32_16x16x32_bf16 v[12:15], v[152:155], v[200:203], v[12:15]
	v_mfma_f32_16x16x32_bf16 v[68:71], v[144:147], v[164:167], v[68:71]
	v_mfma_f32_16x16x32_bf16 v[60:63], v[156:159], v[164:167], v[60:63]
	v_mfma_f32_16x16x32_bf16 v[52:55], v[144:147], v[176:179], v[52:55]
	v_mfma_f32_16x16x32_bf16 v[44:47], v[156:159], v[176:179], v[44:47]
	v_mfma_f32_16x16x32_bf16 v[36:39], v[144:147], v[196:199], v[36:39]
	v_mfma_f32_16x16x32_bf16 v[28:31], v[156:159], v[196:199], v[28:31]
	v_mfma_f32_16x16x32_bf16 v[20:23], v[144:147], v[204:207], v[20:23]
	v_mfma_f32_16x16x32_bf16 v[12:15], v[156:159], v[204:207], v[12:15]
	s_barrier
	s_add_i32 s4, s39, s21
	v_lshl_add_u64 v[140:141], v[184:185], 0, s[42:43]
	s_mov_b32 m0, s4
	s_nop 0
	global_load_lds_dwordx4 v[140:141], off
	v_lshl_add_u64 v[140:141], v[184:185], 0, s[50:51]
	s_add_i32 m0, s4, 0x2000
	s_nop 0
	global_load_lds_dwordx4 v[140:141], off
	s_cmp_lg_u32 s18, -2
	s_cbranch_scc1 .Lzil_FFI_3
	v_mov_b64_e32 v[8:9], 0
	v_mov_b64_e32 v[10:11], 0
	v_mov_b64_e32 v[16:17], 0
	v_mov_b64_e32 v[18:19], 0
	v_mov_b64_e32 v[24:25], 0
	v_mov_b64_e32 v[26:27], 0
	v_mov_b64_e32 v[32:33], 0
	v_mov_b64_e32 v[34:35], 0
	v_mov_b64_e32 v[40:41], 0
	v_mov_b64_e32 v[42:43], 0
	v_mov_b64_e32 v[48:49], 0
	v_mov_b64_e32 v[50:51], 0
	v_mov_b64_e32 v[56:57], 0
	v_mov_b64_e32 v[58:59], 0
	v_mov_b64_e32 v[64:65], 0
	v_mov_b64_e32 v[66:67], 0
; #define G_STAGE(bufoff, gbase, o0, h64) do { \
;         __builtin_amdgcn_global_load_lds((const unsigned*)((const char*)(gbase) + (o0)), (LAS unsigned*)(lds + (bufoff) + ldsw), 16, 0, 0); \
;         __builtin_amdgcn_global_load_lds((const unsigned*)((const char*)(gbase) + (h64) + (o0)), (LAS unsigned*)(lds + (bufoff) + ldsw + 8192), 16, 0, 0); } while (0)
; #define G_LDA(dst, b, h) do { _Pragma("unroll") for (int m = 0; m < 4; ++m) _Pragma("unroll") for (int k = 0; k < 2; ++k) dst[m][k] = *(const LAS bf16x8*)(lds + G_SA(b, h) + aoff + m * 2048 + k * 1024); } while (0)
; #define G_LDB(dst, b, h) do { _Pragma("unroll") for (int n = 0; n < 2; ++n) _Pragma("unroll") for (int k = 0; k < 2; ++k) dst[n][k] = *(const LAS bf16x8*)(lds + G_SB(b, h) + boff + n * 2048 + k * 1024); } while (0)
; #define G_WAIT_V(n) asm volatile("s_waitcnt vmcnt(" #n ")" ::: "memory")
; #define G_WAIT_L(n) asm volatile("s_waitcnt lgkmcnt(" #n ")" ::: "memory")
; #define G_BAR __builtin_amdgcn_s_barrier()
; #define G_SCHED __builtin_amdgcn_sched_barrier(0)
;     ...
;             G_STAGE(G_SB(0, 1), b2 + chB, cB0, qB);
;             G_WAIT_V(6); G_BAR; G_MMA(1, 1, At, B1); G_BAR;
;             G_LDB(B0, 1, 0); G_SCHED; G_LDA(At, 1, 0); G_STAGE(G_SA(0, 1), a2 + chA, cA0, qA);
;             G_WAIT_L(8); G_BAR; G_WAIT_L(0); G_MMA(0, 0, At, B0); G_BAR; G_SCHED;
;             G_LDB(B1, 1, 1); G_STAGE(G_SB(1, 0), b3, cB0, qB);
;             G_BAR; G_WAIT_L(0); G_MMA(0, 1, At, B1); G_BAR;
;             G_LDA(At, 1, 1); G_STAGE(G_SA(1, 0), a3, cA0, qA);
.Lzil_FFI_3:
	s_waitcnt vmcnt(6)
	s_barrier
	v_mfma_f32_16x16x32_bf16 v[64:67], v[208:211], v[160:163], v[64:67]
	v_mfma_f32_16x16x32_bf16 v[56:59], v[216:219], v[160:163], v[56:59]
	v_mfma_f32_16x16x32_bf16 v[48:51], v[208:211], v[172:175], v[48:51]
	v_mfma_f32_16x16x32_bf16 v[40:43], v[216:219], v[172:175], v[40:43]
	v_mfma_f32_16x16x32_bf16 v[32:35], v[208:211], v[180:183], v[32:35]
	v_mfma_f32_16x16x32_bf16 v[24:27], v[216:219], v[180:183], v[24:27]
	v_mfma_f32_16x16x32_bf16 v[16:19], v[208:211], v[200:203], v[16:19]
	v_mfma_f32_16x16x32_bf16 v[8:11], v[216:219], v[200:203], v[8:11]
	v_mfma_f32_16x16x32_bf16 v[64:67], v[212:215], v[164:167], v[64:67]
	v_mfma_f32_16x16x32_bf16 v[56:59], v[220:223], v[164:167], v[56:59]
	v_mfma_f32_16x16x32_bf16 v[48:51], v[212:215], v[176:179], v[48:51]
	v_mfma_f32_16x16x32_bf16 v[40:43], v[220:223], v[176:179], v[40:43]
	v_mfma_f32_16x16x32_bf16 v[32:35], v[212:215], v[196:199], v[32:35]
	v_mfma_f32_16x16x32_bf16 v[24:27], v[220:223], v[196:199], v[24:27]
	v_mfma_f32_16x16x32_bf16 v[16:19], v[212:215], v[204:207], v[16:19]
	v_mfma_f32_16x16x32_bf16 v[8:11], v[220:223], v[204:207], v[8:11]
	s_barrier
	s_add_i32 s4, 0, 0x18000
	v_add_u32_e32 v0, s4, v149
	ds_read_b128 v[140:143], v0
	ds_read_b128 v[144:147], v0 offset:1024
	ds_read_b128 v[152:155], v0 offset:2048
	ds_read_b128 v[156:159], v0 offset:3072
	s_mov_b32 m0, s29
	v_lshl_add_u64 v[208:209], v[224:225], 0, s[42:43]
	ds_read_b128 v[160:163], v150 offset:32768
	ds_read_b128 v[164:167], v150 offset:33792
	ds_read_b128 v[172:175], v150 offset:34816
	ds_read_b128 v[176:179], v150 offset:35840
	ds_read_b128 v[180:183], v150 offset:36864
	ds_read_b128 v[196:199], v150 offset:37888
	ds_read_b128 v[200:203], v150 offset:38912
	ds_read_b128 v[204:207], v150 offset:39936
	global_load_lds_dwordx4 v[208:209], off
	v_lshl_add_u64 v[208:209], v[224:225], 0, s[50:51]
	s_mov_b32 m0, s30
	s_nop 0
	global_load_lds_dwordx4 v[208:209], off
	s_waitcnt lgkmcnt(8)
	s_barrier
	s_waitcnt lgkmcnt(0)
	v_mfma_f32_16x16x32_bf16 v[132:135], v[140:143], v[160:163], v[132:135]
	v_mfma_f32_16x16x32_bf16 v[124:127], v[152:155], v[160:163], v[124:127]
	v_mfma_f32_16x16x32_bf16 v[116:119], v[140:143], v[172:175], v[116:119]
	v_mfma_f32_16x16x32_bf16 v[108:111], v[152:155], v[172:175], v[108:111]
	v_mfma_f32_16x16x32_bf16 v[100:103], v[140:143], v[180:183], v[100:103]
	v_mfma_f32_16x16x32_bf16 v[92:95], v[152:155], v[180:183], v[92:95]
	v_mfma_f32_16x16x32_bf16 v[84:87], v[140:143], v[200:203], v[84:87]
	v_mfma_f32_16x16x32_bf16 v[76:79], v[152:155], v[200:203], v[76:79]
	v_mfma_f32_16x16x32_bf16 v[132:135], v[144:147], v[164:167], v[132:135]
	v_mfma_f32_16x16x32_bf16 v[124:127], v[156:159], v[164:167], v[124:127]
	v_mfma_f32_16x16x32_bf16 v[116:119], v[144:147], v[176:179], v[116:119]
	v_mfma_f32_16x16x32_bf16 v[108:111], v[156:159], v[176:179], v[108:111]
	v_mfma_f32_16x16x32_bf16 v[100:103], v[144:147], v[196:199], v[100:103]
	v_mfma_f32_16x16x32_bf16 v[92:95], v[156:159], v[196:199], v[92:95]
	v_mfma_f32_16x16x32_bf16 v[84:87], v[144:147], v[204:207], v[84:87]
	v_mfma_f32_16x16x32_bf16 v[76:79], v[156:159], v[204:207], v[76:79]
	s_barrier
	s_add_i32 s5, 0, 0x1c000
	s_add_i32 s4, s4, s21
	v_add_u32_e32 v0, s5, v149
	v_lshl_add_u64 v[226:227], v[184:185], 0, s[46:47]
	s_mov_b32 m0, s4
	ds_read_b128 v[208:211], v0
	ds_read_b128 v[212:215], v0 offset:1024
	ds_read_b128 v[216:219], v0 offset:2048
	ds_read_b128 v[220:223], v0 offset:3072
	global_load_lds_dwordx4 v[226:227], off
	v_lshl_add_u64 v[226:227], v[184:185], 0, s[52:53]
	s_add_i32 m0, s4, 0x2000
	s_nop 0
	global_load_lds_dwordx4 v[226:227], off
	s_barrier
; #define G_STAGE(bufoff, gbase, o0, h64) do { \
;         __builtin_amdgcn_global_load_lds((const unsigned*)((const char*)(gbase) + (o0)), (LAS unsigned*)(lds + (bufoff) + ldsw), 16, 0, 0); \
;         __builtin_amdgcn_global_load_lds((const unsigned*)((const char*)(gbase) + (h64) + (o0)), (LAS unsigned*)(lds + (bufoff) + ldsw + 8192), 16, 0, 0); } while (0)
; #define G_LDA(dst, b, h) do { _Pragma("unroll") for (int m = 0; m < 4; ++m) _Pragma("unroll") for (int k = 0; k < 2; ++k) dst[m][k] = *(const LAS bf16x8*)(lds + G_SA(b, h) + aoff + m * 2048 + k * 1024); } while (0)
; #define G_WAIT_V(n) asm volatile("s_waitcnt vmcnt(" #n ")" ::: "memory")
; #define G_WAIT_L(n) asm volatile("s_waitcnt lgkmcnt(" #n ")" ::: "memory")
; #define G_BAR __builtin_amdgcn_s_barrier()
; #define G_SCHED __builtin_amdgcn_sched_barrier(0)
;     ...
;             G_LDA(At, 1, 1); G_STAGE(G_SA(1, 0), a3, cA0, qA);
;             G_BAR; G_WAIT_L(0); G_MMA(1, 0, At, B0); G_BAR; G_SCHED;
;             G_STAGE(G_SB(1, 1), b3 + chB, cB0, qB);
;             G_WAIT_V(6); G_BAR; G_MMA(1, 1, At, B1); G_BAR;
;         }
	s_waitcnt lgkmcnt(0)
	v_mfma_f32_16x16x32_bf16 v[128:131], v[208:211], v[160:163], v[128:131]
	v_mfma_f32_16x16x32_bf16 v[120:123], v[216:219], v[160:163], v[120:123]
	v_mfma_f32_16x16x32_bf16 v[112:115], v[208:211], v[172:175], v[112:115]
	v_mfma_f32_16x16x32_bf16 v[104:107], v[216:219], v[172:175], v[104:107]
	v_mfma_f32_16x16x32_bf16 v[96:99], v[208:211], v[180:183], v[96:99]
	v_mfma_f32_16x16x32_bf16 v[88:91], v[216:219], v[180:183], v[88:91]
	v_mfma_f32_16x16x32_bf16 v[80:83], v[208:211], v[200:203], v[80:83]
	v_mfma_f32_16x16x32_bf16 v[72:75], v[216:219], v[200:203], v[72:75]
	v_mfma_f32_16x16x32_bf16 v[128:131], v[212:215], v[164:167], v[128:131]
	v_mfma_f32_16x16x32_bf16 v[120:123], v[220:223], v[164:167], v[120:123]
	v_mfma_f32_16x16x32_bf16 v[112:115], v[212:215], v[176:179], v[112:115]
	v_mfma_f32_16x16x32_bf16 v[104:107], v[220:223], v[176:179], v[104:107]
	v_mfma_f32_16x16x32_bf16 v[96:99], v[212:215], v[196:199], v[96:99]
	v_mfma_f32_16x16x32_bf16 v[88:91], v[220:223], v[196:199], v[88:91]
	v_mfma_f32_16x16x32_bf16 v[80:83], v[212:215], v[204:207], v[80:83]
	v_mfma_f32_16x16x32_bf16 v[72:75], v[220:223], v[204:207], v[72:75]
	s_barrier
	s_mov_b32 m0, s31
	v_lshl_add_u64 v[226:227], v[224:225], 0, s[46:47]
	ds_read_b128 v[160:163], v150 offset:49152
	ds_read_b128 v[164:167], v150 offset:50176
	ds_read_b128 v[172:175], v150 offset:51200
	ds_read_b128 v[176:179], v150 offset:52224
	ds_read_b128 v[180:183], v150 offset:53248
	ds_read_b128 v[196:199], v150 offset:54272
	ds_read_b128 v[200:203], v150 offset:55296
	ds_read_b128 v[204:207], v150 offset:56320
	global_load_lds_dwordx4 v[226:227], off
	v_lshl_add_u64 v[224:225], v[224:225], 0, s[52:53]
	s_mov_b32 m0, s34
	s_nop 0
	global_load_lds_dwordx4 v[224:225], off
	s_barrier
	s_waitcnt lgkmcnt(0)
	v_mfma_f32_16x16x32_bf16 v[68:71], v[140:143], v[160:163], v[68:71]
	v_mfma_f32_16x16x32_bf16 v[60:63], v[152:155], v[160:163], v[60:63]
	v_mfma_f32_16x16x32_bf16 v[52:55], v[140:143], v[172:175], v[52:55]
	v_mfma_f32_16x16x32_bf16 v[44:47], v[152:155], v[172:175], v[44:47]
	v_mfma_f32_16x16x32_bf16 v[36:39], v[140:143], v[180:183], v[36:39]
	v_mfma_f32_16x16x32_bf16 v[28:31], v[152:155], v[180:183], v[28:31]
	v_mfma_f32_16x16x32_bf16 v[20:23], v[140:143], v[200:203], v[20:23]
	v_mfma_f32_16x16x32_bf16 v[12:15], v[152:155], v[200:203], v[12:15]
	v_mfma_f32_16x16x32_bf16 v[68:71], v[144:147], v[164:167], v[68:71]
	v_mfma_f32_16x16x32_bf16 v[60:63], v[156:159], v[164:167], v[60:63]
	v_mfma_f32_16x16x32_bf16 v[52:55], v[144:147], v[176:179], v[52:55]
	v_mfma_f32_16x16x32_bf16 v[44:47], v[156:159], v[176:179], v[44:47]
	v_mfma_f32_16x16x32_bf16 v[36:39], v[144:147], v[196:199], v[36:39]
	v_mfma_f32_16x16x32_bf16 v[28:31], v[156:159], v[196:199], v[28:31]
	v_mfma_f32_16x16x32_bf16 v[20:23], v[144:147], v[204:207], v[20:23]
	v_mfma_f32_16x16x32_bf16 v[12:15], v[156:159], v[204:207], v[12:15]
	s_barrier
	s_add_i32 s4, s5, s21
	v_lshl_add_u64 v[140:141], v[184:185], 0, s[54:55]
	s_mov_b32 m0, s4
	s_nop 0
	global_load_lds_dwordx4 v[140:141], off
	v_lshl_add_u64 v[140:141], v[184:185], 0, s[58:59]
	s_add_i32 m0, s4, 0x2000
	s_nop 0
	global_load_lds_dwordx4 v[140:141], off
	s_add_i32 s18, s18, 2
	s_add_u32 s2, s2, 0x100
	s_addc_u32 s3, s3, 0
	s_add_u32 s16, s16, 0x100
	s_addc_u32 s17, s17, 0
	s_cmp_gt_u32 s18, 13
	s_waitcnt vmcnt(6)
	s_barrier
	v_mfma_f32_16x16x32_bf16 v[64:67], v[208:211], v[160:163], v[64:67]
	v_mfma_f32_16x16x32_bf16 v[56:59], v[216:219], v[160:163], v[56:59]
	v_mfma_f32_16x16x32_bf16 v[48:51], v[208:211], v[172:175], v[48:51]
	v_mfma_f32_16x16x32_bf16 v[40:43], v[216:219], v[172:175], v[40:43]
	v_mfma_f32_16x16x32_bf16 v[32:35], v[208:211], v[180:183], v[32:35]
	v_mfma_f32_16x16x32_bf16 v[24:27], v[216:219], v[180:183], v[24:27]
	v_mfma_f32_16x16x32_bf16 v[16:19], v[208:211], v[200:203], v[16:19]
	v_mfma_f32_16x16x32_bf16 v[8:11], v[216:219], v[200:203], v[8:11]
	v_mfma_f32_16x16x32_bf16 v[64:67], v[212:215], v[164:167], v[64:67]
	v_mfma_f32_16x16x32_bf16 v[56:59], v[220:223], v[164:167], v[56:59]
	v_mfma_f32_16x16x32_bf16 v[48:51], v[212:215], v[176:179], v[48:51]
	v_mfma_f32_16x16x32_bf16 v[40:43], v[220:223], v[176:179], v[40:43]
	v_mfma_f32_16x16x32_bf16 v[32:35], v[212:215], v[196:199], v[32:35]
	v_mfma_f32_16x16x32_bf16 v[24:27], v[220:223], v[196:199], v[24:27]
	v_mfma_f32_16x16x32_bf16 v[16:19], v[212:215], v[204:207], v[16:19]
	v_mfma_f32_16x16x32_bf16 v[8:11], v[220:223], v[204:207], v[8:11]
	s_cbranch_scc0 .Ldb_FFI_cont
	v_readfirstlane_b32 s101, v186
	s_cmpk_gt_u32 s101, 0xff
	s_cbranch_scc1 .Ldb_FFI_young
	s_barrier
	s_mov_b32 s101, 1
	s_branch .Ldb_FFI_exit

; #define G_STAGE(bufoff, gbase, o0, h64) do { \
;         __builtin_amdgcn_global_load_lds((const unsigned*)((const char*)(gbase) + (o0)), (LAS unsigned*)(lds + (bufoff) + ldsw), 16, 0, 0); \
;         __builtin_amdgcn_global_load_lds((const unsigned*)((const char*)(gbase) + (h64) + (o0)), (LAS unsigned*)(lds + (bufoff) + ldsw + 8192), 16, 0, 0); } while (0)
; #define G_LDA(dst, b, h) do { _Pragma("unroll") for (int m = 0; m < 4; ++m) _Pragma("unroll") for (int k = 0; k < 2; ++k) dst[m][k] = *(const LAS bf16x8*)(lds + G_SA(b, h) + aoff + m * 2048 + k * 1024); } while (0)
; #define G_LDB(dst, b, h) do { _Pragma("unroll") for (int n = 0; n < 2; ++n) _Pragma("unroll") for (int k = 0; k < 2; ++k) dst[n][k] = *(const LAS bf16x8*)(lds + G_SB(b, h) + boff + n * 2048 + k * 1024); } while (0)
; #define G_SCHED __builtin_amdgcn_sched_barrier(0)
;     ...
;         for (int t = 0; t < nt; t += 2) {
;             const bool last = (t == nt - 2);
;             const char* a1 = cA + (size_t)(t + 1) * ckA;
;             const char* a2 = last ? nA : cA + (size_t)(t + 2) * ckA; const char* b2 = last ? nB : cB + (size_t)(t + 2) * kB;
;             const char* a3 = a2 + ckA; const char* b3 = b2 + kB;
;             G_LDB(B0, 0, 0); G_SCHED; G_LDA(At, 0, 0); G_STAGE(G_SA(1, 1), a1 + chA, cA0, qA);
;     ...
;         if (!(cs.kind == K_MG_B && cur.aux < 2))
; #pragma unroll
;         for (int a = 0; a < 2; ++a)
; #pragma unroll
;             for (int b = 0; b < 2; ++b)
; #pragma unroll
;                 for (int m = 0; m < 4; ++m)
; #pragma unroll
;                     for (int n = 0; n < 2; ++n) acc[a][b][m][n] = (f32x4){0.f, 0.f, 0.f, 0.f};
;         cur = nxt; cA = nA; cB = nB; ++ui;
.LBB0_1184:
	s_add_u32 s2, s2, 0xb0080
	s_addc_u32 s3, s3, 0
	s_add_u32 s6, s6, 0x100
	s_waitcnt lgkmcnt(0)
	s_addc_u32 s7, s7, 0
	s_mov_b32 s21, -2
	s_mov_b64 s[52:53], 0xb0080
	s_mov_b64 s[54:55], 0x108080
	s_cmp_eq_u32 s101, 2
	s_cselect_b32 s101, 0, s101
.LBB0_1185:
	s_add_u32 s4, s2, 0xfff50080
	s_addc_u32 s5, s3, -1
	s_add_i32 s33, 0, 0x10000
	v_add_u32_e32 v0, s33, v185
	ds_read_b128 v[136:139], v0
	ds_read_b128 v[140:143], v0 offset:1024
	ds_read_b128 v[144:147], v0 offset:2048
	ds_read_b128 v[148:151], v0 offset:3072
	s_cmp_eq_u32 s21, 40
	s_cselect_b32 s5, s17, s5
	s_cselect_b32 s4, s16, s4
	s_cselect_b32 s23, s19, s7
	s_cselect_b32 s22, s18, s6
	v_lshl_add_u64 v[204:205], s[2:3], 0, v[174:175]
	s_add_i32 m0, s26, 0xc000
	ds_read_b128 v[152:155], v195
	ds_read_b128 v[156:159], v195 offset:1024
	ds_read_b128 v[160:163], v195 offset:2048
	ds_read_b128 v[164:167], v195 offset:3072
	ds_read_b128 v[176:179], v195 offset:4096
	ds_read_b128 v[180:183], v195 offset:5120
	ds_read_b128 v[196:199], v195 offset:6144
	ds_read_b128 v[200:203], v195 offset:7168
	global_load_lds_dwordx4 v[204:205], off
	v_lshl_add_u64 v[204:205], v[204:205], 0, s[86:87]
	s_add_i32 m0, s26, 0xe000
	s_nop 0
	global_load_lds_dwordx4 v[204:205], off
	s_cmp_lg_u32 s21, -2
	s_cbranch_scc1 .Lzil_FFO_0
	v_mov_b64_e32 v[80:81], 0
	v_mov_b64_e32 v[82:83], 0
	v_mov_b64_e32 v[84:85], 0
	v_mov_b64_e32 v[86:87], 0
	v_mov_b64_e32 v[96:97], 0
	v_mov_b64_e32 v[98:99], 0
	v_mov_b64_e32 v[100:101], 0
	v_mov_b64_e32 v[102:103], 0
	v_mov_b64_e32 v[112:113], 0
	v_mov_b64_e32 v[114:115], 0
	v_mov_b64_e32 v[116:117], 0
	v_mov_b64_e32 v[118:119], 0
	v_mov_b64_e32 v[128:129], 0
	v_mov_b64_e32 v[130:131], 0
	v_mov_b64_e32 v[132:133], 0
	v_mov_b64_e32 v[134:135], 0

; #define G_STAGE(bufoff, gbase, o0, h64) do { \
;         __builtin_amdgcn_global_load_lds((const unsigned*)((const char*)(gbase) + (o0)), (LAS unsigned*)(lds + (bufoff) + ldsw), 16, 0, 0); \
;         __builtin_amdgcn_global_load_lds((const unsigned*)((const char*)(gbase) + (h64) + (o0)), (LAS unsigned*)(lds + (bufoff) + ldsw + 8192), 16, 0, 0); } while (0)
; #define G_LDA(dst, b, h) do { _Pragma("unroll") for (int m = 0; m < 4; ++m) _Pragma("unroll") for (int k = 0; k < 2; ++k) dst[m][k] = *(const LAS bf16x8*)(lds + G_SA(b, h) + aoff + m * 2048 + k * 1024); } while (0)
; #define G_LDB(dst, b, h) do { _Pragma("unroll") for (int n = 0; n < 2; ++n) _Pragma("unroll") for (int k = 0; k < 2; ++k) dst[n][k] = *(const LAS bf16x8*)(lds + G_SB(b, h) + boff + n * 2048 + k * 1024); } while (0)
; #define G_WAIT_L(n) asm volatile("s_waitcnt lgkmcnt(" #n ")" ::: "memory")
; #define G_BAR __builtin_amdgcn_s_barrier()
; #define G_SCHED __builtin_amdgcn_sched_barrier(0)
;     ...
;             G_LDB(B0, 0, 0); G_SCHED; G_LDA(At, 0, 0); G_STAGE(G_SA(1, 1), a1 + chA, cA0, qA);
;             G_WAIT_L(8); G_BAR; G_WAIT_L(0); G_MMA(0, 0, At, B0); G_BAR; G_SCHED;
;             G_LDB(B1, 0, 1); G_STAGE(G_SB(0, 0), b2, cB0, qB);
;             G_BAR; G_WAIT_L(0); G_MMA(0, 1, At, B1); G_BAR;
;             G_LDA(At, 0, 1); G_STAGE(G_SA(0, 0), a2, cA0, qA);
;             G_BAR; G_WAIT_L(0); G_MMA(1, 0, At, B0); G_BAR; G_SCHED;
;             G_STAGE(G_SB(0, 1), b2 + chB, cB0, qB);
;     ...
;         for (int a = 0; a < 2; ++a)
; #pragma unroll
;             for (int b = 0; b < 2; ++b)
; #pragma unroll
;                 for (int m = 0; m < 4; ++m)
; #pragma unroll
;                     for (int n = 0; n < 2; ++n) acc[a][b][m][n] = (f32x4){0.f, 0.f, 0.f, 0.f};
.Ldb_FFO_sk:
	s_mov_b32 s101, 0
	s_waitcnt lgkmcnt(0)
	v_mfma_f32_16x16x32_bf16 v[132:135], v[136:139], v[152:155], v[132:135]
	v_mfma_f32_16x16x32_bf16 v[128:131], v[144:147], v[152:155], v[128:131]
	v_mfma_f32_16x16x32_bf16 v[116:119], v[136:139], v[160:163], v[116:119]
	v_mfma_f32_16x16x32_bf16 v[112:115], v[144:147], v[160:163], v[112:115]
	v_mfma_f32_16x16x32_bf16 v[100:103], v[136:139], v[176:179], v[100:103]
	v_mfma_f32_16x16x32_bf16 v[96:99], v[144:147], v[176:179], v[96:99]
	v_mfma_f32_16x16x32_bf16 v[84:87], v[136:139], v[196:199], v[84:87]
	v_mfma_f32_16x16x32_bf16 v[80:83], v[144:147], v[196:199], v[80:83]
	v_mfma_f32_16x16x32_bf16 v[132:135], v[140:143], v[156:159], v[132:135]
	v_mfma_f32_16x16x32_bf16 v[128:131], v[148:151], v[156:159], v[128:131]
	v_mfma_f32_16x16x32_bf16 v[116:119], v[140:143], v[164:167], v[116:119]
	v_mfma_f32_16x16x32_bf16 v[112:115], v[148:151], v[164:167], v[112:115]
	v_mfma_f32_16x16x32_bf16 v[100:103], v[140:143], v[180:183], v[100:103]
	v_mfma_f32_16x16x32_bf16 v[96:99], v[148:151], v[180:183], v[96:99]
	v_mfma_f32_16x16x32_bf16 v[84:87], v[140:143], v[200:203], v[84:87]
	v_mfma_f32_16x16x32_bf16 v[80:83], v[148:151], v[200:203], v[80:83]
	s_barrier
	s_add_i32 s44, 0, 0x14000
	v_lshl_add_u64 v[220:221], s[22:23], 0, v[172:173]
	s_add_i32 s22, s33, s25
	v_add_u32_e32 v0, s44, v185
	s_mov_b32 m0, s22
	ds_read_b128 v[204:207], v0
	ds_read_b128 v[208:211], v0 offset:1024
	ds_read_b128 v[212:215], v0 offset:2048
	ds_read_b128 v[216:219], v0 offset:3072
	global_load_lds_dwordx4 v[220:221], off
	v_lshl_add_u64 v[222:223], v[220:221], 0, s[86:87]
	s_add_i32 m0, s22, 0x2000
	s_nop 0
	global_load_lds_dwordx4 v[222:223], off
	s_cmp_lg_u32 s21, -2
	s_cbranch_scc1 .Lzil_FFO_1
	v_mov_b64_e32 v[72:73], 0
	v_mov_b64_e32 v[74:75], 0
	v_mov_b64_e32 v[76:77], 0
	v_mov_b64_e32 v[78:79], 0
	v_mov_b64_e32 v[88:89], 0
	v_mov_b64_e32 v[90:91], 0
	v_mov_b64_e32 v[92:93], 0
	v_mov_b64_e32 v[94:95], 0
	v_mov_b64_e32 v[104:105], 0
	v_mov_b64_e32 v[106:107], 0
	v_mov_b64_e32 v[108:109], 0
	v_mov_b64_e32 v[110:111], 0
	v_mov_b64_e32 v[120:121], 0
	v_mov_b64_e32 v[122:123], 0
	v_mov_b64_e32 v[124:125], 0
	v_mov_b64_e32 v[126:127], 0
.Lzil_FFO_1:
	s_barrier
	s_waitcnt lgkmcnt(0)
	v_mfma_f32_16x16x32_bf16 v[124:127], v[204:207], v[152:155], v[124:127]
	v_mfma_f32_16x16x32_bf16 v[120:123], v[212:215], v[152:155], v[120:123]
	v_mfma_f32_16x16x32_bf16 v[108:111], v[204:207], v[160:163], v[108:111]
	v_mfma_f32_16x16x32_bf16 v[104:107], v[212:215], v[160:163], v[104:107]
	v_mfma_f32_16x16x32_bf16 v[92:95], v[204:207], v[176:179], v[92:95]
	v_mfma_f32_16x16x32_bf16 v[88:91], v[212:215], v[176:179], v[88:91]
	v_mfma_f32_16x16x32_bf16 v[76:79], v[204:207], v[196:199], v[76:79]
	v_mfma_f32_16x16x32_bf16 v[72:75], v[212:215], v[196:199], v[72:75]
	v_mfma_f32_16x16x32_bf16 v[124:127], v[208:211], v[156:159], v[124:127]
	v_mfma_f32_16x16x32_bf16 v[120:123], v[216:219], v[156:159], v[120:123]
	v_mfma_f32_16x16x32_bf16 v[108:111], v[208:211], v[164:167], v[108:111]
	v_mfma_f32_16x16x32_bf16 v[104:107], v[216:219], v[164:167], v[104:107]
	v_mfma_f32_16x16x32_bf16 v[92:95], v[208:211], v[180:183], v[92:95]
	v_mfma_f32_16x16x32_bf16 v[88:91], v[216:219], v[180:183], v[88:91]
	v_mfma_f32_16x16x32_bf16 v[76:79], v[208:211], v[200:203], v[76:79]
	v_mfma_f32_16x16x32_bf16 v[72:75], v[216:219], v[200:203], v[72:75]
	s_barrier
	s_mov_b32 m0, s26
	v_lshl_add_u64 v[222:223], s[4:5], 0, v[2:3]
	ds_read_b128 v[152:155], v195 offset:16384
	ds_read_b128 v[156:159], v195 offset:17408
	ds_read_b128 v[160:163], v195 offset:18432
	ds_read_b128 v[164:167], v195 offset:19456
	ds_read_b128 v[176:179], v195 offset:20480
	ds_read_b128 v[180:183], v195 offset:21504
	ds_read_b128 v[196:199], v195 offset:22528
	ds_read_b128 v[200:203], v195 offset:23552
	global_load_lds_dwordx4 v[222:223], off
	v_lshl_add_u64 v[224:225], v[222:223], 0, s[86:87]
	s_mov_b32 m0, s27
	s_nop 0
	global_load_lds_dwordx4 v[224:225], off
	s_cmp_lg_u32 s21, -2
	s_cbranch_scc1 .Lzil_FFO_2
	v_mov_b64_e32 v[16:17], 0
	v_mov_b64_e32 v[18:19], 0
	v_mov_b64_e32 v[20:21], 0
	v_mov_b64_e32 v[22:23], 0
	v_mov_b64_e32 v[32:33], 0
	v_mov_b64_e32 v[34:35], 0
	v_mov_b64_e32 v[36:37], 0
	v_mov_b64_e32 v[38:39], 0
	v_mov_b64_e32 v[48:49], 0
	v_mov_b64_e32 v[50:51], 0
	v_mov_b64_e32 v[52:53], 0
	v_mov_b64_e32 v[54:55], 0
	v_mov_b64_e32 v[64:65], 0
	v_mov_b64_e32 v[66:67], 0
	v_mov_b64_e32 v[68:69], 0
	v_mov_b64_e32 v[70:71], 0
.Lzil_FFO_2:
	s_barrier
	s_waitcnt lgkmcnt(0)
	v_mfma_f32_16x16x32_bf16 v[68:71], v[136:139], v[152:155], v[68:71]
	v_mfma_f32_16x16x32_bf16 v[64:67], v[144:147], v[152:155], v[64:67]
	v_mfma_f32_16x16x32_bf16 v[52:55], v[136:139], v[160:163], v[52:55]
	v_mfma_f32_16x16x32_bf16 v[48:51], v[144:147], v[160:163], v[48:51]
	v_mfma_f32_16x16x32_bf16 v[36:39], v[136:139], v[176:179], v[36:39]
	v_mfma_f32_16x16x32_bf16 v[32:35], v[144:147], v[176:179], v[32:35]
	v_mfma_f32_16x16x32_bf16 v[20:23], v[136:139], v[196:199], v[20:23]
	v_mfma_f32_16x16x32_bf16 v[16:19], v[144:147], v[196:199], v[16:19]
	v_mfma_f32_16x16x32_bf16 v[68:71], v[140:143], v[156:159], v[68:71]
	v_mfma_f32_16x16x32_bf16 v[64:67], v[148:151], v[156:159], v[64:67]
	v_mfma_f32_16x16x32_bf16 v[52:55], v[140:143], v[164:167], v[52:55]
	v_mfma_f32_16x16x32_bf16 v[48:51], v[148:151], v[164:167], v[48:51]
	v_mfma_f32_16x16x32_bf16 v[36:39], v[140:143], v[180:183], v[36:39]
	v_mfma_f32_16x16x32_bf16 v[32:35], v[148:151], v[180:183], v[32:35]
	v_mfma_f32_16x16x32_bf16 v[20:23], v[140:143], v[200:203], v[20:23]
	v_mfma_f32_16x16x32_bf16 v[16:19], v[148:151], v[200:203], v[16:19]
	s_barrier
	s_add_i32 s4, s44, s25
	v_lshl_add_u64 v[136:137], v[220:221], 0, s[88:89]
	s_mov_b32 m0, s4
	s_nop 0
	global_load_lds_dwordx4 v[136:137], off
	v_lshl_add_u64 v[136:137], v[220:221], 0, s[64:65]
	s_add_i32 m0, s4, 0x2000
	s_nop 0
	global_load_lds_dwordx4 v[136:137], off
	s_cmp_lg_u32 s21, -2
	s_cbranch_scc1 .Lzil_FFO_3
	v_mov_b64_e32 v[8:9], 0
	v_mov_b64_e32 v[10:11], 0
	v_mov_b64_e32 v[12:13], 0
	v_mov_b64_e32 v[14:15], 0
	v_mov_b64_e32 v[24:25], 0
	v_mov_b64_e32 v[26:27], 0
	v_mov_b64_e32 v[28:29], 0
	v_mov_b64_e32 v[30:31], 0
	v_mov_b64_e32 v[40:41], 0
	v_mov_b64_e32 v[42:43], 0
	v_mov_b64_e32 v[44:45], 0
	v_mov_b64_e32 v[46:47], 0
	v_mov_b64_e32 v[56:57], 0
	v_mov_b64_e32 v[58:59], 0
	v_mov_b64_e32 v[60:61], 0
	v_mov_b64_e32 v[62:63], 0
; #define G_STAGE(bufoff, gbase, o0, h64) do { \
;         __builtin_amdgcn_global_load_lds((const unsigned*)((const char*)(gbase) + (o0)), (LAS unsigned*)(lds + (bufoff) + ldsw), 16, 0, 0); \
;         __builtin_amdgcn_global_load_lds((const unsigned*)((const char*)(gbase) + (h64) + (o0)), (LAS unsigned*)(lds + (bufoff) + ldsw + 8192), 16, 0, 0); } while (0)
; #define G_LDA(dst, b, h) do { _Pragma("unroll") for (int m = 0; m < 4; ++m) _Pragma("unroll") for (int k = 0; k < 2; ++k) dst[m][k] = *(const LAS bf16x8*)(lds + G_SA(b, h) + aoff + m * 2048 + k * 1024); } while (0)
; #define G_LDB(dst, b, h) do { _Pragma("unroll") for (int n = 0; n < 2; ++n) _Pragma("unroll") for (int k = 0; k < 2; ++k) dst[n][k] = *(const LAS bf16x8*)(lds + G_SB(b, h) + boff + n * 2048 + k * 1024); } while (0)
; #define G_WAIT_V(n) asm volatile("s_waitcnt vmcnt(" #n ")" ::: "memory")
; #define G_WAIT_L(n) asm volatile("s_waitcnt lgkmcnt(" #n ")" ::: "memory")
; #define G_BAR __builtin_amdgcn_s_barrier()
; #define G_SCHED __builtin_amdgcn_sched_barrier(0)
;     ...
;             G_STAGE(G_SB(0, 1), b2 + chB, cB0, qB);
;             G_WAIT_V(6); G_BAR; G_MMA(1, 1, At, B1); G_BAR;
;             G_LDB(B0, 1, 0); G_SCHED; G_LDA(At, 1, 0); G_STAGE(G_SA(0, 1), a2 + chA, cA0, qA);
;             G_WAIT_L(8); G_BAR; G_WAIT_L(0); G_MMA(0, 0, At, B0); G_BAR; G_SCHED;
;             G_LDB(B1, 1, 1); G_STAGE(G_SB(1, 0), b3, cB0, qB);
;             G_BAR; G_WAIT_L(0); G_MMA(0, 1, At, B1); G_BAR;
;             G_LDA(At, 1, 1); G_STAGE(G_SA(1, 0), a3, cA0, qA);
.Lzil_FFO_3:
	s_waitcnt vmcnt(6)
	s_barrier
	v_mfma_f32_16x16x32_bf16 v[60:63], v[204:207], v[152:155], v[60:63]
	v_mfma_f32_16x16x32_bf16 v[56:59], v[212:215], v[152:155], v[56:59]
	v_mfma_f32_16x16x32_bf16 v[44:47], v[204:207], v[160:163], v[44:47]
	v_mfma_f32_16x16x32_bf16 v[40:43], v[212:215], v[160:163], v[40:43]
	v_mfma_f32_16x16x32_bf16 v[28:31], v[204:207], v[176:179], v[28:31]
	v_mfma_f32_16x16x32_bf16 v[24:27], v[212:215], v[176:179], v[24:27]
	v_mfma_f32_16x16x32_bf16 v[12:15], v[204:207], v[196:199], v[12:15]
	v_mfma_f32_16x16x32_bf16 v[8:11], v[212:215], v[196:199], v[8:11]
	v_mfma_f32_16x16x32_bf16 v[60:63], v[208:211], v[156:159], v[60:63]
	v_mfma_f32_16x16x32_bf16 v[56:59], v[216:219], v[156:159], v[56:59]
	v_mfma_f32_16x16x32_bf16 v[44:47], v[208:211], v[164:167], v[44:47]
	v_mfma_f32_16x16x32_bf16 v[40:43], v[216:219], v[164:167], v[40:43]
	v_mfma_f32_16x16x32_bf16 v[28:31], v[208:211], v[180:183], v[28:31]
	v_mfma_f32_16x16x32_bf16 v[24:27], v[216:219], v[180:183], v[24:27]
	v_mfma_f32_16x16x32_bf16 v[12:15], v[208:211], v[200:203], v[12:15]
	v_mfma_f32_16x16x32_bf16 v[8:11], v[216:219], v[200:203], v[8:11]
	s_barrier
	s_add_i32 s4, 0, 0x18000
	v_add_u32_e32 v0, s4, v185
	ds_read_b128 v[136:139], v0
	ds_read_b128 v[140:143], v0 offset:1024
	ds_read_b128 v[144:147], v0 offset:2048
	ds_read_b128 v[148:151], v0 offset:3072
	s_mov_b32 m0, s29
	v_lshl_add_u64 v[204:205], v[222:223], 0, s[88:89]
	ds_read_b128 v[152:155], v195 offset:32768
	ds_read_b128 v[156:159], v195 offset:33792
	ds_read_b128 v[160:163], v195 offset:34816
	ds_read_b128 v[164:167], v195 offset:35840
	ds_read_b128 v[176:179], v195 offset:36864
	ds_read_b128 v[180:183], v195 offset:37888
	ds_read_b128 v[196:199], v195 offset:38912
	ds_read_b128 v[200:203], v195 offset:39936
	global_load_lds_dwordx4 v[204:205], off
	v_lshl_add_u64 v[204:205], v[222:223], 0, s[64:65]
	s_mov_b32 m0, s30
	s_nop 0
	global_load_lds_dwordx4 v[204:205], off
	s_waitcnt lgkmcnt(8)
	s_barrier
	s_waitcnt lgkmcnt(0)
	v_mfma_f32_16x16x32_bf16 v[132:135], v[136:139], v[152:155], v[132:135]
	v_mfma_f32_16x16x32_bf16 v[128:131], v[144:147], v[152:155], v[128:131]
	v_mfma_f32_16x16x32_bf16 v[116:119], v[136:139], v[160:163], v[116:119]
	v_mfma_f32_16x16x32_bf16 v[112:115], v[144:147], v[160:163], v[112:115]
	v_mfma_f32_16x16x32_bf16 v[100:103], v[136:139], v[176:179], v[100:103]
	v_mfma_f32_16x16x32_bf16 v[96:99], v[144:147], v[176:179], v[96:99]
	v_mfma_f32_16x16x32_bf16 v[84:87], v[136:139], v[196:199], v[84:87]
	v_mfma_f32_16x16x32_bf16 v[80:83], v[144:147], v[196:199], v[80:83]
	v_mfma_f32_16x16x32_bf16 v[132:135], v[140:143], v[156:159], v[132:135]
	v_mfma_f32_16x16x32_bf16 v[128:131], v[148:151], v[156:159], v[128:131]
	v_mfma_f32_16x16x32_bf16 v[116:119], v[140:143], v[164:167], v[116:119]
	v_mfma_f32_16x16x32_bf16 v[112:115], v[148:151], v[164:167], v[112:115]
	v_mfma_f32_16x16x32_bf16 v[100:103], v[140:143], v[180:183], v[100:103]
	v_mfma_f32_16x16x32_bf16 v[96:99], v[148:151], v[180:183], v[96:99]
	v_mfma_f32_16x16x32_bf16 v[84:87], v[140:143], v[200:203], v[84:87]
	v_mfma_f32_16x16x32_bf16 v[80:83], v[148:151], v[200:203], v[80:83]
	s_barrier
	s_add_i32 s5, 0, 0x1c000
	s_add_i32 s4, s4, s25
	v_add_u32_e32 v0, s5, v185
	v_lshl_add_u64 v[224:225], v[220:221], 0, s[46:47]
	s_mov_b32 m0, s4
	ds_read_b128 v[204:207], v0
	ds_read_b128 v[208:211], v0 offset:1024
	ds_read_b128 v[212:215], v0 offset:2048
	ds_read_b128 v[216:219], v0 offset:3072
	global_load_lds_dwordx4 v[224:225], off
	v_lshl_add_u64 v[224:225], v[220:221], 0, s[66:67]
	s_add_i32 m0, s4, 0x2000
	s_nop 0
	global_load_lds_dwordx4 v[224:225], off
	s_barrier
; #define G_STAGE(bufoff, gbase, o0, h64) do { \
;         __builtin_amdgcn_global_load_lds((const unsigned*)((const char*)(gbase) + (o0)), (LAS unsigned*)(lds + (bufoff) + ldsw), 16, 0, 0); \
;         __builtin_amdgcn_global_load_lds((const unsigned*)((const char*)(gbase) + (h64) + (o0)), (LAS unsigned*)(lds + (bufoff) + ldsw + 8192), 16, 0, 0); } while (0)
; #define G_LDA(dst, b, h) do { _Pragma("unroll") for (int m = 0; m < 4; ++m) _Pragma("unroll") for (int k = 0; k < 2; ++k) dst[m][k] = *(const LAS bf16x8*)(lds + G_SA(b, h) + aoff + m * 2048 + k * 1024); } while (0)
; #define G_WAIT_V(n) asm volatile("s_waitcnt vmcnt(" #n ")" ::: "memory")
; #define G_WAIT_L(n) asm volatile("s_waitcnt lgkmcnt(" #n ")" ::: "memory")
; #define G_BAR __builtin_amdgcn_s_barrier()
; #define G_SCHED __builtin_amdgcn_sched_barrier(0)
;     ...
;             G_LDA(At, 1, 1); G_STAGE(G_SA(1, 0), a3, cA0, qA);
;             G_BAR; G_WAIT_L(0); G_MMA(1, 0, At, B0); G_BAR; G_SCHED;
;             G_STAGE(G_SB(1, 1), b3 + chB, cB0, qB);
;             G_WAIT_V(6); G_BAR; G_MMA(1, 1, At, B1); G_BAR;
;         }
	s_waitcnt lgkmcnt(0)
	v_mfma_f32_16x16x32_bf16 v[124:127], v[204:207], v[152:155], v[124:127]
	v_mfma_f32_16x16x32_bf16 v[120:123], v[212:215], v[152:155], v[120:123]
	v_mfma_f32_16x16x32_bf16 v[108:111], v[204:207], v[160:163], v[108:111]
	v_mfma_f32_16x16x32_bf16 v[104:107], v[212:215], v[160:163], v[104:107]
	v_mfma_f32_16x16x32_bf16 v[92:95], v[204:207], v[176:179], v[92:95]
	v_mfma_f32_16x16x32_bf16 v[88:91], v[212:215], v[176:179], v[88:91]
	v_mfma_f32_16x16x32_bf16 v[76:79], v[204:207], v[196:199], v[76:79]
	v_mfma_f32_16x16x32_bf16 v[72:75], v[212:215], v[196:199], v[72:75]
	v_mfma_f32_16x16x32_bf16 v[124:127], v[208:211], v[156:159], v[124:127]
	v_mfma_f32_16x16x32_bf16 v[120:123], v[216:219], v[156:159], v[120:123]
	v_mfma_f32_16x16x32_bf16 v[108:111], v[208:211], v[164:167], v[108:111]
	v_mfma_f32_16x16x32_bf16 v[104:107], v[216:219], v[164:167], v[104:107]
	v_mfma_f32_16x16x32_bf16 v[92:95], v[208:211], v[180:183], v[92:95]
	v_mfma_f32_16x16x32_bf16 v[88:91], v[216:219], v[180:183], v[88:91]
	v_mfma_f32_16x16x32_bf16 v[76:79], v[208:211], v[200:203], v[76:79]
	v_mfma_f32_16x16x32_bf16 v[72:75], v[216:219], v[200:203], v[72:75]
	s_barrier
	s_mov_b32 m0, s31
	v_lshl_add_u64 v[224:225], v[222:223], 0, s[46:47]
	ds_read_b128 v[152:155], v195 offset:49152
	ds_read_b128 v[156:159], v195 offset:50176
	ds_read_b128 v[160:163], v195 offset:51200
	ds_read_b128 v[164:167], v195 offset:52224
	ds_read_b128 v[176:179], v195 offset:53248
	ds_read_b128 v[180:183], v195 offset:54272
	ds_read_b128 v[196:199], v195 offset:55296
	ds_read_b128 v[200:203], v195 offset:56320
	global_load_lds_dwordx4 v[224:225], off
	v_lshl_add_u64 v[222:223], v[222:223], 0, s[66:67]
	s_mov_b32 m0, s34
	s_nop 0
	global_load_lds_dwordx4 v[222:223], off
	s_barrier
	s_waitcnt lgkmcnt(0)
	v_mfma_f32_16x16x32_bf16 v[68:71], v[136:139], v[152:155], v[68:71]
	v_mfma_f32_16x16x32_bf16 v[64:67], v[144:147], v[152:155], v[64:67]
	v_mfma_f32_16x16x32_bf16 v[52:55], v[136:139], v[160:163], v[52:55]
	v_mfma_f32_16x16x32_bf16 v[48:51], v[144:147], v[160:163], v[48:51]
	v_mfma_f32_16x16x32_bf16 v[36:39], v[136:139], v[176:179], v[36:39]
	v_mfma_f32_16x16x32_bf16 v[32:35], v[144:147], v[176:179], v[32:35]
	v_mfma_f32_16x16x32_bf16 v[20:23], v[136:139], v[196:199], v[20:23]
	v_mfma_f32_16x16x32_bf16 v[16:19], v[144:147], v[196:199], v[16:19]
	v_mfma_f32_16x16x32_bf16 v[68:71], v[140:143], v[156:159], v[68:71]
	v_mfma_f32_16x16x32_bf16 v[64:67], v[148:151], v[156:159], v[64:67]
	v_mfma_f32_16x16x32_bf16 v[52:55], v[140:143], v[164:167], v[52:55]
	v_mfma_f32_16x16x32_bf16 v[48:51], v[148:151], v[164:167], v[48:51]
	v_mfma_f32_16x16x32_bf16 v[36:39], v[140:143], v[180:183], v[36:39]
	v_mfma_f32_16x16x32_bf16 v[32:35], v[148:151], v[180:183], v[32:35]
	v_mfma_f32_16x16x32_bf16 v[20:23], v[140:143], v[200:203], v[20:23]
	v_mfma_f32_16x16x32_bf16 v[16:19], v[148:151], v[200:203], v[16:19]
	s_barrier
	s_add_i32 s4, s5, s25
	v_lshl_add_u64 v[136:137], v[220:221], 0, s[52:53]
	s_mov_b32 m0, s4
	s_nop 0
	global_load_lds_dwordx4 v[136:137], off
	v_lshl_add_u64 v[136:137], v[220:221], 0, s[54:55]
	s_add_i32 m0, s4, 0x2000
	s_nop 0
	global_load_lds_dwordx4 v[136:137], off
	s_add_i32 s21, s21, 2
	s_add_u32 s2, s2, 0x100
	s_addc_u32 s3, s3, 0
	s_add_u32 s6, s6, 0x100
	s_addc_u32 s7, s7, 0
	s_cmp_gt_u32 s21, 41
	s_waitcnt vmcnt(6)
	s_barrier
	v_mfma_f32_16x16x32_bf16 v[60:63], v[204:207], v[152:155], v[60:63]
	v_mfma_f32_16x16x32_bf16 v[56:59], v[212:215], v[152:155], v[56:59]
	v_mfma_f32_16x16x32_bf16 v[44:47], v[204:207], v[160:163], v[44:47]
	v_mfma_f32_16x16x32_bf16 v[40:43], v[212:215], v[160:163], v[40:43]
	v_mfma_f32_16x16x32_bf16 v[28:31], v[204:207], v[176:179], v[28:31]
	v_mfma_f32_16x16x32_bf16 v[24:27], v[212:215], v[176:179], v[24:27]
	v_mfma_f32_16x16x32_bf16 v[12:15], v[204:207], v[196:199], v[12:15]
	v_mfma_f32_16x16x32_bf16 v[8:11], v[212:215], v[196:199], v[8:11]
	v_mfma_f32_16x16x32_bf16 v[60:63], v[208:211], v[156:159], v[60:63]
	v_mfma_f32_16x16x32_bf16 v[56:59], v[216:219], v[156:159], v[56:59]
	v_mfma_f32_16x16x32_bf16 v[44:47], v[208:211], v[164:167], v[44:47]
	v_mfma_f32_16x16x32_bf16 v[40:43], v[216:219], v[164:167], v[40:43]
	v_mfma_f32_16x16x32_bf16 v[28:31], v[208:211], v[180:183], v[28:31]
	v_mfma_f32_16x16x32_bf16 v[24:27], v[216:219], v[180:183], v[24:27]
	v_mfma_f32_16x16x32_bf16 v[12:15], v[208:211], v[200:203], v[12:15]
	v_mfma_f32_16x16x32_bf16 v[8:11], v[216:219], v[200:203], v[8:11]
	s_cbranch_scc0 .Ldb_FFO_cont
	v_readfirstlane_b32 s101, v186
	s_cmpk_gt_u32 s101, 0xff
	s_cbranch_scc1 .Ldb_FFO_young
	s_barrier
	s_mov_b32 s101, 1
	s_branch .Ldb_FFO_exit

; #define G_STAGE(bufoff, gbase, o0, h64) do { \
;         __builtin_amdgcn_global_load_lds((const unsigned*)((const char*)(gbase) + (o0)), (LAS unsigned*)(lds + (bufoff) + ldsw), 16, 0, 0); \
;         __builtin_amdgcn_global_load_lds((const unsigned*)((const char*)(gbase) + (h64) + (o0)), (LAS unsigned*)(lds + (bufoff) + ldsw + 8192), 16, 0, 0); } while (0)
; #define G_LDA(dst, b, h) do { _Pragma("unroll") for (int m = 0; m < 4; ++m) _Pragma("unroll") for (int k = 0; k < 2; ++k) dst[m][k] = *(const LAS bf16x8*)(lds + G_SA(b, h) + aoff + m * 2048 + k * 1024); } while (0)
; #define G_LDB(dst, b, h) do { _Pragma("unroll") for (int n = 0; n < 2; ++n) _Pragma("unroll") for (int k = 0; k < 2; ++k) dst[n][k] = *(const LAS bf16x8*)(lds + G_SB(b, h) + boff + n * 2048 + k * 1024); } while (0)
; #define G_SCHED __builtin_amdgcn_sched_barrier(0)
;     ...
;         for (int t = 0; t < nt; t += 2) {
;             const bool last = (t == nt - 2);
;             const char* a1 = cA + (size_t)(t + 1) * ckA;
;             const char* a2 = last ? nA : cA + (size_t)(t + 2) * ckA; const char* b2 = last ? nB : cB + (size_t)(t + 2) * kB;
;             const char* a3 = a2 + ckA; const char* b3 = b2 + kB;
;             G_LDB(B0, 0, 0); G_SCHED; G_LDA(At, 0, 0); G_STAGE(G_SA(1, 1), a1 + chA, cA0, qA);
;     ...
;         if (!(cs.kind == K_MG_B && cur.aux < 2))
; #pragma unroll
;         for (int a = 0; a < 2; ++a)
; #pragma unroll
;             for (int b = 0; b < 2; ++b)
; #pragma unroll
;                 for (int m = 0; m < 4; ++m)
; #pragma unroll
;                     for (int n = 0; n < 2; ++n) acc[a][b][m][n] = (f32x4){0.f, 0.f, 0.f, 0.f};
;         cur = nxt; cA = nA; cB = nB; ++ui;
.LBB0_1282:
	s_add_u32 s2, s24, 0x40080
	s_addc_u32 s3, s25, 0
	s_add_u32 s22, s22, 0x100
	s_waitcnt lgkmcnt(0)
	s_addc_u32 s23, s23, 0
	s_mov_b32 s24, -2
	s_mov_b64 s[54:55], 0x40000
	s_mov_b64 s[58:59], 0x60000
	s_mov_b64 s[62:63], 0x20080
	s_mov_b64 s[64:65], 0x40080
	s_mov_b64 s[66:67], 0x60080
	s_cmp_eq_u32 s101, 2
	s_cselect_b32 s101, 0, s101
.LBB0_1283:
	s_add_u32 s4, s2, 0xfffc0080
	s_addc_u32 s5, s3, -1
	s_add_i32 s25, 0, 0x10000
	v_add_u32_e32 v0, s25, v181
	ds_read_b128 v[136:139], v0
	ds_read_b128 v[140:143], v0 offset:1024
	ds_read_b128 v[144:147], v0 offset:2048
	ds_read_b128 v[148:151], v0 offset:3072
	s_cmp_eq_u32 s24, 12
	s_cselect_b32 s5, s19, s5
	s_cselect_b32 s4, s18, s4
	s_cselect_b32 s41, s21, s23
	s_cselect_b32 s40, s20, s22
	v_lshl_add_u64 v[184:185], s[2:3], 0, v[158:159]
	s_add_i32 m0, s29, 0xc000
	ds_read_b128 v[152:155], v182
	ds_read_b128 v[160:163], v182 offset:1024
	ds_read_b128 v[164:167], v182 offset:2048
	ds_read_b128 v[172:175], v182 offset:3072
	ds_read_b128 v[176:179], v182 offset:4096
	ds_read_b128 v[196:199], v182 offset:5120
	ds_read_b128 v[200:203], v182 offset:6144
	ds_read_b128 v[204:207], v182 offset:7168
	global_load_lds_dwordx4 v[184:185], off
	v_lshl_add_u64 v[184:185], v[184:185], 0, s[0:1]
	s_add_i32 m0, s29, 0xe000
	s_nop 0
	global_load_lds_dwordx4 v[184:185], off
	s_cmp_lg_u32 s24, -2
	s_cbranch_scc1 .Lzil_PLE1_0
	v_mov_b64_e32 v[80:81], 0
	v_mov_b64_e32 v[82:83], 0
	v_mov_b64_e32 v[84:85], 0
	v_mov_b64_e32 v[86:87], 0
	v_mov_b64_e32 v[96:97], 0
	v_mov_b64_e32 v[98:99], 0
	v_mov_b64_e32 v[100:101], 0
	v_mov_b64_e32 v[102:103], 0
	v_mov_b64_e32 v[112:113], 0
	v_mov_b64_e32 v[114:115], 0
	v_mov_b64_e32 v[116:117], 0
	v_mov_b64_e32 v[118:119], 0
	v_mov_b64_e32 v[128:129], 0
	v_mov_b64_e32 v[130:131], 0
	v_mov_b64_e32 v[132:133], 0
	v_mov_b64_e32 v[134:135], 0

; #define G_STAGE(bufoff, gbase, o0, h64) do { \
;         __builtin_amdgcn_global_load_lds((const unsigned*)((const char*)(gbase) + (o0)), (LAS unsigned*)(lds + (bufoff) + ldsw), 16, 0, 0); \
;         __builtin_amdgcn_global_load_lds((const unsigned*)((const char*)(gbase) + (h64) + (o0)), (LAS unsigned*)(lds + (bufoff) + ldsw + 8192), 16, 0, 0); } while (0)
; #define G_LDA(dst, b, h) do { _Pragma("unroll") for (int m = 0; m < 4; ++m) _Pragma("unroll") for (int k = 0; k < 2; ++k) dst[m][k] = *(const LAS bf16x8*)(lds + G_SA(b, h) + aoff + m * 2048 + k * 1024); } while (0)
; #define G_LDB(dst, b, h) do { _Pragma("unroll") for (int n = 0; n < 2; ++n) _Pragma("unroll") for (int k = 0; k < 2; ++k) dst[n][k] = *(const LAS bf16x8*)(lds + G_SB(b, h) + boff + n * 2048 + k * 1024); } while (0)
; #define G_WAIT_L(n) asm volatile("s_waitcnt lgkmcnt(" #n ")" ::: "memory")
; #define G_BAR __builtin_amdgcn_s_barrier()
; #define G_SCHED __builtin_amdgcn_sched_barrier(0)
;     ...
;             G_LDB(B0, 0, 0); G_SCHED; G_LDA(At, 0, 0); G_STAGE(G_SA(1, 1), a1 + chA, cA0, qA);
;             G_WAIT_L(8); G_BAR; G_WAIT_L(0); G_MMA(0, 0, At, B0); G_BAR; G_SCHED;
;             G_LDB(B1, 0, 1); G_STAGE(G_SB(0, 0), b2, cB0, qB);
;             G_BAR; G_WAIT_L(0); G_MMA(0, 1, At, B1); G_BAR;
;             G_LDA(At, 0, 1); G_STAGE(G_SA(0, 0), a2, cA0, qA);
;             G_BAR; G_WAIT_L(0); G_MMA(1, 0, At, B0); G_BAR; G_SCHED;
;             G_STAGE(G_SB(0, 1), b2 + chB, cB0, qB);
;     ...
;         for (int a = 0; a < 2; ++a)
; #pragma unroll
;             for (int b = 0; b < 2; ++b)
; #pragma unroll
;                 for (int m = 0; m < 4; ++m)
; #pragma unroll
;                     for (int n = 0; n < 2; ++n) acc[a][b][m][n] = (f32x4){0.f, 0.f, 0.f, 0.f};
.Ldb_PLE1_sk:
	s_mov_b32 s101, 0
	s_waitcnt lgkmcnt(0)
	v_mfma_f32_16x16x32_bf16 v[132:135], v[136:139], v[152:155], v[132:135]
	v_mfma_f32_16x16x32_bf16 v[128:131], v[144:147], v[152:155], v[128:131]
	v_mfma_f32_16x16x32_bf16 v[116:119], v[136:139], v[164:167], v[116:119]
	v_mfma_f32_16x16x32_bf16 v[112:115], v[144:147], v[164:167], v[112:115]
	v_mfma_f32_16x16x32_bf16 v[100:103], v[136:139], v[176:179], v[100:103]
	v_mfma_f32_16x16x32_bf16 v[96:99], v[144:147], v[176:179], v[96:99]
	v_mfma_f32_16x16x32_bf16 v[84:87], v[136:139], v[200:203], v[84:87]
	v_mfma_f32_16x16x32_bf16 v[80:83], v[144:147], v[200:203], v[80:83]
	v_mfma_f32_16x16x32_bf16 v[132:135], v[140:143], v[160:163], v[132:135]
	v_mfma_f32_16x16x32_bf16 v[128:131], v[148:151], v[160:163], v[128:131]
	v_mfma_f32_16x16x32_bf16 v[116:119], v[140:143], v[172:175], v[116:119]
	v_mfma_f32_16x16x32_bf16 v[112:115], v[148:151], v[172:175], v[112:115]
	v_mfma_f32_16x16x32_bf16 v[100:103], v[140:143], v[196:199], v[100:103]
	v_mfma_f32_16x16x32_bf16 v[96:99], v[148:151], v[196:199], v[96:99]
	v_mfma_f32_16x16x32_bf16 v[84:87], v[140:143], v[204:207], v[84:87]
	v_mfma_f32_16x16x32_bf16 v[80:83], v[148:151], v[204:207], v[80:83]
	s_barrier
	s_add_i32 s44, 0, 0x14000
	s_add_i32 s25, s25, s27
	v_add_u32_e32 v0, s44, v181
	v_lshl_add_u64 v[184:185], s[40:41], 0, v[156:157]
	s_mov_b32 m0, s25
	ds_read_b128 v[208:211], v0
	ds_read_b128 v[212:215], v0 offset:1024
	ds_read_b128 v[216:219], v0 offset:2048
	ds_read_b128 v[220:223], v0 offset:3072
	global_load_lds_dwordx4 v[184:185], off
	v_lshl_add_u64 v[224:225], v[184:185], 0, s[0:1]
	s_add_i32 m0, s25, 0x2000
	s_nop 0
	global_load_lds_dwordx4 v[224:225], off
	s_cmp_lg_u32 s24, -2
	s_cbranch_scc1 .Lzil_PLE1_1
	v_mov_b64_e32 v[72:73], 0
	v_mov_b64_e32 v[74:75], 0
	v_mov_b64_e32 v[76:77], 0
	v_mov_b64_e32 v[78:79], 0
	v_mov_b64_e32 v[88:89], 0
	v_mov_b64_e32 v[90:91], 0
	v_mov_b64_e32 v[92:93], 0
	v_mov_b64_e32 v[94:95], 0
	v_mov_b64_e32 v[104:105], 0
	v_mov_b64_e32 v[106:107], 0
	v_mov_b64_e32 v[108:109], 0
	v_mov_b64_e32 v[110:111], 0
	v_mov_b64_e32 v[120:121], 0
	v_mov_b64_e32 v[122:123], 0
	v_mov_b64_e32 v[124:125], 0
	v_mov_b64_e32 v[126:127], 0
.Lzil_PLE1_1:
	s_barrier
	s_waitcnt lgkmcnt(0)
	v_mfma_f32_16x16x32_bf16 v[124:127], v[208:211], v[152:155], v[124:127]
	v_mfma_f32_16x16x32_bf16 v[120:123], v[216:219], v[152:155], v[120:123]
	v_mfma_f32_16x16x32_bf16 v[108:111], v[208:211], v[164:167], v[108:111]
	v_mfma_f32_16x16x32_bf16 v[104:107], v[216:219], v[164:167], v[104:107]
	v_mfma_f32_16x16x32_bf16 v[92:95], v[208:211], v[176:179], v[92:95]
	v_mfma_f32_16x16x32_bf16 v[88:91], v[216:219], v[176:179], v[88:91]
	v_mfma_f32_16x16x32_bf16 v[76:79], v[208:211], v[200:203], v[76:79]
	v_mfma_f32_16x16x32_bf16 v[72:75], v[216:219], v[200:203], v[72:75]
	v_mfma_f32_16x16x32_bf16 v[124:127], v[212:215], v[160:163], v[124:127]
	v_mfma_f32_16x16x32_bf16 v[120:123], v[220:223], v[160:163], v[120:123]
	v_mfma_f32_16x16x32_bf16 v[108:111], v[212:215], v[172:175], v[108:111]
	v_mfma_f32_16x16x32_bf16 v[104:107], v[220:223], v[172:175], v[104:107]
	v_mfma_f32_16x16x32_bf16 v[92:95], v[212:215], v[196:199], v[92:95]
	v_mfma_f32_16x16x32_bf16 v[88:91], v[220:223], v[196:199], v[88:91]
	v_mfma_f32_16x16x32_bf16 v[76:79], v[212:215], v[204:207], v[76:79]
	v_mfma_f32_16x16x32_bf16 v[72:75], v[220:223], v[204:207], v[72:75]
	s_barrier
	s_mov_b32 m0, s29
	v_lshl_add_u64 v[224:225], s[4:5], 0, v[2:3]
	ds_read_b128 v[152:155], v182 offset:16384
	ds_read_b128 v[160:163], v182 offset:17408
	ds_read_b128 v[164:167], v182 offset:18432
	ds_read_b128 v[172:175], v182 offset:19456
	ds_read_b128 v[176:179], v182 offset:20480
	ds_read_b128 v[196:199], v182 offset:21504
	ds_read_b128 v[200:203], v182 offset:22528
	ds_read_b128 v[204:207], v182 offset:23552
	global_load_lds_dwordx4 v[224:225], off
	v_lshl_add_u64 v[226:227], v[224:225], 0, s[0:1]
	s_mov_b32 m0, s30
	s_nop 0
	global_load_lds_dwordx4 v[226:227], off
	s_cmp_lg_u32 s24, -2
	s_cbranch_scc1 .Lzil_PLE1_2
	v_mov_b64_e32 v[16:17], 0
	v_mov_b64_e32 v[18:19], 0
	v_mov_b64_e32 v[20:21], 0
	v_mov_b64_e32 v[22:23], 0
	v_mov_b64_e32 v[32:33], 0
	v_mov_b64_e32 v[34:35], 0
	v_mov_b64_e32 v[36:37], 0
	v_mov_b64_e32 v[38:39], 0
	v_mov_b64_e32 v[48:49], 0
	v_mov_b64_e32 v[50:51], 0
	v_mov_b64_e32 v[52:53], 0
	v_mov_b64_e32 v[54:55], 0
	v_mov_b64_e32 v[64:65], 0
	v_mov_b64_e32 v[66:67], 0
	v_mov_b64_e32 v[68:69], 0
	v_mov_b64_e32 v[70:71], 0
.Lzil_PLE1_2:
	s_barrier
	s_waitcnt lgkmcnt(0)
	v_mfma_f32_16x16x32_bf16 v[68:71], v[136:139], v[152:155], v[68:71]
	v_mfma_f32_16x16x32_bf16 v[64:67], v[144:147], v[152:155], v[64:67]
	v_mfma_f32_16x16x32_bf16 v[52:55], v[136:139], v[164:167], v[52:55]
	v_mfma_f32_16x16x32_bf16 v[48:51], v[144:147], v[164:167], v[48:51]
	v_mfma_f32_16x16x32_bf16 v[36:39], v[136:139], v[176:179], v[36:39]
	v_mfma_f32_16x16x32_bf16 v[32:35], v[144:147], v[176:179], v[32:35]
	v_mfma_f32_16x16x32_bf16 v[20:23], v[136:139], v[200:203], v[20:23]
	v_mfma_f32_16x16x32_bf16 v[16:19], v[144:147], v[200:203], v[16:19]
	v_mfma_f32_16x16x32_bf16 v[68:71], v[140:143], v[160:163], v[68:71]
	v_mfma_f32_16x16x32_bf16 v[64:67], v[148:151], v[160:163], v[64:67]
	v_mfma_f32_16x16x32_bf16 v[52:55], v[140:143], v[172:175], v[52:55]
	v_mfma_f32_16x16x32_bf16 v[48:51], v[148:151], v[172:175], v[48:51]
	v_mfma_f32_16x16x32_bf16 v[36:39], v[140:143], v[196:199], v[36:39]
	v_mfma_f32_16x16x32_bf16 v[32:35], v[148:151], v[196:199], v[32:35]
	v_mfma_f32_16x16x32_bf16 v[20:23], v[140:143], v[204:207], v[20:23]
	v_mfma_f32_16x16x32_bf16 v[16:19], v[148:151], v[204:207], v[16:19]
	s_barrier
	s_add_i32 s4, s44, s27
	v_lshl_add_u64 v[136:137], v[184:185], 0, s[54:55]
	s_mov_b32 m0, s4
	s_nop 0
	global_load_lds_dwordx4 v[136:137], off
	v_lshl_add_u64 v[136:137], v[184:185], 0, s[58:59]
	s_add_i32 m0, s4, 0x2000
	s_nop 0
	global_load_lds_dwordx4 v[136:137], off
	s_cmp_lg_u32 s24, -2
	s_cbranch_scc1 .Lzil_PLE1_3
	v_mov_b64_e32 v[8:9], 0
	v_mov_b64_e32 v[10:11], 0
	v_mov_b64_e32 v[12:13], 0
	v_mov_b64_e32 v[14:15], 0
	v_mov_b64_e32 v[24:25], 0
	v_mov_b64_e32 v[26:27], 0
	v_mov_b64_e32 v[28:29], 0
	v_mov_b64_e32 v[30:31], 0
	v_mov_b64_e32 v[40:41], 0
	v_mov_b64_e32 v[42:43], 0
	v_mov_b64_e32 v[44:45], 0
	v_mov_b64_e32 v[46:47], 0
	v_mov_b64_e32 v[56:57], 0
	v_mov_b64_e32 v[58:59], 0
	v_mov_b64_e32 v[60:61], 0
	v_mov_b64_e32 v[62:63], 0
; #define G_STAGE(bufoff, gbase, o0, h64) do { \
;         __builtin_amdgcn_global_load_lds((const unsigned*)((const char*)(gbase) + (o0)), (LAS unsigned*)(lds + (bufoff) + ldsw), 16, 0, 0); \
;         __builtin_amdgcn_global_load_lds((const unsigned*)((const char*)(gbase) + (h64) + (o0)), (LAS unsigned*)(lds + (bufoff) + ldsw + 8192), 16, 0, 0); } while (0)
; #define G_LDA(dst, b, h) do { _Pragma("unroll") for (int m = 0; m < 4; ++m) _Pragma("unroll") for (int k = 0; k < 2; ++k) dst[m][k] = *(const LAS bf16x8*)(lds + G_SA(b, h) + aoff + m * 2048 + k * 1024); } while (0)
; #define G_LDB(dst, b, h) do { _Pragma("unroll") for (int n = 0; n < 2; ++n) _Pragma("unroll") for (int k = 0; k < 2; ++k) dst[n][k] = *(const LAS bf16x8*)(lds + G_SB(b, h) + boff + n * 2048 + k * 1024); } while (0)
; #define G_WAIT_V(n) asm volatile("s_waitcnt vmcnt(" #n ")" ::: "memory")
; #define G_WAIT_L(n) asm volatile("s_waitcnt lgkmcnt(" #n ")" ::: "memory")
; #define G_BAR __builtin_amdgcn_s_barrier()
; #define G_SCHED __builtin_amdgcn_sched_barrier(0)
;     ...
;             G_STAGE(G_SB(0, 1), b2 + chB, cB0, qB);
;             G_WAIT_V(6); G_BAR; G_MMA(1, 1, At, B1); G_BAR;
;             G_LDB(B0, 1, 0); G_SCHED; G_LDA(At, 1, 0); G_STAGE(G_SA(0, 1), a2 + chA, cA0, qA);
;             G_WAIT_L(8); G_BAR; G_WAIT_L(0); G_MMA(0, 0, At, B0); G_BAR; G_SCHED;
;             G_LDB(B1, 1, 1); G_STAGE(G_SB(1, 0), b3, cB0, qB);
;             G_BAR; G_WAIT_L(0); G_MMA(0, 1, At, B1); G_BAR;
;             G_LDA(At, 1, 1); G_STAGE(G_SA(1, 0), a3, cA0, qA);
.Lzil_PLE1_3:
	s_waitcnt vmcnt(6)
	s_barrier
	v_mfma_f32_16x16x32_bf16 v[60:63], v[208:211], v[152:155], v[60:63]
	v_mfma_f32_16x16x32_bf16 v[56:59], v[216:219], v[152:155], v[56:59]
	v_mfma_f32_16x16x32_bf16 v[44:47], v[208:211], v[164:167], v[44:47]
	v_mfma_f32_16x16x32_bf16 v[40:43], v[216:219], v[164:167], v[40:43]
	v_mfma_f32_16x16x32_bf16 v[28:31], v[208:211], v[176:179], v[28:31]
	v_mfma_f32_16x16x32_bf16 v[24:27], v[216:219], v[176:179], v[24:27]
	v_mfma_f32_16x16x32_bf16 v[12:15], v[208:211], v[200:203], v[12:15]
	v_mfma_f32_16x16x32_bf16 v[8:11], v[216:219], v[200:203], v[8:11]
	v_mfma_f32_16x16x32_bf16 v[60:63], v[212:215], v[160:163], v[60:63]
	v_mfma_f32_16x16x32_bf16 v[56:59], v[220:223], v[160:163], v[56:59]
	v_mfma_f32_16x16x32_bf16 v[44:47], v[212:215], v[172:175], v[44:47]
	v_mfma_f32_16x16x32_bf16 v[40:43], v[220:223], v[172:175], v[40:43]
	v_mfma_f32_16x16x32_bf16 v[28:31], v[212:215], v[196:199], v[28:31]
	v_mfma_f32_16x16x32_bf16 v[24:27], v[220:223], v[196:199], v[24:27]
	v_mfma_f32_16x16x32_bf16 v[12:15], v[212:215], v[204:207], v[12:15]
	v_mfma_f32_16x16x32_bf16 v[8:11], v[220:223], v[204:207], v[8:11]
	s_barrier
	s_add_i32 s4, 0, 0x18000
	v_add_u32_e32 v0, s4, v181
	ds_read_b128 v[136:139], v0
	ds_read_b128 v[140:143], v0 offset:1024
	ds_read_b128 v[144:147], v0 offset:2048
	ds_read_b128 v[148:151], v0 offset:3072
	s_mov_b32 m0, s31
	v_lshl_add_u64 v[208:209], v[224:225], 0, s[54:55]
	ds_read_b128 v[152:155], v182 offset:32768
	ds_read_b128 v[160:163], v182 offset:33792
	ds_read_b128 v[164:167], v182 offset:34816
	ds_read_b128 v[172:175], v182 offset:35840
	ds_read_b128 v[176:179], v182 offset:36864
	ds_read_b128 v[196:199], v182 offset:37888
	ds_read_b128 v[200:203], v182 offset:38912
	ds_read_b128 v[204:207], v182 offset:39936
	global_load_lds_dwordx4 v[208:209], off
	v_lshl_add_u64 v[208:209], v[224:225], 0, s[58:59]
	s_mov_b32 m0, s34
	s_nop 0
	global_load_lds_dwordx4 v[208:209], off
	s_waitcnt lgkmcnt(8)
	s_barrier
	s_waitcnt lgkmcnt(0)
	v_mfma_f32_16x16x32_bf16 v[132:135], v[136:139], v[152:155], v[132:135]
	v_mfma_f32_16x16x32_bf16 v[128:131], v[144:147], v[152:155], v[128:131]
	v_mfma_f32_16x16x32_bf16 v[116:119], v[136:139], v[164:167], v[116:119]
	v_mfma_f32_16x16x32_bf16 v[112:115], v[144:147], v[164:167], v[112:115]
	v_mfma_f32_16x16x32_bf16 v[100:103], v[136:139], v[176:179], v[100:103]
	v_mfma_f32_16x16x32_bf16 v[96:99], v[144:147], v[176:179], v[96:99]
	v_mfma_f32_16x16x32_bf16 v[84:87], v[136:139], v[200:203], v[84:87]
	v_mfma_f32_16x16x32_bf16 v[80:83], v[144:147], v[200:203], v[80:83]
	v_mfma_f32_16x16x32_bf16 v[132:135], v[140:143], v[160:163], v[132:135]
	v_mfma_f32_16x16x32_bf16 v[128:131], v[148:151], v[160:163], v[128:131]
	v_mfma_f32_16x16x32_bf16 v[116:119], v[140:143], v[172:175], v[116:119]
	v_mfma_f32_16x16x32_bf16 v[112:115], v[148:151], v[172:175], v[112:115]
	v_mfma_f32_16x16x32_bf16 v[100:103], v[140:143], v[196:199], v[100:103]
	v_mfma_f32_16x16x32_bf16 v[96:99], v[148:151], v[196:199], v[96:99]
	v_mfma_f32_16x16x32_bf16 v[84:87], v[140:143], v[204:207], v[84:87]
	v_mfma_f32_16x16x32_bf16 v[80:83], v[148:151], v[204:207], v[80:83]
	s_barrier
	s_add_i32 s5, 0, 0x1c000
	s_add_i32 s4, s4, s27
	v_add_u32_e32 v0, s5, v181
	v_lshl_add_u64 v[226:227], v[184:185], 0, s[46:47]
	s_mov_b32 m0, s4
	ds_read_b128 v[208:211], v0
	ds_read_b128 v[212:215], v0 offset:1024
	ds_read_b128 v[216:219], v0 offset:2048
	ds_read_b128 v[220:223], v0 offset:3072
	global_load_lds_dwordx4 v[226:227], off
	v_lshl_add_u64 v[226:227], v[184:185], 0, s[62:63]
	s_add_i32 m0, s4, 0x2000
	s_nop 0
	global_load_lds_dwordx4 v[226:227], off
	s_barrier
; #define G_STAGE(bufoff, gbase, o0, h64) do { \
;         __builtin_amdgcn_global_load_lds((const unsigned*)((const char*)(gbase) + (o0)), (LAS unsigned*)(lds + (bufoff) + ldsw), 16, 0, 0); \
;         __builtin_amdgcn_global_load_lds((const unsigned*)((const char*)(gbase) + (h64) + (o0)), (LAS unsigned*)(lds + (bufoff) + ldsw + 8192), 16, 0, 0); } while (0)
; #define G_LDA(dst, b, h) do { _Pragma("unroll") for (int m = 0; m < 4; ++m) _Pragma("unroll") for (int k = 0; k < 2; ++k) dst[m][k] = *(const LAS bf16x8*)(lds + G_SA(b, h) + aoff + m * 2048 + k * 1024); } while (0)
; #define G_WAIT_V(n) asm volatile("s_waitcnt vmcnt(" #n ")" ::: "memory")
; #define G_WAIT_L(n) asm volatile("s_waitcnt lgkmcnt(" #n ")" ::: "memory")
; #define G_BAR __builtin_amdgcn_s_barrier()
; #define G_SCHED __builtin_amdgcn_sched_barrier(0)
;     ...
;             G_LDA(At, 1, 1); G_STAGE(G_SA(1, 0), a3, cA0, qA);
;             G_BAR; G_WAIT_L(0); G_MMA(1, 0, At, B0); G_BAR; G_SCHED;
;             G_STAGE(G_SB(1, 1), b3 + chB, cB0, qB);
;             G_WAIT_V(6); G_BAR; G_MMA(1, 1, At, B1); G_BAR;
;         }
	s_waitcnt lgkmcnt(0)
	v_mfma_f32_16x16x32_bf16 v[124:127], v[208:211], v[152:155], v[124:127]
	v_mfma_f32_16x16x32_bf16 v[120:123], v[216:219], v[152:155], v[120:123]
	v_mfma_f32_16x16x32_bf16 v[108:111], v[208:211], v[164:167], v[108:111]
	v_mfma_f32_16x16x32_bf16 v[104:107], v[216:219], v[164:167], v[104:107]
	v_mfma_f32_16x16x32_bf16 v[92:95], v[208:211], v[176:179], v[92:95]
	v_mfma_f32_16x16x32_bf16 v[88:91], v[216:219], v[176:179], v[88:91]
	v_mfma_f32_16x16x32_bf16 v[76:79], v[208:211], v[200:203], v[76:79]
	v_mfma_f32_16x16x32_bf16 v[72:75], v[216:219], v[200:203], v[72:75]
	v_mfma_f32_16x16x32_bf16 v[124:127], v[212:215], v[160:163], v[124:127]
	v_mfma_f32_16x16x32_bf16 v[120:123], v[220:223], v[160:163], v[120:123]
	v_mfma_f32_16x16x32_bf16 v[108:111], v[212:215], v[172:175], v[108:111]
	v_mfma_f32_16x16x32_bf16 v[104:107], v[220:223], v[172:175], v[104:107]
	v_mfma_f32_16x16x32_bf16 v[92:95], v[212:215], v[196:199], v[92:95]
	v_mfma_f32_16x16x32_bf16 v[88:91], v[220:223], v[196:199], v[88:91]
	v_mfma_f32_16x16x32_bf16 v[76:79], v[212:215], v[204:207], v[76:79]
	v_mfma_f32_16x16x32_bf16 v[72:75], v[220:223], v[204:207], v[72:75]
	s_barrier
	s_mov_b32 m0, s35
	v_lshl_add_u64 v[226:227], v[224:225], 0, s[46:47]
	ds_read_b128 v[152:155], v182 offset:49152
	ds_read_b128 v[160:163], v182 offset:50176
	ds_read_b128 v[164:167], v182 offset:51200
	ds_read_b128 v[172:175], v182 offset:52224
	ds_read_b128 v[176:179], v182 offset:53248
	ds_read_b128 v[196:199], v182 offset:54272
	ds_read_b128 v[200:203], v182 offset:55296
	ds_read_b128 v[204:207], v182 offset:56320
	global_load_lds_dwordx4 v[226:227], off
	v_lshl_add_u64 v[224:225], v[224:225], 0, s[62:63]
	s_mov_b32 m0, s36
	s_nop 0
	global_load_lds_dwordx4 v[224:225], off
	s_barrier
	s_waitcnt lgkmcnt(0)
	v_mfma_f32_16x16x32_bf16 v[68:71], v[136:139], v[152:155], v[68:71]
	v_mfma_f32_16x16x32_bf16 v[64:67], v[144:147], v[152:155], v[64:67]
	v_mfma_f32_16x16x32_bf16 v[52:55], v[136:139], v[164:167], v[52:55]
	v_mfma_f32_16x16x32_bf16 v[48:51], v[144:147], v[164:167], v[48:51]
	v_mfma_f32_16x16x32_bf16 v[36:39], v[136:139], v[176:179], v[36:39]
	v_mfma_f32_16x16x32_bf16 v[32:35], v[144:147], v[176:179], v[32:35]
	v_mfma_f32_16x16x32_bf16 v[20:23], v[136:139], v[200:203], v[20:23]
	v_mfma_f32_16x16x32_bf16 v[16:19], v[144:147], v[200:203], v[16:19]
	v_mfma_f32_16x16x32_bf16 v[68:71], v[140:143], v[160:163], v[68:71]
	v_mfma_f32_16x16x32_bf16 v[64:67], v[148:151], v[160:163], v[64:67]
	v_mfma_f32_16x16x32_bf16 v[52:55], v[140:143], v[172:175], v[52:55]
	v_mfma_f32_16x16x32_bf16 v[48:51], v[148:151], v[172:175], v[48:51]
	v_mfma_f32_16x16x32_bf16 v[36:39], v[140:143], v[196:199], v[36:39]
	v_mfma_f32_16x16x32_bf16 v[32:35], v[148:151], v[196:199], v[32:35]
	v_mfma_f32_16x16x32_bf16 v[20:23], v[140:143], v[204:207], v[20:23]
	v_mfma_f32_16x16x32_bf16 v[16:19], v[148:151], v[204:207], v[16:19]
	s_barrier
	s_add_i32 s4, s5, s27
	v_lshl_add_u64 v[136:137], v[184:185], 0, s[64:65]
	s_mov_b32 m0, s4
	s_nop 0
	global_load_lds_dwordx4 v[136:137], off
	v_lshl_add_u64 v[136:137], v[184:185], 0, s[66:67]
	s_add_i32 m0, s4, 0x2000
	s_nop 0
	global_load_lds_dwordx4 v[136:137], off
	s_add_i32 s24, s24, 2
	s_add_u32 s2, s2, 0x100
	s_addc_u32 s3, s3, 0
	s_add_u32 s22, s22, 0x100
	s_addc_u32 s23, s23, 0
	s_cmp_gt_u32 s24, 13
	s_waitcnt vmcnt(6)
	s_barrier
	v_mfma_f32_16x16x32_bf16 v[60:63], v[208:211], v[152:155], v[60:63]
	v_mfma_f32_16x16x32_bf16 v[56:59], v[216:219], v[152:155], v[56:59]
	v_mfma_f32_16x16x32_bf16 v[44:47], v[208:211], v[164:167], v[44:47]
	v_mfma_f32_16x16x32_bf16 v[40:43], v[216:219], v[164:167], v[40:43]
	v_mfma_f32_16x16x32_bf16 v[28:31], v[208:211], v[176:179], v[28:31]
	v_mfma_f32_16x16x32_bf16 v[24:27], v[216:219], v[176:179], v[24:27]
	v_mfma_f32_16x16x32_bf16 v[12:15], v[208:211], v[200:203], v[12:15]
	v_mfma_f32_16x16x32_bf16 v[8:11], v[216:219], v[200:203], v[8:11]
	v_mfma_f32_16x16x32_bf16 v[60:63], v[212:215], v[160:163], v[60:63]
	v_mfma_f32_16x16x32_bf16 v[56:59], v[220:223], v[160:163], v[56:59]
	v_mfma_f32_16x16x32_bf16 v[44:47], v[212:215], v[172:175], v[44:47]
	v_mfma_f32_16x16x32_bf16 v[40:43], v[220:223], v[172:175], v[40:43]
	v_mfma_f32_16x16x32_bf16 v[28:31], v[212:215], v[196:199], v[28:31]
	v_mfma_f32_16x16x32_bf16 v[24:27], v[220:223], v[196:199], v[24:27]
	v_mfma_f32_16x16x32_bf16 v[12:15], v[212:215], v[204:207], v[12:15]
	v_mfma_f32_16x16x32_bf16 v[8:11], v[220:223], v[204:207], v[8:11]
	s_cbranch_scc0 .Ldb_PLE1_cont
	v_readfirstlane_b32 s101, v186
	s_cmpk_gt_u32 s101, 0xff
	s_cbranch_scc1 .Ldb_PLE1_young
	s_barrier
	s_mov_b32 s101, 1
	s_branch .Ldb_PLE1_exit
